# GEMM loops: As low-half DMA stage moved from SP2 to next SP1 load segment (4/4 pieces), waits 8/6/8/6
# speedup vs baseline: 1.0068x; 1.0068x over previous
; #define PG8_STAGE(bufoff, gbase, voff) do { _Pragma("unroll") for (int _i = 0; _i < 2; ++_i) \
;         __builtin_amdgcn_global_load_lds((const unsigned*)((const char*)(gbase) + (voff)[_i]), (PG8_LAS unsigned*)(lds + (bufoff) + ldsw + _i * 8192), 16, 0, 0); } while (0)
; #define PG8_WAIT_V(n) asm volatile("s_waitcnt vmcnt(" #n ")" ::: "memory")
; #define PG8_BAR __builtin_amdgcn_s_barrier()
; template <class Epi, class Sched, bool ALIGN_EPI = false, bool SP2 = false>
; __device__ __forceinline__ void gemm_phase(PG8_LAS unsigned char* lds, const Gemm g, const Sched& S, const Epi& E) {
;     const int tid = threadIdx.x, wid = __builtin_amdgcn_readfirstlane(tid >> 6), lane = tid & 63, wr = wid >> 2, wc = wid & 3, fr = lane & 15, fq = lane >> 4;
;     const int K = g.K, nt = K / BK;
;     unsigned voffA[2], voffB[2];
; #pragma unroll
;     for (int i = 0; i < 2; ++i) { int R, C; stage_rc(tid * 16 + i * 8192, R, C); const int Rb = Epi::PERM ? ((R & ~31) + perm32(R & 31)) : R;
;         voffA[i] = (unsigned)(R * K + C) * 2u; voffB[i] = (unsigned)(Rb * K + C) * 2u; }
;     const size_t kstep = (size_t)(BK * 2);
;     const size_t hstep = (size_t)HALF * K * 2;
;     const size_t tstep = 2 * hstep;
;     const unsigned ldsw = (unsigned)wid * 1024u;
;     const int aoff = lds_byte(wr * 64 + fr, fq * 8), boff = lds_byte(wc * 32 + fr, fq * 8);
;     ...
;         PG8_STAGE(PG8_SB(0, 0), cB, voffB); PG8_STAGE(PG8_SB(0, 1), cB + hstep, voffB); PG8_STAGE(PG8_SA(0, 0), cA, voffA); PG8_STAGE(PG8_SA(0, 1), cA + hstep, voffA);
;         if (wr == 1) PG8_BAR;
;         PG8_WAIT_V(2); PG8_BAR;
;         PG8_STAGE(PG8_SB(1, 0), cB + kstep, voffB); PG8_STAGE(PG8_SA(1, 0), cA + kstep, voffA); PG8_STAGE(PG8_SB(1, 1), cB + hstep + kstep, voffB);
;         PG8_WAIT_V(6); PG8_BAR;
.LBB0_169:
	s_lshl_b32 s36, s36, 5
	s_and_b32 s41, s36, 0x60
	s_mov_b64 s[36:37], 0x80
	s_add_i32 m0, s28, 0x18000
	v_lshl_add_u64 v[6:7], v[6:7], 0, s[36:37]
	s_lshl_b32 s3, s40, 13
	s_lshl_b32 s46, s41, 7
	s_waitcnt vmcnt(2)
	s_barrier
	global_load_lds_dwordx4 v[6:7], off
	v_lshl_add_u64 v[4:5], v[4:5], 0, s[36:37]
	s_add_i32 m0, s28, 0x1a000
	s_add_i32 s65, s28, 0x8000
	s_add_i32 s66, s28, 0xa000
	global_load_lds_dwordx4 v[4:5], off
	v_lshl_add_u64 v[0:1], v[0:1], 0, s[36:37]
	s_mov_b32 m0, s65
	s_add_u32 s44, s60, 0x40080
	global_load_lds_dwordx4 v[0:1], off
	v_mov_b32_e32 v232, v0
	v_mov_b32_e32 v233, v1
	v_lshl_add_u64 v[0:1], v[2:3], 0, s[36:37]
	s_mov_b32 m0, s66
	s_addc_u32 s45, s61, 0
	global_load_lds_dwordx4 v[0:1], off
	v_mov_b32_e32 v234, v0
	v_mov_b32_e32 v235, v1
	s_add_i32 m0, s28, 0x1c000
	v_lshl_add_u64 v[0:1], s[44:45], 0, v[132:133]
	global_load_lds_dwordx4 v[0:1], off
	v_lshl_add_u64 v[0:1], s[44:45], 0, v[128:129]
	s_add_i32 m0, s28, 0x1e000
	v_lshlrev_b32_e32 v2, 2, v201
	global_load_lds_dwordx4 v[0:1], off
	v_and_b32_e32 v0, 15, v201
	v_lshlrev_b32_e32 v1, 1, v11
	v_lshl_or_b32 v174, s40, 6, v0
	v_lshl_or_b32 v0, v0, 6, v1
	v_and_b32_e32 v2, 32, v2
	v_bitop3_b32 v0, v0, s3, v2 bitop3:0xde
	v_lshlrev_b32_e32 v3, 6, v201
	s_movk_i32 s3, 0x3c0
	v_and_or_b32 v1, v3, s3, v1
	v_bitop3_b32 v175, s46, v1, v2 bitop3:0xf6
	v_lshlrev_b32_e32 v1, 8, v201
	v_and_b32_e32 v1, 0x38000, v1
	v_lshlrev_b32_e32 v2, 11, v12
	v_or3_b32 v1, v9, v1, v2
	v_add_u32_e32 v136, v1, v10
	v_lshlrev_b32_e32 v1, 4, v8
	s_waitcnt vmcnt(6)
	s_cmpk_lt_u32 s39, 0x100
	v_and_b32_e32 v1, 0x78000, v1
	s_sext_i32_i8 s70, s38
	s_cselect_b64 s[38:39], -1, 0
	v_or3_b32 v1, v9, v1, v2
	s_add_i32 s67, 0, 0x10000
	s_add_i32 s68, 0, 0x14000
	v_or_b32_e32 v176, s41, v11
	v_mov_b32_e32 v137, v133
	v_add_u32_e32 v138, v1, v10
	v_mov_b32_e32 v139, v133
	v_add_u32_e32 v177, s67, v175
	v_add_u32_e32 v178, s68, v175
	v_add_u32_e32 v179, 0, v0
	v_mov_b32_e32 v180, 0x358637bd
	s_movk_i32 s69, 0x1600
	s_barrier
	s_branch .LBB0_172

; #define PG8_STAGE(bufoff, gbase, voff) do { _Pragma("unroll") for (int _i = 0; _i < 2; ++_i) \
;         __builtin_amdgcn_global_load_lds((const unsigned*)((const char*)(gbase) + (voff)[_i]), (PG8_LAS unsigned*)(lds + (bufoff) + ldsw + _i * 8192), 16, 0, 0); } while (0)
; #define PG8_LDA(dst, b, h) do { _Pragma("unroll") for (int m = 0; m < 4; ++m) _Pragma("unroll") for (int k = 0; k < 2; ++k) dst[m][k] = *(const PG8_LAS bf16x8*)(lds + PG8_SA(b, h) + aoff + m * 2048 + k * 1024); } while (0)
; #define PG8_LDB(dst, b, h) do { _Pragma("unroll") for (int n = 0; n < 2; ++n) _Pragma("unroll") for (int k = 0; k < 2; ++k) dst[n][k] = *(const PG8_LAS bf16x8*)(lds + PG8_SB(b, h) + boff + n * 2048 + k * 1024); } while (0)
; #define PG8_MMA(ai, bj, At, Bt) do { __builtin_amdgcn_s_setprio(1); _Pragma("unroll") for (int m = 0; m < 4; ++m) _Pragma("unroll") for (int n = 0; n < 2; ++n) _Pragma("unroll") for (int k = 0; k < 2; ++k) \
;         acc[ai][bj][m][n] = __builtin_amdgcn_mfma_f32_16x16x32_bf16(Bt[n][k], At[m][k], acc[ai][bj][m][n], 0, 0, 0); __builtin_amdgcn_s_setprio(0); } while (0)
; #define PG8_WAIT_V(n) asm volatile("s_waitcnt vmcnt(" #n ")" ::: "memory")
; #define PG8_WAIT_L(n) asm volatile("s_waitcnt lgkmcnt(" #n ")" ::: "memory")
; #define PG8_BAR __builtin_amdgcn_s_barrier()
; #define PG8_SCHED __builtin_amdgcn_sched_barrier(0)
; template <class Epi, class Sched, bool ALIGN_EPI = false, bool SP2 = false>
; __device__ __forceinline__ void gemm_phase(PG8_LAS unsigned char* lds, const Gemm g, const Sched& S, const Epi& E) {
;     ...
;             PG8_LDB(B0, 0, 0); PG8_LDB(B1, 0, 1); PG8_SCHED; PG8_LDA(At, 0, 0); PG8_STAGE(PG8_SA(1, 1), a1 + hstep, voffA);
;             PG8_WAIT_V(8); PG8_WAIT_L(0); PG8_BAR; PG8_MMA(0, 0, At, B0); PG8_MMA(0, 1, At, B1); PG8_BAR; PG8_SCHED;
;             PG8_LDA(At, 0, 1); PG8_STAGE(PG8_SB(0, 0), b2, voffB); PG8_STAGE(PG8_SB(0, 1), b2 + hstep, voffB); PG8_STAGE(PG8_SA(0, 0), a2, voffA);
;             PG8_WAIT_V(8); PG8_WAIT_L(0); PG8_BAR; PG8_MMA(1, 0, At, B0); PG8_MMA(1, 1, At, B1); PG8_BAR; PG8_SCHED;
.LBB0_175:
	ds_read_b128 v[140:143], v177
	ds_read_b128 v[144:147], v177 offset:1024
	ds_read_b128 v[148:151], v177 offset:2048
	ds_read_b128 v[152:155], v177 offset:3072
	ds_read_b128 v[156:159], v178
	ds_read_b128 v[160:163], v178 offset:1024
	ds_read_b128 v[164:167], v178 offset:2048
	ds_read_b128 v[168:171], v178 offset:3072
	s_add_u32 s60, s58, 0xfffc0080
	s_addc_u32 s61, s59, -1
	s_cmp_eq_u32 s74, 12
	s_cselect_b32 s63, s3, s61
	s_cselect_b32 s62, s41, s60
	s_cselect_b32 s61, s45, s73
	s_cselect_b32 s60, s71, s72
	v_lshl_add_u64 v[172:173], s[58:59], 0, v[136:137]
	s_mov_b32 m0, s65
	s_nop 0
	global_load_lds_dwordx4 v[232:233], off
	s_mov_b32 m0, s66
	s_nop 0
	global_load_lds_dwordx4 v[234:235], off
	s_add_i32 m0, s28, 0xc000
	ds_read_b128 v[182:185], v179
	ds_read_b128 v[186:189], v179 offset:1024
	ds_read_b128 v[190:193], v179 offset:2048
	ds_read_b128 v[194:197], v179 offset:3072
	ds_read_b128 v[202:205], v179 offset:4096
	ds_read_b128 v[206:209], v179 offset:5120
	ds_read_b128 v[210:213], v179 offset:6144
	ds_read_b128 v[214:217], v179 offset:7168
	global_load_lds_dwordx4 v[172:173], off
	v_lshl_add_u64 v[172:173], s[58:59], 0, v[138:139]
	s_add_i32 m0, s28, 0xe000
	s_nop 0
	global_load_lds_dwordx4 v[172:173], off
	s_waitcnt vmcnt(8)
	s_waitcnt lgkmcnt(0)
	s_barrier
	s_setprio 1
	s_waitcnt lgkmcnt(0)
	v_mfma_f32_16x16x32_bf16 v[124:127], v[140:143], v[182:185], v[124:127]
	v_mfma_f32_16x16x32_bf16 v[120:123], v[148:151], v[182:185], v[120:123]
	v_mfma_f32_16x16x32_bf16 v[108:111], v[140:143], v[190:193], v[108:111]
	v_mfma_f32_16x16x32_bf16 v[104:107], v[148:151], v[190:193], v[104:107]
	v_mfma_f32_16x16x32_bf16 v[92:95], v[140:143], v[202:205], v[92:95]
	v_mfma_f32_16x16x32_bf16 v[88:91], v[148:151], v[202:205], v[88:91]
	v_mfma_f32_16x16x32_bf16 v[76:79], v[140:143], v[210:213], v[76:79]
	v_mfma_f32_16x16x32_bf16 v[72:75], v[148:151], v[210:213], v[72:75]
	v_mfma_f32_16x16x32_bf16 v[124:127], v[144:147], v[186:189], v[124:127]
	v_mfma_f32_16x16x32_bf16 v[120:123], v[152:155], v[186:189], v[120:123]
	v_mfma_f32_16x16x32_bf16 v[108:111], v[144:147], v[194:197], v[108:111]
	v_mfma_f32_16x16x32_bf16 v[104:107], v[152:155], v[194:197], v[104:107]
	v_mfma_f32_16x16x32_bf16 v[92:95], v[144:147], v[206:209], v[92:95]
	v_mfma_f32_16x16x32_bf16 v[88:91], v[152:155], v[206:209], v[88:91]
	v_mfma_f32_16x16x32_bf16 v[76:79], v[144:147], v[214:217], v[76:79]
	v_mfma_f32_16x16x32_bf16 v[72:75], v[152:155], v[214:217], v[72:75]
	s_setprio 0
	s_setprio 1
	v_mfma_f32_16x16x32_bf16 v[116:119], v[156:159], v[182:185], v[116:119]
	v_mfma_f32_16x16x32_bf16 v[112:115], v[164:167], v[182:185], v[112:115]
	v_mfma_f32_16x16x32_bf16 v[100:103], v[156:159], v[190:193], v[100:103]
	v_mfma_f32_16x16x32_bf16 v[96:99], v[164:167], v[190:193], v[96:99]
	v_mfma_f32_16x16x32_bf16 v[84:87], v[156:159], v[202:205], v[84:87]
	v_mfma_f32_16x16x32_bf16 v[80:83], v[164:167], v[202:205], v[80:83]
	v_mfma_f32_16x16x32_bf16 v[68:71], v[156:159], v[210:213], v[68:71]
	v_mfma_f32_16x16x32_bf16 v[64:67], v[164:167], v[210:213], v[64:67]
	v_mfma_f32_16x16x32_bf16 v[116:119], v[160:163], v[186:189], v[116:119]
	v_mfma_f32_16x16x32_bf16 v[112:115], v[168:171], v[186:189], v[112:115]
	v_mfma_f32_16x16x32_bf16 v[100:103], v[160:163], v[194:197], v[100:103]
	v_mfma_f32_16x16x32_bf16 v[96:99], v[168:171], v[194:197], v[96:99]
	v_mfma_f32_16x16x32_bf16 v[84:87], v[160:163], v[206:209], v[84:87]
	v_mfma_f32_16x16x32_bf16 v[80:83], v[168:171], v[206:209], v[80:83]
	v_mfma_f32_16x16x32_bf16 v[68:71], v[160:163], v[214:217], v[68:71]
	v_mfma_f32_16x16x32_bf16 v[64:67], v[168:171], v[214:217], v[64:67]
	s_setprio 0
	s_barrier
	s_add_i32 s75, s67, s21
	v_lshl_add_u64 v[172:173], s[60:61], 0, v[132:133]
	s_mov_b32 m0, s75
	ds_read_b128 v[182:185], v179 offset:16384
	ds_read_b128 v[186:189], v179 offset:17408
	ds_read_b128 v[190:193], v179 offset:18432
	ds_read_b128 v[194:197], v179 offset:19456
	ds_read_b128 v[202:205], v179 offset:20480
	ds_read_b128 v[206:209], v179 offset:21504
	ds_read_b128 v[210:213], v179 offset:22528
	ds_read_b128 v[214:217], v179 offset:23552
	global_load_lds_dwordx4 v[172:173], off
	s_add_i32 m0, s75, 0x2000
	s_add_u32 s76, s60, 0x40000
	v_lshl_add_u64 v[198:199], s[60:61], 0, v[128:129]
	s_addc_u32 s77, s61, 0
	s_add_i32 s75, s68, s21
	global_load_lds_dwordx4 v[198:199], off
	v_lshl_add_u64 v[218:219], s[76:77], 0, v[132:133]
	s_mov_b32 m0, s75
	v_lshl_add_u64 v[220:221], s[62:63], 0, v[130:131]
	global_load_lds_dwordx4 v[218:219], off
	v_lshl_add_u64 v[218:219], s[76:77], 0, v[128:129]
	s_add_i32 m0, s75, 0x2000
	s_nop 0
	global_load_lds_dwordx4 v[218:219], off
	v_lshl_add_u64 v[218:219], s[62:63], 0, v[134:135]
	v_mov_b32_e32 v236, v218
	v_mov_b32_e32 v237, v219
	v_mov_b32_e32 v238, v220
	v_mov_b32_e32 v239, v221
	s_waitcnt vmcnt(6)
	s_waitcnt lgkmcnt(0)
	s_barrier
; #define PG8_STAGE(bufoff, gbase, voff) do { _Pragma("unroll") for (int _i = 0; _i < 2; ++_i) \
;         __builtin_amdgcn_global_load_lds((const unsigned*)((const char*)(gbase) + (voff)[_i]), (PG8_LAS unsigned*)(lds + (bufoff) + ldsw + _i * 8192), 16, 0, 0); } while (0)
; #define PG8_LDA(dst, b, h) do { _Pragma("unroll") for (int m = 0; m < 4; ++m) _Pragma("unroll") for (int k = 0; k < 2; ++k) dst[m][k] = *(const PG8_LAS bf16x8*)(lds + PG8_SA(b, h) + aoff + m * 2048 + k * 1024); } while (0)
; #define PG8_LDB(dst, b, h) do { _Pragma("unroll") for (int n = 0; n < 2; ++n) _Pragma("unroll") for (int k = 0; k < 2; ++k) dst[n][k] = *(const PG8_LAS bf16x8*)(lds + PG8_SB(b, h) + boff + n * 2048 + k * 1024); } while (0)
; #define PG8_MMA(ai, bj, At, Bt) do { __builtin_amdgcn_s_setprio(1); _Pragma("unroll") for (int m = 0; m < 4; ++m) _Pragma("unroll") for (int n = 0; n < 2; ++n) _Pragma("unroll") for (int k = 0; k < 2; ++k) \
;         acc[ai][bj][m][n] = __builtin_amdgcn_mfma_f32_16x16x32_bf16(Bt[n][k], At[m][k], acc[ai][bj][m][n], 0, 0, 0); __builtin_amdgcn_s_setprio(0); } while (0)
; #define PG8_WAIT_V(n) asm volatile("s_waitcnt vmcnt(" #n ")" ::: "memory")
; #define PG8_WAIT_L(n) asm volatile("s_waitcnt lgkmcnt(" #n ")" ::: "memory")
; #define PG8_BAR __builtin_amdgcn_s_barrier()
; #define PG8_SCHED __builtin_amdgcn_sched_barrier(0)
; template <class Epi, class Sched, bool ALIGN_EPI = false, bool SP2 = false>
; __device__ __forceinline__ void gemm_phase(PG8_LAS unsigned char* lds, const Gemm g, const Sched& S, const Epi& E) {
;     ...
;             PG8_WAIT_V(8); PG8_WAIT_L(0); PG8_BAR; PG8_MMA(1, 0, At, B0); PG8_MMA(1, 1, At, B1); PG8_BAR; PG8_SCHED;
;             PG8_LDB(B0, 1, 0); PG8_LDB(B1, 1, 1); PG8_SCHED; PG8_LDA(At, 1, 0); PG8_STAGE(PG8_SA(0, 1), a2 + hstep, voffA);
;             PG8_WAIT_V(8); PG8_WAIT_L(0); PG8_BAR; PG8_MMA(0, 0, At, B0); PG8_MMA(0, 1, At, B1); PG8_BAR; PG8_SCHED;
	s_setprio 1
	s_waitcnt lgkmcnt(0)
	v_mfma_f32_16x16x32_bf16 v[60:63], v[140:143], v[182:185], v[60:63]
	v_mfma_f32_16x16x32_bf16 v[56:59], v[148:151], v[182:185], v[56:59]
	v_mfma_f32_16x16x32_bf16 v[44:47], v[140:143], v[190:193], v[44:47]
	v_mfma_f32_16x16x32_bf16 v[40:43], v[148:151], v[190:193], v[40:43]
	v_mfma_f32_16x16x32_bf16 v[28:31], v[140:143], v[202:205], v[28:31]
	v_mfma_f32_16x16x32_bf16 v[24:27], v[148:151], v[202:205], v[24:27]
	v_mfma_f32_16x16x32_bf16 v[12:15], v[140:143], v[210:213], v[12:15]
	v_mfma_f32_16x16x32_bf16 v[8:11], v[148:151], v[210:213], v[8:11]
	v_mfma_f32_16x16x32_bf16 v[60:63], v[144:147], v[186:189], v[60:63]
	v_mfma_f32_16x16x32_bf16 v[56:59], v[152:155], v[186:189], v[56:59]
	v_mfma_f32_16x16x32_bf16 v[44:47], v[144:147], v[194:197], v[44:47]
	v_mfma_f32_16x16x32_bf16 v[40:43], v[152:155], v[194:197], v[40:43]
	v_mfma_f32_16x16x32_bf16 v[28:31], v[144:147], v[206:209], v[28:31]
	v_mfma_f32_16x16x32_bf16 v[24:27], v[152:155], v[206:209], v[24:27]
	v_mfma_f32_16x16x32_bf16 v[12:15], v[144:147], v[214:217], v[12:15]
	v_mfma_f32_16x16x32_bf16 v[8:11], v[152:155], v[214:217], v[8:11]
	s_setprio 0
	s_setprio 1
	v_mfma_f32_16x16x32_bf16 v[52:55], v[156:159], v[182:185], v[52:55]
	v_mfma_f32_16x16x32_bf16 v[48:51], v[164:167], v[182:185], v[48:51]
	v_mfma_f32_16x16x32_bf16 v[36:39], v[156:159], v[190:193], v[36:39]
	v_mfma_f32_16x16x32_bf16 v[32:35], v[164:167], v[190:193], v[32:35]
	v_mfma_f32_16x16x32_bf16 v[20:23], v[156:159], v[202:205], v[20:23]
	v_mfma_f32_16x16x32_bf16 v[16:19], v[164:167], v[202:205], v[16:19]
	v_mfma_f32_16x16x32_bf16 v[4:7], v[156:159], v[210:213], v[4:7]
	v_mfma_f32_16x16x32_bf16 v[0:3], v[164:167], v[210:213], v[0:3]
	v_mfma_f32_16x16x32_bf16 v[52:55], v[160:163], v[186:189], v[52:55]
	v_mfma_f32_16x16x32_bf16 v[48:51], v[168:171], v[186:189], v[48:51]
	v_mfma_f32_16x16x32_bf16 v[36:39], v[160:163], v[194:197], v[36:39]
	v_mfma_f32_16x16x32_bf16 v[32:35], v[168:171], v[194:197], v[32:35]
	v_mfma_f32_16x16x32_bf16 v[20:23], v[160:163], v[206:209], v[20:23]
	v_mfma_f32_16x16x32_bf16 v[16:19], v[168:171], v[206:209], v[16:19]
	v_mfma_f32_16x16x32_bf16 v[4:7], v[160:163], v[214:217], v[4:7]
	v_mfma_f32_16x16x32_bf16 v[0:3], v[168:171], v[214:217], v[0:3]
	s_setprio 0
	s_barrier
	s_add_i32 s75, 0, 0x18000
	s_add_i32 s76, 0, 0x1c000
	v_add_u32_e32 v152, s75, v175
	v_add_u32_e32 v168, s76, v175
	ds_read_b128 v[140:143], v152
	ds_read_b128 v[144:147], v152 offset:1024
	ds_read_b128 v[148:151], v152 offset:2048
	ds_read_b128 v[152:155], v152 offset:3072
	ds_read_b128 v[156:159], v168
	ds_read_b128 v[160:163], v168 offset:1024
	ds_read_b128 v[164:167], v168 offset:2048
	ds_read_b128 v[168:171], v168 offset:3072
	s_add_u32 s62, s62, 0x40000
	s_addc_u32 s63, s63, 0
	s_mov_b32 m0, s28
	s_nop 0
	global_load_lds_dwordx4 v[236:237], off
	s_mov_b32 m0, s29
	s_nop 0
	global_load_lds_dwordx4 v[238:239], off
	s_mov_b32 m0, s30
	v_lshl_add_u64 v[222:223], s[62:63], 0, v[134:135]
	ds_read_b128 v[182:185], v179 offset:32768
	ds_read_b128 v[186:189], v179 offset:33792
	ds_read_b128 v[190:193], v179 offset:34816
	ds_read_b128 v[194:197], v179 offset:35840
	ds_read_b128 v[202:205], v179 offset:36864
	ds_read_b128 v[206:209], v179 offset:37888
	ds_read_b128 v[210:213], v179 offset:38912
	ds_read_b128 v[214:217], v179 offset:39936
	global_load_lds_dwordx4 v[222:223], off
	v_lshl_add_u64 v[222:223], s[62:63], 0, v[130:131]
	s_mov_b32 m0, s31
	s_nop 0
	global_load_lds_dwordx4 v[222:223], off
	s_waitcnt vmcnt(8)
	s_waitcnt lgkmcnt(0)
	s_barrier
	s_setprio 1
	s_waitcnt lgkmcnt(0)
	v_mfma_f32_16x16x32_bf16 v[124:127], v[140:143], v[182:185], v[124:127]
	v_mfma_f32_16x16x32_bf16 v[120:123], v[148:151], v[182:185], v[120:123]
	v_mfma_f32_16x16x32_bf16 v[108:111], v[140:143], v[190:193], v[108:111]
	v_mfma_f32_16x16x32_bf16 v[104:107], v[148:151], v[190:193], v[104:107]
	v_mfma_f32_16x16x32_bf16 v[92:95], v[140:143], v[202:205], v[92:95]
	v_mfma_f32_16x16x32_bf16 v[88:91], v[148:151], v[202:205], v[88:91]
	v_mfma_f32_16x16x32_bf16 v[76:79], v[140:143], v[210:213], v[76:79]
	v_mfma_f32_16x16x32_bf16 v[72:75], v[148:151], v[210:213], v[72:75]
	v_mfma_f32_16x16x32_bf16 v[124:127], v[144:147], v[186:189], v[124:127]
	v_mfma_f32_16x16x32_bf16 v[120:123], v[152:155], v[186:189], v[120:123]
	v_mfma_f32_16x16x32_bf16 v[108:111], v[144:147], v[194:197], v[108:111]
	v_mfma_f32_16x16x32_bf16 v[104:107], v[152:155], v[194:197], v[104:107]
	v_mfma_f32_16x16x32_bf16 v[92:95], v[144:147], v[206:209], v[92:95]
	v_mfma_f32_16x16x32_bf16 v[88:91], v[152:155], v[206:209], v[88:91]
	v_mfma_f32_16x16x32_bf16 v[76:79], v[144:147], v[214:217], v[76:79]
	v_mfma_f32_16x16x32_bf16 v[72:75], v[152:155], v[214:217], v[72:75]
	s_setprio 0
	s_setprio 1
	v_mfma_f32_16x16x32_bf16 v[116:119], v[156:159], v[182:185], v[116:119]
	v_mfma_f32_16x16x32_bf16 v[112:115], v[164:167], v[182:185], v[112:115]
	v_mfma_f32_16x16x32_bf16 v[100:103], v[156:159], v[190:193], v[100:103]
	v_mfma_f32_16x16x32_bf16 v[96:99], v[164:167], v[190:193], v[96:99]
	v_mfma_f32_16x16x32_bf16 v[84:87], v[156:159], v[202:205], v[84:87]
	v_mfma_f32_16x16x32_bf16 v[80:83], v[164:167], v[202:205], v[80:83]
	v_mfma_f32_16x16x32_bf16 v[68:71], v[156:159], v[210:213], v[68:71]
	v_mfma_f32_16x16x32_bf16 v[64:67], v[164:167], v[210:213], v[64:67]
	v_mfma_f32_16x16x32_bf16 v[116:119], v[160:163], v[186:189], v[116:119]
	v_mfma_f32_16x16x32_bf16 v[112:115], v[168:171], v[186:189], v[112:115]
	v_mfma_f32_16x16x32_bf16 v[100:103], v[160:163], v[194:197], v[100:103]
	v_mfma_f32_16x16x32_bf16 v[96:99], v[168:171], v[194:197], v[96:99]
	v_mfma_f32_16x16x32_bf16 v[84:87], v[160:163], v[206:209], v[84:87]
	v_mfma_f32_16x16x32_bf16 v[80:83], v[168:171], v[206:209], v[80:83]
	v_mfma_f32_16x16x32_bf16 v[68:71], v[160:163], v[214:217], v[68:71]
	v_mfma_f32_16x16x32_bf16 v[64:67], v[168:171], v[214:217], v[64:67]
	s_setprio 0
	s_barrier
; #define PG8_STAGE(bufoff, gbase, voff) do { _Pragma("unroll") for (int _i = 0; _i < 2; ++_i) \
;         __builtin_amdgcn_global_load_lds((const unsigned*)((const char*)(gbase) + (voff)[_i]), (PG8_LAS unsigned*)(lds + (bufoff) + ldsw + _i * 8192), 16, 0, 0); } while (0)
; #define PG8_LDA(dst, b, h) do { _Pragma("unroll") for (int m = 0; m < 4; ++m) _Pragma("unroll") for (int k = 0; k < 2; ++k) dst[m][k] = *(const PG8_LAS bf16x8*)(lds + PG8_SA(b, h) + aoff + m * 2048 + k * 1024); } while (0)
; #define PG8_MMA(ai, bj, At, Bt) do { __builtin_amdgcn_s_setprio(1); _Pragma("unroll") for (int m = 0; m < 4; ++m) _Pragma("unroll") for (int n = 0; n < 2; ++n) _Pragma("unroll") for (int k = 0; k < 2; ++k) \
;         acc[ai][bj][m][n] = __builtin_amdgcn_mfma_f32_16x16x32_bf16(Bt[n][k], At[m][k], acc[ai][bj][m][n], 0, 0, 0); __builtin_amdgcn_s_setprio(0); } while (0)
; #define PG8_WAIT_V(n) asm volatile("s_waitcnt vmcnt(" #n ")" ::: "memory")
; #define PG8_WAIT_L(n) asm volatile("s_waitcnt lgkmcnt(" #n ")" ::: "memory")
; #define PG8_BAR __builtin_amdgcn_s_barrier()
; #define PG8_SCHED __builtin_amdgcn_sched_barrier(0)
; template <class Epi, class Sched, bool ALIGN_EPI = false, bool SP2 = false>
; __device__ __forceinline__ void gemm_phase(PG8_LAS unsigned char* lds, const Gemm g, const Sched& S, const Epi& E) {
;     ...
;         for (int t = 0; t < nt; t += 2) {
;             const bool last = (t == nt - 2);
;             const char* a1 = cA + (size_t)(t + 1) * kstep;
;             const char* a2 = last ? nA : cA + (size_t)(t + 2) * kstep; const char* b2 = last ? nB : cB + (size_t)(t + 2) * kstep;
;     ...
;             PG8_LDA(At, 1, 1); PG8_STAGE(PG8_SB(1, 0), b3, voffB); PG8_STAGE(PG8_SB(1, 1), b3 + hstep, voffB); PG8_STAGE(PG8_SA(1, 0), a3, voffA);
;             PG8_WAIT_V(8); PG8_WAIT_L(0); PG8_BAR; PG8_MMA(1, 0, At, B0); PG8_MMA(1, 1, At, B1); PG8_BAR; PG8_SCHED;
;     ...
;         if constexpr (ALIGN_EPI) { if (wr == 0) PG8_BAR; }
	s_add_i32 s62, s75, s21
	v_lshl_add_u64 v[172:173], v[172:173], 0, s[36:37]
	s_mov_b32 m0, s62
	ds_read_b128 v[182:185], v179 offset:49152
	ds_read_b128 v[186:189], v179 offset:50176
	ds_read_b128 v[190:193], v179 offset:51200
	ds_read_b128 v[194:197], v179 offset:52224
	ds_read_b128 v[202:205], v179 offset:53248
	ds_read_b128 v[206:209], v179 offset:54272
	ds_read_b128 v[210:213], v179 offset:55296
	ds_read_b128 v[214:217], v179 offset:56320
	global_load_lds_dwordx4 v[172:173], off
	s_add_i32 m0, s62, 0x2000
	s_add_u32 s60, s60, 0x40080
	v_lshl_add_u64 v[172:173], v[198:199], 0, s[36:37]
	s_addc_u32 s61, s61, 0
	s_add_i32 s62, s76, s21
	global_load_lds_dwordx4 v[172:173], off
	v_lshl_add_u64 v[172:173], s[60:61], 0, v[132:133]
	s_mov_b32 m0, s62
	s_nop 0
	global_load_lds_dwordx4 v[172:173], off
	v_lshl_add_u64 v[172:173], s[60:61], 0, v[128:129]
	s_add_i32 m0, s62, 0x2000
	s_nop 0
	global_load_lds_dwordx4 v[172:173], off
	v_lshl_add_u64 v[172:173], v[218:219], 0, s[36:37]
	v_mov_b32_e32 v232, v172
	v_mov_b32_e32 v233, v173
	v_lshl_add_u64 v[172:173], v[220:221], 0, s[36:37]
	v_mov_b32_e32 v234, v172
	v_mov_b32_e32 v235, v173
	s_waitcnt vmcnt(6)
	s_waitcnt lgkmcnt(0)
	s_barrier
	s_setprio 1
	s_waitcnt lgkmcnt(0)
	v_mfma_f32_16x16x32_bf16 v[60:63], v[140:143], v[182:185], v[60:63]
	v_mfma_f32_16x16x32_bf16 v[56:59], v[148:151], v[182:185], v[56:59]
	v_mfma_f32_16x16x32_bf16 v[44:47], v[140:143], v[190:193], v[44:47]
	v_mfma_f32_16x16x32_bf16 v[40:43], v[148:151], v[190:193], v[40:43]
	v_mfma_f32_16x16x32_bf16 v[28:31], v[140:143], v[202:205], v[28:31]
	v_mfma_f32_16x16x32_bf16 v[24:27], v[148:151], v[202:205], v[24:27]
	v_mfma_f32_16x16x32_bf16 v[12:15], v[140:143], v[210:213], v[12:15]
	v_mfma_f32_16x16x32_bf16 v[8:11], v[148:151], v[210:213], v[8:11]
	v_mfma_f32_16x16x32_bf16 v[60:63], v[144:147], v[186:189], v[60:63]
	v_mfma_f32_16x16x32_bf16 v[56:59], v[152:155], v[186:189], v[56:59]
	v_mfma_f32_16x16x32_bf16 v[44:47], v[144:147], v[194:197], v[44:47]
	v_mfma_f32_16x16x32_bf16 v[40:43], v[152:155], v[194:197], v[40:43]
	v_mfma_f32_16x16x32_bf16 v[28:31], v[144:147], v[206:209], v[28:31]
	v_mfma_f32_16x16x32_bf16 v[24:27], v[152:155], v[206:209], v[24:27]
	v_mfma_f32_16x16x32_bf16 v[12:15], v[144:147], v[214:217], v[12:15]
	v_mfma_f32_16x16x32_bf16 v[8:11], v[152:155], v[214:217], v[8:11]
	s_setprio 0
	s_setprio 1
	v_mfma_f32_16x16x32_bf16 v[52:55], v[156:159], v[182:185], v[52:55]
	v_mfma_f32_16x16x32_bf16 v[48:51], v[164:167], v[182:185], v[48:51]
	v_mfma_f32_16x16x32_bf16 v[36:39], v[156:159], v[190:193], v[36:39]
	v_mfma_f32_16x16x32_bf16 v[32:35], v[164:167], v[190:193], v[32:35]
	v_mfma_f32_16x16x32_bf16 v[20:23], v[156:159], v[202:205], v[20:23]
	v_mfma_f32_16x16x32_bf16 v[16:19], v[164:167], v[202:205], v[16:19]
	v_mfma_f32_16x16x32_bf16 v[4:7], v[156:159], v[210:213], v[4:7]
	v_mfma_f32_16x16x32_bf16 v[0:3], v[164:167], v[210:213], v[0:3]
	v_mfma_f32_16x16x32_bf16 v[52:55], v[160:163], v[186:189], v[52:55]
	v_mfma_f32_16x16x32_bf16 v[48:51], v[168:171], v[186:189], v[48:51]
	v_mfma_f32_16x16x32_bf16 v[36:39], v[160:163], v[194:197], v[36:39]
	v_mfma_f32_16x16x32_bf16 v[32:35], v[168:171], v[194:197], v[32:35]
	v_mfma_f32_16x16x32_bf16 v[20:23], v[160:163], v[206:209], v[20:23]
	v_mfma_f32_16x16x32_bf16 v[16:19], v[168:171], v[206:209], v[16:19]
	v_mfma_f32_16x16x32_bf16 v[4:7], v[160:163], v[214:217], v[4:7]
	v_mfma_f32_16x16x32_bf16 v[0:3], v[168:171], v[214:217], v[0:3]
	s_setprio 0
	s_barrier
	s_add_i32 s74, s74, 2
	s_add_u32 s58, s58, 0x100
	s_addc_u32 s59, s59, 0
	s_add_u32 s72, s72, 0x100
	s_addc_u32 s73, s73, 0
	s_cmp_gt_u32 s74, 13
	s_cbranch_scc0 .LBB0_175
	s_and_b64 vcc, exec, s[38:39]
	s_cbranch_vccz .LBB0_178
	s_barrier

; #define PG8_STAGE(bufoff, gbase, voff) do { _Pragma("unroll") for (int _i = 0; _i < 2; ++_i) \
;         __builtin_amdgcn_global_load_lds((const unsigned*)((const char*)(gbase) + (voff)[_i]), (PG8_LAS unsigned*)(lds + (bufoff) + ldsw + _i * 8192), 16, 0, 0); } while (0)
; #define PG8_WAIT_V(n) asm volatile("s_waitcnt vmcnt(" #n ")" ::: "memory")
; #define PG8_BAR __builtin_amdgcn_s_barrier()
; template <class Epi, class Sched, bool ALIGN_EPI = false, bool SP2 = false>
; __device__ __forceinline__ void gemm_phase(PG8_LAS unsigned char* lds, const Gemm g, const Sched& S, const Epi& E) {
;     const int tid = threadIdx.x, wid = __builtin_amdgcn_readfirstlane(tid >> 6), lane = tid & 63, wr = wid >> 2, wc = wid & 3, fr = lane & 15, fq = lane >> 4;
;     const int K = g.K, nt = K / BK;
;     unsigned voffA[2], voffB[2];
; #pragma unroll
;     for (int i = 0; i < 2; ++i) { int R, C; stage_rc(tid * 16 + i * 8192, R, C); const int Rb = Epi::PERM ? ((R & ~31) + perm32(R & 31)) : R;
;         voffA[i] = (unsigned)(R * K + C) * 2u; voffB[i] = (unsigned)(Rb * K + C) * 2u; }
;     const size_t kstep = (size_t)(BK * 2);
;     const size_t hstep = (size_t)HALF * K * 2;
;     const size_t tstep = 2 * hstep;
;     const unsigned ldsw = (unsigned)wid * 1024u;
;     const int aoff = lds_byte(wr * 64 + fr, fq * 8), boff = lds_byte(wc * 32 + fr, fq * 8);
;     ...
;         PG8_STAGE(PG8_SB(0, 0), cB, voffB); PG8_STAGE(PG8_SB(0, 1), cB + hstep, voffB); PG8_STAGE(PG8_SA(0, 0), cA, voffA); PG8_STAGE(PG8_SA(0, 1), cA + hstep, voffA);
;         if (wr == 1) PG8_BAR;
;         PG8_WAIT_V(2); PG8_BAR;
;         PG8_STAGE(PG8_SB(1, 0), cB + kstep, voffB); PG8_STAGE(PG8_SA(1, 0), cA + kstep, voffA); PG8_STAGE(PG8_SB(1, 1), cB + hstep + kstep, voffB);
;         PG8_WAIT_V(6); PG8_BAR;
.LBB0_235:
	s_add_u32 s38, s26, 0x40000
	s_addc_u32 s39, s27, 0
	s_lshl_b32 s3, s3, 5
	s_mov_b64 s[40:41], 0x80
	s_and_b32 s46, s3, 0x60
	s_add_i32 m0, s28, 0x18000
	v_lshl_add_u64 v[6:7], v[6:7], 0, s[40:41]
	s_lshl_b32 s5, s2, 13
	s_lshl_b32 s3, s46, 7
	s_waitcnt vmcnt(2)
	s_barrier
	global_load_lds_dwordx4 v[6:7], off
	v_lshl_add_u64 v[4:5], v[4:5], 0, s[40:41]
	s_add_i32 m0, s28, 0x1a000
	s_add_i32 s64, s28, 0x8000
	s_add_i32 s65, s28, 0xa000
	global_load_lds_dwordx4 v[4:5], off
	v_lshl_add_u64 v[0:1], v[0:1], 0, s[40:41]
	s_mov_b32 m0, s64
	s_add_u32 s44, s58, 0xb0080
	global_load_lds_dwordx4 v[0:1], off
	v_mov_b32_e32 v232, v0
	v_mov_b32_e32 v233, v1
	v_lshl_add_u64 v[0:1], v[2:3], 0, s[40:41]
	s_mov_b32 m0, s65
	s_addc_u32 s45, s59, 0
	global_load_lds_dwordx4 v[0:1], off
	v_mov_b32_e32 v234, v0
	v_mov_b32_e32 v235, v1
	s_add_i32 m0, s28, 0x1c000
	v_lshl_add_u64 v[0:1], s[44:45], 0, v[138:139]
	global_load_lds_dwordx4 v[0:1], off
	v_lshl_add_u64 v[0:1], s[44:45], 0, v[142:143]
	s_add_i32 m0, s28, 0x1e000
	v_lshlrev_b32_e32 v3, 2, v201
	global_load_lds_dwordx4 v[0:1], off
	v_bfe_u32 v0, v201, 4, 2
	v_and_b32_e32 v1, 15, v201
	v_lshl_or_b32 v154, s2, 6, v1
	v_lshlrev_b32_e32 v2, 4, v0
	v_lshlrev_b32_e32 v4, 6, v201
	s_movk_i32 s2, 0x3c0
	v_lshl_or_b32 v1, v1, 6, v2
	v_and_b32_e32 v3, 32, v3
	v_and_or_b32 v2, v4, s2, v2
	v_bitop3_b32 v2, s3, v2, v3 bitop3:0xf6
	s_cmpk_lt_u32 s4, 0x100
	v_cmp_eq_u32_e64 s[2:3], 0, v0
	v_lshl_or_b32 v155, v0, 3, s46
	v_add_u16_e32 v0, v8, v9
	s_waitcnt vmcnt(6)
	s_cselect_b64 s[44:45], -1, 0
	v_lshrrev_b16_e32 v0, 1, v0
	s_add_i32 s73, 0, 0x10000
	s_add_i32 s75, 0, 0x14000
	v_bitop3_b32 v1, v1, s5, v3 bitop3:0xde
	v_add_lshl_u32 v144, v10, v0, 1
	v_add_lshl_u32 v146, v11, v0, 1
	v_add_u32_e32 v156, s73, v2
	v_add_u32_e32 v157, s75, v2
	v_mbcnt_lo_u32_b32 v0, -1, 0
	s_add_i32 s73, s73, s21
	s_add_i32 s75, s75, s21
	s_add_i32 s77, 0, 0x18000
	s_add_i32 s78, 0, 0x1c000
	s_mov_b32 s66, 0x18000
	v_mov_b32_e32 v145, v139
	v_mov_b32_e32 v147, v139
	v_add_u32_e32 v158, 0, v1
	s_mov_b32 s67, 0x40000
	s_mov_b32 s68, 0x48000
	s_mov_b32 s69, 0x50000
	s_mov_b32 s70, 0x58000
	v_mbcnt_hi_u32_b32 v159, -1, v0
	s_add_i32 s71, s28, 0xc000
	s_add_i32 s72, s28, 0xe000
	s_add_i32 s74, s73, 0x2000
	s_add_i32 s76, s75, 0x2000
	v_add_u32_e32 v160, s77, v2
	v_add_u32_e32 v161, s78, v2
	s_barrier
	s_branch .LBB0_238

; #define PG8_STAGE(bufoff, gbase, voff) do { _Pragma("unroll") for (int _i = 0; _i < 2; ++_i) \
;         __builtin_amdgcn_global_load_lds((const unsigned*)((const char*)(gbase) + (voff)[_i]), (PG8_LAS unsigned*)(lds + (bufoff) + ldsw + _i * 8192), 16, 0, 0); } while (0)
; #define PG8_LDA(dst, b, h) do { _Pragma("unroll") for (int m = 0; m < 4; ++m) _Pragma("unroll") for (int k = 0; k < 2; ++k) dst[m][k] = *(const PG8_LAS bf16x8*)(lds + PG8_SA(b, h) + aoff + m * 2048 + k * 1024); } while (0)
; #define PG8_LDB(dst, b, h) do { _Pragma("unroll") for (int n = 0; n < 2; ++n) _Pragma("unroll") for (int k = 0; k < 2; ++k) dst[n][k] = *(const PG8_LAS bf16x8*)(lds + PG8_SB(b, h) + boff + n * 2048 + k * 1024); } while (0)
; #define PG8_MMA(ai, bj, At, Bt) do { __builtin_amdgcn_s_setprio(1); _Pragma("unroll") for (int m = 0; m < 4; ++m) _Pragma("unroll") for (int n = 0; n < 2; ++n) _Pragma("unroll") for (int k = 0; k < 2; ++k) \
;         acc[ai][bj][m][n] = __builtin_amdgcn_mfma_f32_16x16x32_bf16(Bt[n][k], At[m][k], acc[ai][bj][m][n], 0, 0, 0); __builtin_amdgcn_s_setprio(0); } while (0)
; #define PG8_WAIT_V(n) asm volatile("s_waitcnt vmcnt(" #n ")" ::: "memory")
; #define PG8_WAIT_L(n) asm volatile("s_waitcnt lgkmcnt(" #n ")" ::: "memory")
; #define PG8_BAR __builtin_amdgcn_s_barrier()
; #define PG8_SCHED __builtin_amdgcn_sched_barrier(0)
; template <class Epi, class Sched, bool ALIGN_EPI = false, bool SP2 = false>
; __device__ __forceinline__ void gemm_phase(PG8_LAS unsigned char* lds, const Gemm g, const Sched& S, const Epi& E) {
;     ...
;             PG8_LDB(B0, 0, 0); PG8_LDB(B1, 0, 1); PG8_SCHED; PG8_LDA(At, 0, 0); PG8_STAGE(PG8_SA(1, 1), a1 + hstep, voffA);
;             PG8_WAIT_V(8); PG8_WAIT_L(0); PG8_BAR; PG8_MMA(0, 0, At, B0); PG8_MMA(0, 1, At, B1); PG8_BAR; PG8_SCHED;
;             PG8_LDA(At, 0, 1); PG8_STAGE(PG8_SB(0, 0), b2, voffB); PG8_STAGE(PG8_SB(0, 1), b2 + hstep, voffB); PG8_STAGE(PG8_SA(0, 0), a2, voffA);
;             PG8_WAIT_V(8); PG8_WAIT_L(0); PG8_BAR; PG8_MMA(1, 0, At, B0); PG8_MMA(1, 1, At, B1); PG8_BAR; PG8_SCHED;
.LBB0_245:
	ds_read_b128 v[128:131], v156
	ds_read_b128 v[132:135], v156 offset:1024
	ds_read_b128 v[148:151], v156 offset:2048
	ds_read_b128 v[162:165], v156 offset:3072
	ds_read_b128 v[166:169], v157
	ds_read_b128 v[170:173], v157 offset:1024
	ds_read_b128 v[174:177], v157 offset:2048
	ds_read_b128 v[178:181], v157 offset:3072
	s_add_u32 s58, s56, 0xfff50080
	s_addc_u32 s59, s57, -1
	s_cmp_eq_u32 s85, 40
	s_cselect_b32 s61, s47, s59
	s_cselect_b32 s60, s46, s58
	s_cselect_b32 s59, s51, s84
	s_cselect_b32 s58, s50, s83
	s_mov_b32 m0, s64
	s_nop 0
	global_load_lds_dwordx4 v[232:233], off
	s_mov_b32 m0, s65
	s_nop 0
	global_load_lds_dwordx4 v[234:235], off
	s_mov_b32 m0, s71
	v_lshl_add_u64 v[152:153], s[56:57], 0, v[144:145]
	ds_read_b128 v[182:185], v158
	ds_read_b128 v[186:189], v158 offset:1024
	ds_read_b128 v[190:193], v158 offset:2048
	ds_read_b128 v[194:197], v158 offset:3072
	ds_read_b128 v[202:205], v158 offset:4096
	ds_read_b128 v[206:209], v158 offset:5120
	ds_read_b128 v[210:213], v158 offset:6144
	ds_read_b128 v[214:217], v158 offset:7168
	global_load_lds_dwordx4 v[152:153], off
	v_lshl_add_u64 v[152:153], s[56:57], 0, v[146:147]
	s_mov_b32 m0, s72
	s_nop 0
	global_load_lds_dwordx4 v[152:153], off
	s_waitcnt vmcnt(8)
	s_waitcnt lgkmcnt(0)
	s_barrier
	s_setprio 1
	s_waitcnt lgkmcnt(0)
	v_mfma_f32_16x16x32_bf16 v[124:127], v[128:131], v[182:185], v[124:127]
	v_mfma_f32_16x16x32_bf16 v[120:123], v[148:151], v[182:185], v[120:123]
	v_mfma_f32_16x16x32_bf16 v[108:111], v[128:131], v[190:193], v[108:111]
	v_mfma_f32_16x16x32_bf16 v[104:107], v[148:151], v[190:193], v[104:107]
	v_mfma_f32_16x16x32_bf16 v[92:95], v[128:131], v[202:205], v[92:95]
	v_mfma_f32_16x16x32_bf16 v[88:91], v[148:151], v[202:205], v[88:91]
	v_mfma_f32_16x16x32_bf16 v[76:79], v[128:131], v[210:213], v[76:79]
	v_mfma_f32_16x16x32_bf16 v[72:75], v[148:151], v[210:213], v[72:75]
	v_mfma_f32_16x16x32_bf16 v[124:127], v[132:135], v[186:189], v[124:127]
	v_mfma_f32_16x16x32_bf16 v[120:123], v[162:165], v[186:189], v[120:123]
	v_mfma_f32_16x16x32_bf16 v[108:111], v[132:135], v[194:197], v[108:111]
	v_mfma_f32_16x16x32_bf16 v[104:107], v[162:165], v[194:197], v[104:107]
	v_mfma_f32_16x16x32_bf16 v[92:95], v[132:135], v[206:209], v[92:95]
	v_mfma_f32_16x16x32_bf16 v[88:91], v[162:165], v[206:209], v[88:91]
	v_mfma_f32_16x16x32_bf16 v[76:79], v[132:135], v[214:217], v[76:79]
	v_mfma_f32_16x16x32_bf16 v[72:75], v[162:165], v[214:217], v[72:75]
	s_setprio 0
	s_setprio 1
	v_mfma_f32_16x16x32_bf16 v[116:119], v[166:169], v[182:185], v[116:119]
	v_mfma_f32_16x16x32_bf16 v[112:115], v[174:177], v[182:185], v[112:115]
	v_mfma_f32_16x16x32_bf16 v[100:103], v[166:169], v[190:193], v[100:103]
	v_mfma_f32_16x16x32_bf16 v[96:99], v[174:177], v[190:193], v[96:99]
	v_mfma_f32_16x16x32_bf16 v[84:87], v[166:169], v[202:205], v[84:87]
	v_mfma_f32_16x16x32_bf16 v[80:83], v[174:177], v[202:205], v[80:83]
	v_mfma_f32_16x16x32_bf16 v[68:71], v[166:169], v[210:213], v[68:71]
	v_mfma_f32_16x16x32_bf16 v[64:67], v[174:177], v[210:213], v[64:67]
	v_mfma_f32_16x16x32_bf16 v[116:119], v[170:173], v[186:189], v[116:119]
	v_mfma_f32_16x16x32_bf16 v[112:115], v[178:181], v[186:189], v[112:115]
	v_mfma_f32_16x16x32_bf16 v[100:103], v[170:173], v[194:197], v[100:103]
	v_mfma_f32_16x16x32_bf16 v[96:99], v[178:181], v[194:197], v[96:99]
	v_mfma_f32_16x16x32_bf16 v[84:87], v[170:173], v[206:209], v[84:87]
	v_mfma_f32_16x16x32_bf16 v[80:83], v[178:181], v[206:209], v[80:83]
	v_mfma_f32_16x16x32_bf16 v[68:71], v[170:173], v[214:217], v[68:71]
	v_mfma_f32_16x16x32_bf16 v[64:67], v[178:181], v[214:217], v[64:67]
	s_setprio 0
	s_barrier
	s_mov_b32 m0, s73
	v_lshl_add_u64 v[152:153], s[58:59], 0, v[138:139]
	s_add_u32 s86, s58, 0xb0000
	ds_read_b128 v[182:185], v158 offset:16384
	ds_read_b128 v[186:189], v158 offset:17408
	ds_read_b128 v[190:193], v158 offset:18432
	ds_read_b128 v[194:197], v158 offset:19456
	ds_read_b128 v[202:205], v158 offset:20480
	ds_read_b128 v[206:209], v158 offset:21504
	ds_read_b128 v[210:213], v158 offset:22528
	ds_read_b128 v[214:217], v158 offset:23552
	global_load_lds_dwordx4 v[152:153], off
	v_lshl_add_u64 v[198:199], s[58:59], 0, v[142:143]
	s_mov_b32 m0, s74
	s_addc_u32 s87, s59, 0
	global_load_lds_dwordx4 v[198:199], off
	v_lshl_add_u64 v[218:219], s[86:87], 0, v[138:139]
	s_mov_b32 m0, s75
	v_lshl_add_u64 v[220:221], s[60:61], 0, v[140:141]
	global_load_lds_dwordx4 v[218:219], off
	v_lshl_add_u64 v[218:219], s[86:87], 0, v[142:143]
	s_mov_b32 m0, s76
	s_nop 0
	global_load_lds_dwordx4 v[218:219], off
	v_lshl_add_u64 v[218:219], s[60:61], 0, v[136:137]
	v_mov_b32_e32 v236, v218
	v_mov_b32_e32 v237, v219
	v_mov_b32_e32 v238, v220
	v_mov_b32_e32 v239, v221
	s_waitcnt vmcnt(6)
	s_waitcnt lgkmcnt(0)
	s_barrier
; #define PG8_STAGE(bufoff, gbase, voff) do { _Pragma("unroll") for (int _i = 0; _i < 2; ++_i) \
;         __builtin_amdgcn_global_load_lds((const unsigned*)((const char*)(gbase) + (voff)[_i]), (PG8_LAS unsigned*)(lds + (bufoff) + ldsw + _i * 8192), 16, 0, 0); } while (0)
; #define PG8_LDA(dst, b, h) do { _Pragma("unroll") for (int m = 0; m < 4; ++m) _Pragma("unroll") for (int k = 0; k < 2; ++k) dst[m][k] = *(const PG8_LAS bf16x8*)(lds + PG8_SA(b, h) + aoff + m * 2048 + k * 1024); } while (0)
; #define PG8_LDB(dst, b, h) do { _Pragma("unroll") for (int n = 0; n < 2; ++n) _Pragma("unroll") for (int k = 0; k < 2; ++k) dst[n][k] = *(const PG8_LAS bf16x8*)(lds + PG8_SB(b, h) + boff + n * 2048 + k * 1024); } while (0)
; #define PG8_MMA(ai, bj, At, Bt) do { __builtin_amdgcn_s_setprio(1); _Pragma("unroll") for (int m = 0; m < 4; ++m) _Pragma("unroll") for (int n = 0; n < 2; ++n) _Pragma("unroll") for (int k = 0; k < 2; ++k) \
;         acc[ai][bj][m][n] = __builtin_amdgcn_mfma_f32_16x16x32_bf16(Bt[n][k], At[m][k], acc[ai][bj][m][n], 0, 0, 0); __builtin_amdgcn_s_setprio(0); } while (0)
; #define PG8_WAIT_V(n) asm volatile("s_waitcnt vmcnt(" #n ")" ::: "memory")
; #define PG8_WAIT_L(n) asm volatile("s_waitcnt lgkmcnt(" #n ")" ::: "memory")
; #define PG8_BAR __builtin_amdgcn_s_barrier()
; #define PG8_SCHED __builtin_amdgcn_sched_barrier(0)
; template <class Epi, class Sched, bool ALIGN_EPI = false, bool SP2 = false>
; __device__ __forceinline__ void gemm_phase(PG8_LAS unsigned char* lds, const Gemm g, const Sched& S, const Epi& E) {
;     ...
;             PG8_WAIT_V(8); PG8_WAIT_L(0); PG8_BAR; PG8_MMA(1, 0, At, B0); PG8_MMA(1, 1, At, B1); PG8_BAR; PG8_SCHED;
;             PG8_LDB(B0, 1, 0); PG8_LDB(B1, 1, 1); PG8_SCHED; PG8_LDA(At, 1, 0); PG8_STAGE(PG8_SA(0, 1), a2 + hstep, voffA);
;             PG8_WAIT_V(8); PG8_WAIT_L(0); PG8_BAR; PG8_MMA(0, 0, At, B0); PG8_MMA(0, 1, At, B1); PG8_BAR; PG8_SCHED;
	s_setprio 1
	s_waitcnt lgkmcnt(0)
	v_mfma_f32_16x16x32_bf16 v[60:63], v[128:131], v[182:185], v[60:63]
	v_mfma_f32_16x16x32_bf16 v[56:59], v[148:151], v[182:185], v[56:59]
	v_mfma_f32_16x16x32_bf16 v[44:47], v[128:131], v[190:193], v[44:47]
	v_mfma_f32_16x16x32_bf16 v[40:43], v[148:151], v[190:193], v[40:43]
	v_mfma_f32_16x16x32_bf16 v[32:35], v[128:131], v[202:205], v[32:35]
	v_mfma_f32_16x16x32_bf16 v[24:27], v[148:151], v[202:205], v[24:27]
	v_mfma_f32_16x16x32_bf16 v[16:19], v[128:131], v[210:213], v[16:19]
	v_mfma_f32_16x16x32_bf16 v[8:11], v[148:151], v[210:213], v[8:11]
	v_mfma_f32_16x16x32_bf16 v[60:63], v[132:135], v[186:189], v[60:63]
	v_mfma_f32_16x16x32_bf16 v[56:59], v[162:165], v[186:189], v[56:59]
	v_mfma_f32_16x16x32_bf16 v[44:47], v[132:135], v[194:197], v[44:47]
	v_mfma_f32_16x16x32_bf16 v[40:43], v[162:165], v[194:197], v[40:43]
	v_mfma_f32_16x16x32_bf16 v[32:35], v[132:135], v[206:209], v[32:35]
	v_mfma_f32_16x16x32_bf16 v[24:27], v[162:165], v[206:209], v[24:27]
	v_mfma_f32_16x16x32_bf16 v[16:19], v[132:135], v[214:217], v[16:19]
	v_mfma_f32_16x16x32_bf16 v[8:11], v[162:165], v[214:217], v[8:11]
	s_setprio 0
	s_setprio 1
	v_mfma_f32_16x16x32_bf16 v[52:55], v[166:169], v[182:185], v[52:55]
	v_mfma_f32_16x16x32_bf16 v[48:51], v[174:177], v[182:185], v[48:51]
	v_mfma_f32_16x16x32_bf16 v[36:39], v[166:169], v[190:193], v[36:39]
	v_mfma_f32_16x16x32_bf16 v[28:31], v[174:177], v[190:193], v[28:31]
	v_mfma_f32_16x16x32_bf16 v[20:23], v[166:169], v[202:205], v[20:23]
	v_mfma_f32_16x16x32_bf16 v[12:15], v[174:177], v[202:205], v[12:15]
	v_mfma_f32_16x16x32_bf16 v[4:7], v[166:169], v[210:213], v[4:7]
	v_mfma_f32_16x16x32_bf16 v[0:3], v[174:177], v[210:213], v[0:3]
	v_mfma_f32_16x16x32_bf16 v[52:55], v[170:173], v[186:189], v[52:55]
	v_mfma_f32_16x16x32_bf16 v[48:51], v[178:181], v[186:189], v[48:51]
	v_mfma_f32_16x16x32_bf16 v[36:39], v[170:173], v[194:197], v[36:39]
	v_mfma_f32_16x16x32_bf16 v[28:31], v[178:181], v[194:197], v[28:31]
	v_mfma_f32_16x16x32_bf16 v[20:23], v[170:173], v[206:209], v[20:23]
	v_mfma_f32_16x16x32_bf16 v[12:15], v[178:181], v[206:209], v[12:15]
	v_mfma_f32_16x16x32_bf16 v[4:7], v[170:173], v[214:217], v[4:7]
	v_mfma_f32_16x16x32_bf16 v[0:3], v[178:181], v[214:217], v[0:3]
	s_setprio 0
	s_barrier
	ds_read_b128 v[128:131], v160
	ds_read_b128 v[132:135], v160 offset:1024
	ds_read_b128 v[148:151], v160 offset:2048
	ds_read_b128 v[162:165], v160 offset:3072
	ds_read_b128 v[166:169], v161
	ds_read_b128 v[170:173], v161 offset:1024
	ds_read_b128 v[174:177], v161 offset:2048
	ds_read_b128 v[178:181], v161 offset:3072
	s_add_u32 s60, s60, 0xb0000
	s_addc_u32 s61, s61, 0
	s_mov_b32 m0, s28
	s_nop 0
	global_load_lds_dwordx4 v[236:237], off
	s_mov_b32 m0, s29
	s_nop 0
	global_load_lds_dwordx4 v[238:239], off
	s_mov_b32 m0, s30
	v_lshl_add_u64 v[222:223], s[60:61], 0, v[136:137]
	ds_read_b128 v[182:185], v158 offset:32768
	ds_read_b128 v[186:189], v158 offset:33792
	ds_read_b128 v[190:193], v158 offset:34816
	ds_read_b128 v[194:197], v158 offset:35840
	ds_read_b128 v[202:205], v158 offset:36864
	ds_read_b128 v[206:209], v158 offset:37888
	ds_read_b128 v[210:213], v158 offset:38912
	ds_read_b128 v[214:217], v158 offset:39936
	global_load_lds_dwordx4 v[222:223], off
	v_lshl_add_u64 v[222:223], s[60:61], 0, v[140:141]
	s_mov_b32 m0, s31
	s_nop 0
	global_load_lds_dwordx4 v[222:223], off
	s_waitcnt vmcnt(8)
	s_waitcnt lgkmcnt(0)
	s_barrier
	s_setprio 1
	s_waitcnt lgkmcnt(0)
	v_mfma_f32_16x16x32_bf16 v[124:127], v[128:131], v[182:185], v[124:127]
	v_mfma_f32_16x16x32_bf16 v[120:123], v[148:151], v[182:185], v[120:123]
	v_mfma_f32_16x16x32_bf16 v[108:111], v[128:131], v[190:193], v[108:111]
	v_mfma_f32_16x16x32_bf16 v[104:107], v[148:151], v[190:193], v[104:107]
	v_mfma_f32_16x16x32_bf16 v[92:95], v[128:131], v[202:205], v[92:95]
	v_mfma_f32_16x16x32_bf16 v[88:91], v[148:151], v[202:205], v[88:91]
	v_mfma_f32_16x16x32_bf16 v[76:79], v[128:131], v[210:213], v[76:79]
	v_mfma_f32_16x16x32_bf16 v[72:75], v[148:151], v[210:213], v[72:75]
	v_mfma_f32_16x16x32_bf16 v[124:127], v[132:135], v[186:189], v[124:127]
	v_mfma_f32_16x16x32_bf16 v[120:123], v[162:165], v[186:189], v[120:123]
	v_mfma_f32_16x16x32_bf16 v[108:111], v[132:135], v[194:197], v[108:111]
	v_mfma_f32_16x16x32_bf16 v[104:107], v[162:165], v[194:197], v[104:107]
	v_mfma_f32_16x16x32_bf16 v[92:95], v[132:135], v[206:209], v[92:95]
	v_mfma_f32_16x16x32_bf16 v[88:91], v[162:165], v[206:209], v[88:91]
	v_mfma_f32_16x16x32_bf16 v[76:79], v[132:135], v[214:217], v[76:79]
	v_mfma_f32_16x16x32_bf16 v[72:75], v[162:165], v[214:217], v[72:75]
	s_setprio 0
	s_setprio 1
	v_mfma_f32_16x16x32_bf16 v[116:119], v[166:169], v[182:185], v[116:119]
	v_mfma_f32_16x16x32_bf16 v[112:115], v[174:177], v[182:185], v[112:115]
	v_mfma_f32_16x16x32_bf16 v[100:103], v[166:169], v[190:193], v[100:103]
	v_mfma_f32_16x16x32_bf16 v[96:99], v[174:177], v[190:193], v[96:99]
	v_mfma_f32_16x16x32_bf16 v[84:87], v[166:169], v[202:205], v[84:87]
	v_mfma_f32_16x16x32_bf16 v[80:83], v[174:177], v[202:205], v[80:83]
	v_mfma_f32_16x16x32_bf16 v[68:71], v[166:169], v[210:213], v[68:71]
	v_mfma_f32_16x16x32_bf16 v[64:67], v[174:177], v[210:213], v[64:67]
	v_mfma_f32_16x16x32_bf16 v[116:119], v[170:173], v[186:189], v[116:119]
	v_mfma_f32_16x16x32_bf16 v[112:115], v[178:181], v[186:189], v[112:115]
	v_mfma_f32_16x16x32_bf16 v[100:103], v[170:173], v[194:197], v[100:103]
	v_mfma_f32_16x16x32_bf16 v[96:99], v[178:181], v[194:197], v[96:99]
	v_mfma_f32_16x16x32_bf16 v[84:87], v[170:173], v[206:209], v[84:87]
	v_mfma_f32_16x16x32_bf16 v[80:83], v[178:181], v[206:209], v[80:83]
	v_mfma_f32_16x16x32_bf16 v[68:71], v[170:173], v[214:217], v[68:71]
	v_mfma_f32_16x16x32_bf16 v[64:67], v[178:181], v[214:217], v[64:67]
	s_setprio 0
	s_barrier
; #define PG8_STAGE(bufoff, gbase, voff) do { _Pragma("unroll") for (int _i = 0; _i < 2; ++_i) \
;         __builtin_amdgcn_global_load_lds((const unsigned*)((const char*)(gbase) + (voff)[_i]), (PG8_LAS unsigned*)(lds + (bufoff) + ldsw + _i * 8192), 16, 0, 0); } while (0)
; #define PG8_LDA(dst, b, h) do { _Pragma("unroll") for (int m = 0; m < 4; ++m) _Pragma("unroll") for (int k = 0; k < 2; ++k) dst[m][k] = *(const PG8_LAS bf16x8*)(lds + PG8_SA(b, h) + aoff + m * 2048 + k * 1024); } while (0)
; #define PG8_MMA(ai, bj, At, Bt) do { __builtin_amdgcn_s_setprio(1); _Pragma("unroll") for (int m = 0; m < 4; ++m) _Pragma("unroll") for (int n = 0; n < 2; ++n) _Pragma("unroll") for (int k = 0; k < 2; ++k) \
;         acc[ai][bj][m][n] = __builtin_amdgcn_mfma_f32_16x16x32_bf16(Bt[n][k], At[m][k], acc[ai][bj][m][n], 0, 0, 0); __builtin_amdgcn_s_setprio(0); } while (0)
; #define PG8_WAIT_V(n) asm volatile("s_waitcnt vmcnt(" #n ")" ::: "memory")
; #define PG8_WAIT_L(n) asm volatile("s_waitcnt lgkmcnt(" #n ")" ::: "memory")
; #define PG8_BAR __builtin_amdgcn_s_barrier()
; #define PG8_SCHED __builtin_amdgcn_sched_barrier(0)
; template <class Epi, class Sched, bool ALIGN_EPI = false, bool SP2 = false>
; __device__ __forceinline__ void gemm_phase(PG8_LAS unsigned char* lds, const Gemm g, const Sched& S, const Epi& E) {
;     ...
;         for (int t = 0; t < nt; t += 2) {
;             const bool last = (t == nt - 2);
;             const char* a1 = cA + (size_t)(t + 1) * kstep;
;             const char* a2 = last ? nA : cA + (size_t)(t + 2) * kstep; const char* b2 = last ? nB : cB + (size_t)(t + 2) * kstep;
;     ...
;             PG8_LDA(At, 1, 1); PG8_STAGE(PG8_SB(1, 0), b3, voffB); PG8_STAGE(PG8_SB(1, 1), b3 + hstep, voffB); PG8_STAGE(PG8_SA(1, 0), a3, voffA);
;             PG8_WAIT_V(8); PG8_WAIT_L(0); PG8_BAR; PG8_MMA(1, 0, At, B0); PG8_MMA(1, 1, At, B1); PG8_BAR; PG8_SCHED;
;     ...
;         if constexpr (ALIGN_EPI) { if (wr == 0) PG8_BAR; }
	s_add_i32 s60, s77, s21
	v_lshl_add_u64 v[152:153], v[152:153], 0, s[40:41]
	s_mov_b32 m0, s60
	ds_read_b128 v[182:185], v158 offset:49152
	ds_read_b128 v[186:189], v158 offset:50176
	ds_read_b128 v[190:193], v158 offset:51200
	ds_read_b128 v[194:197], v158 offset:52224
	ds_read_b128 v[202:205], v158 offset:53248
	ds_read_b128 v[206:209], v158 offset:54272
	ds_read_b128 v[210:213], v158 offset:55296
	ds_read_b128 v[214:217], v158 offset:56320
	global_load_lds_dwordx4 v[152:153], off
	s_add_i32 m0, s60, 0x2000
	s_add_u32 s58, s58, 0xb0080
	v_lshl_add_u64 v[152:153], v[198:199], 0, s[40:41]
	s_addc_u32 s59, s59, 0
	s_add_i32 s60, s78, s21
	global_load_lds_dwordx4 v[152:153], off
	v_lshl_add_u64 v[152:153], s[58:59], 0, v[138:139]
	s_mov_b32 m0, s60
	s_nop 0
	global_load_lds_dwordx4 v[152:153], off
	v_lshl_add_u64 v[152:153], s[58:59], 0, v[142:143]
	s_add_i32 m0, s60, 0x2000
	s_nop 0
	global_load_lds_dwordx4 v[152:153], off
	v_lshl_add_u64 v[152:153], v[218:219], 0, s[40:41]
	v_mov_b32_e32 v232, v152
	v_mov_b32_e32 v233, v153
	v_lshl_add_u64 v[152:153], v[220:221], 0, s[40:41]
	v_mov_b32_e32 v234, v152
	v_mov_b32_e32 v235, v153
	s_waitcnt vmcnt(6)
	s_waitcnt lgkmcnt(0)
	s_barrier
	s_setprio 1
	s_waitcnt lgkmcnt(0)
	v_mfma_f32_16x16x32_bf16 v[60:63], v[128:131], v[182:185], v[60:63]
	v_mfma_f32_16x16x32_bf16 v[56:59], v[148:151], v[182:185], v[56:59]
	v_mfma_f32_16x16x32_bf16 v[44:47], v[128:131], v[190:193], v[44:47]
	v_mfma_f32_16x16x32_bf16 v[40:43], v[148:151], v[190:193], v[40:43]
	v_mfma_f32_16x16x32_bf16 v[32:35], v[128:131], v[202:205], v[32:35]
	v_mfma_f32_16x16x32_bf16 v[24:27], v[148:151], v[202:205], v[24:27]
	v_mfma_f32_16x16x32_bf16 v[16:19], v[128:131], v[210:213], v[16:19]
	v_mfma_f32_16x16x32_bf16 v[8:11], v[148:151], v[210:213], v[8:11]
	v_mfma_f32_16x16x32_bf16 v[60:63], v[132:135], v[186:189], v[60:63]
	v_mfma_f32_16x16x32_bf16 v[56:59], v[162:165], v[186:189], v[56:59]
	v_mfma_f32_16x16x32_bf16 v[44:47], v[132:135], v[194:197], v[44:47]
	v_mfma_f32_16x16x32_bf16 v[40:43], v[162:165], v[194:197], v[40:43]
	v_mfma_f32_16x16x32_bf16 v[32:35], v[132:135], v[206:209], v[32:35]
	v_mfma_f32_16x16x32_bf16 v[24:27], v[162:165], v[206:209], v[24:27]
	v_mfma_f32_16x16x32_bf16 v[16:19], v[132:135], v[214:217], v[16:19]
	v_mfma_f32_16x16x32_bf16 v[8:11], v[162:165], v[214:217], v[8:11]
	s_setprio 0
	s_setprio 1
	v_mfma_f32_16x16x32_bf16 v[52:55], v[166:169], v[182:185], v[52:55]
	v_mfma_f32_16x16x32_bf16 v[48:51], v[174:177], v[182:185], v[48:51]
	v_mfma_f32_16x16x32_bf16 v[36:39], v[166:169], v[190:193], v[36:39]
	v_mfma_f32_16x16x32_bf16 v[28:31], v[174:177], v[190:193], v[28:31]
	v_mfma_f32_16x16x32_bf16 v[20:23], v[166:169], v[202:205], v[20:23]
	v_mfma_f32_16x16x32_bf16 v[12:15], v[174:177], v[202:205], v[12:15]
	v_mfma_f32_16x16x32_bf16 v[4:7], v[166:169], v[210:213], v[4:7]
	v_mfma_f32_16x16x32_bf16 v[0:3], v[174:177], v[210:213], v[0:3]
	v_mfma_f32_16x16x32_bf16 v[52:55], v[170:173], v[186:189], v[52:55]
	v_mfma_f32_16x16x32_bf16 v[48:51], v[178:181], v[186:189], v[48:51]
	v_mfma_f32_16x16x32_bf16 v[36:39], v[170:173], v[194:197], v[36:39]
	v_mfma_f32_16x16x32_bf16 v[28:31], v[178:181], v[194:197], v[28:31]
	v_mfma_f32_16x16x32_bf16 v[20:23], v[170:173], v[206:209], v[20:23]
	v_mfma_f32_16x16x32_bf16 v[12:15], v[178:181], v[206:209], v[12:15]
	v_mfma_f32_16x16x32_bf16 v[4:7], v[170:173], v[214:217], v[4:7]
	v_mfma_f32_16x16x32_bf16 v[0:3], v[178:181], v[214:217], v[0:3]
	s_setprio 0
	s_barrier
	s_add_i32 s85, s85, 2
	s_add_u32 s56, s56, 0x100
	s_addc_u32 s57, s57, 0
	s_add_u32 s83, s83, 0x100
	s_addc_u32 s84, s84, 0
	s_cmp_gt_u32 s85, 41
	s_cbranch_scc0 .LBB0_245
	s_and_b64 vcc, exec, s[44:45]
	s_cbranch_vccz .LBB0_248
	s_barrier

; #define PG8_STAGE(bufoff, gbase, voff) do { _Pragma("unroll") for (int _i = 0; _i < 2; ++_i) \
;         __builtin_amdgcn_global_load_lds((const unsigned*)((const char*)(gbase) + (voff)[_i]), (PG8_LAS unsigned*)(lds + (bufoff) + ldsw + _i * 8192), 16, 0, 0); } while (0)
; #define PG8_WAIT_V(n) asm volatile("s_waitcnt vmcnt(" #n ")" ::: "memory")
; #define PG8_BAR __builtin_amdgcn_s_barrier()
; template <class Epi, class Sched, bool ALIGN_EPI = false, bool SP2 = false>
; __device__ __forceinline__ void gemm_phase(PG8_LAS unsigned char* lds, const Gemm g, const Sched& S, const Epi& E) {
;     const int tid = threadIdx.x, wid = __builtin_amdgcn_readfirstlane(tid >> 6), lane = tid & 63, wr = wid >> 2, wc = wid & 3, fr = lane & 15, fq = lane >> 4;
;     const int K = g.K, nt = K / BK;
;     unsigned voffA[2], voffB[2];
; #pragma unroll
;     for (int i = 0; i < 2; ++i) { int R, C; stage_rc(tid * 16 + i * 8192, R, C); const int Rb = Epi::PERM ? ((R & ~31) + perm32(R & 31)) : R;
;         voffA[i] = (unsigned)(R * K + C) * 2u; voffB[i] = (unsigned)(Rb * K + C) * 2u; }
;     const size_t kstep = (size_t)(BK * 2);
;     const size_t hstep = (size_t)HALF * K * 2;
;     const size_t tstep = 2 * hstep;
;     const unsigned ldsw = (unsigned)wid * 1024u;
;     const int aoff = lds_byte(wr * 64 + fr, fq * 8), boff = lds_byte(wc * 32 + fr, fq * 8);
;     ...
;         PG8_STAGE(PG8_SB(0, 0), cB, voffB); PG8_STAGE(PG8_SB(0, 1), cB + hstep, voffB); PG8_STAGE(PG8_SA(0, 0), cA, voffA); PG8_STAGE(PG8_SA(0, 1), cA + hstep, voffA);
;         if (wr == 1) PG8_BAR;
;         PG8_WAIT_V(2); PG8_BAR;
;         PG8_STAGE(PG8_SB(1, 0), cB + kstep, voffB); PG8_STAGE(PG8_SA(1, 0), cA + kstep, voffA); PG8_STAGE(PG8_SB(1, 1), cB + hstep + kstep, voffB);
;         PG8_WAIT_V(6); PG8_BAR;
.LBB0_319:
	s_add_u32 s50, s26, 0x1c0000
	s_addc_u32 s51, s27, 0
	s_lshl_b32 s3, s3, 5
	s_mov_b64 s[56:57], 0x80
	s_and_b32 s62, s3, 0x60
	s_add_i32 m0, s28, 0x18000
	v_lshl_add_u64 v[6:7], v[6:7], 0, s[56:57]
	s_lshl_b32 s5, s2, 13
	s_lshl_b32 s3, s62, 7
	s_waitcnt vmcnt(2)
	s_barrier
	global_load_lds_dwordx4 v[6:7], off
	v_lshl_add_u64 v[4:5], v[4:5], 0, s[56:57]
	s_add_i32 m0, s28, 0x1a000
	s_add_i32 s39, s28, 0x8000
	s_add_i32 s78, s28, 0xa000
	global_load_lds_dwordx4 v[4:5], off
	v_lshl_add_u64 v[0:1], v[0:1], 0, s[56:57]
	s_mov_b32 m0, s39
	s_add_u32 s60, s74, 0x40080
	global_load_lds_dwordx4 v[0:1], off
	v_mov_b32_e32 v232, v0
	v_mov_b32_e32 v233, v1
	v_lshl_add_u64 v[0:1], v[2:3], 0, s[56:57]
	s_mov_b32 m0, s78
	s_addc_u32 s61, s75, 0
	global_load_lds_dwordx4 v[0:1], off
	v_mov_b32_e32 v234, v0
	v_mov_b32_e32 v235, v1
	s_add_i32 m0, s28, 0x1c000
	v_lshl_add_u64 v[0:1], s[60:61], 0, v[130:131]
	global_load_lds_dwordx4 v[0:1], off
	v_lshl_add_u64 v[0:1], s[60:61], 0, v[134:135]
	s_add_i32 m0, s28, 0x1e000
	v_lshlrev_b32_e32 v3, 2, v158
	global_load_lds_dwordx4 v[0:1], off
	v_bfe_u32 v0, v201, 4, 2
	v_lshlrev_b32_e32 v1, 4, v0
	v_lshl_or_b32 v2, v158, 6, v1
	v_and_b32_e32 v3, 32, v3
	v_lshl_or_b32 v159, s2, 6, v158
	v_bitop3_b32 v2, v2, s5, v3 bitop3:0xde
	v_lshlrev_b32_e32 v3, 6, v201
	s_movk_i32 s2, 0x3c0
	v_and_or_b32 v1, v3, s2, v1
	v_lshlrev_b32_e32 v3, 2, v201
	v_and_b32_e32 v3, 32, v3
	v_bitop3_b32 v160, s3, v1, v3 bitop3:0xf6
	v_cmp_eq_u32_e64 s[2:3], 0, v0
	v_lshl_or_b32 v161, v0, 3, s62
	v_lshlrev_b32_e32 v0, 8, v201
	v_and_b32_e32 v0, 0x38000, v0
	v_lshlrev_b32_e32 v1, 11, v10
	v_or3_b32 v0, v8, v0, v1
	v_add_u32_e32 v136, v0, v9
	v_lshlrev_b32_e32 v0, 4, v11
	v_and_b32_e32 v0, 0x78000, v0
	s_waitcnt vmcnt(6)
	s_cmpk_lt_u32 s58, 0x100
	v_or3_b32 v0, v8, v0, v1
	s_cselect_b64 s[58:59], -1, 0
	v_add_u32_e32 v138, v0, v9
	s_add_i32 s79, 0, 0x10000
	s_add_i32 s80, 0, 0x14000
	v_mbcnt_lo_u32_b32 v0, -1, 0
	v_mov_b32_e32 v137, v131
	v_mov_b32_e32 v139, v131
	v_add_u32_e32 v162, s79, v160
	v_add_u32_e32 v163, s80, v160
	v_add_u32_e32 v164, 0, v2
	v_mov_b32_e32 v165, 0x358637bd
	s_movk_i32 s81, 0x1600
	v_mbcnt_hi_u32_b32 v166, -1, v0
	s_barrier
	s_branch .LBB0_322

; #define PG8_STAGE(bufoff, gbase, voff) do { _Pragma("unroll") for (int _i = 0; _i < 2; ++_i) \
;         __builtin_amdgcn_global_load_lds((const unsigned*)((const char*)(gbase) + (voff)[_i]), (PG8_LAS unsigned*)(lds + (bufoff) + ldsw + _i * 8192), 16, 0, 0); } while (0)
; #define PG8_LDA(dst, b, h) do { _Pragma("unroll") for (int m = 0; m < 4; ++m) _Pragma("unroll") for (int k = 0; k < 2; ++k) dst[m][k] = *(const PG8_LAS bf16x8*)(lds + PG8_SA(b, h) + aoff + m * 2048 + k * 1024); } while (0)
; #define PG8_LDB(dst, b, h) do { _Pragma("unroll") for (int n = 0; n < 2; ++n) _Pragma("unroll") for (int k = 0; k < 2; ++k) dst[n][k] = *(const PG8_LAS bf16x8*)(lds + PG8_SB(b, h) + boff + n * 2048 + k * 1024); } while (0)
; #define PG8_MMA(ai, bj, At, Bt) do { __builtin_amdgcn_s_setprio(1); _Pragma("unroll") for (int m = 0; m < 4; ++m) _Pragma("unroll") for (int n = 0; n < 2; ++n) _Pragma("unroll") for (int k = 0; k < 2; ++k) \
;         acc[ai][bj][m][n] = __builtin_amdgcn_mfma_f32_16x16x32_bf16(Bt[n][k], At[m][k], acc[ai][bj][m][n], 0, 0, 0); __builtin_amdgcn_s_setprio(0); } while (0)
; #define PG8_WAIT_V(n) asm volatile("s_waitcnt vmcnt(" #n ")" ::: "memory")
; #define PG8_WAIT_L(n) asm volatile("s_waitcnt lgkmcnt(" #n ")" ::: "memory")
; #define PG8_BAR __builtin_amdgcn_s_barrier()
; #define PG8_SCHED __builtin_amdgcn_sched_barrier(0)
; template <class Epi, class Sched, bool ALIGN_EPI = false, bool SP2 = false>
; __device__ __forceinline__ void gemm_phase(PG8_LAS unsigned char* lds, const Gemm g, const Sched& S, const Epi& E) {
;     ...
;             PG8_LDB(B0, 0, 0); PG8_LDB(B1, 0, 1); PG8_SCHED; PG8_LDA(At, 0, 0); PG8_STAGE(PG8_SA(1, 1), a1 + hstep, voffA);
;             PG8_WAIT_V(8); PG8_WAIT_L(0); PG8_BAR; PG8_MMA(0, 0, At, B0); PG8_MMA(0, 1, At, B1); PG8_BAR; PG8_SCHED;
;             PG8_LDA(At, 0, 1); PG8_STAGE(PG8_SB(0, 0), b2, voffB); PG8_STAGE(PG8_SB(0, 1), b2 + hstep, voffB); PG8_STAGE(PG8_SA(0, 0), a2, voffA);
;             PG8_WAIT_V(8); PG8_WAIT_L(0); PG8_BAR; PG8_MMA(1, 0, At, B0); PG8_MMA(1, 1, At, B1); PG8_BAR; PG8_SCHED;
.LBB0_325:
	ds_read_b128 v[140:143], v162
	ds_read_b128 v[144:147], v162 offset:1024
	ds_read_b128 v[148:151], v162 offset:2048
	ds_read_b128 v[152:155], v162 offset:3072
	ds_read_b128 v[168:171], v163
	ds_read_b128 v[172:175], v163 offset:1024
	ds_read_b128 v[176:179], v163 offset:2048
	ds_read_b128 v[180:183], v163 offset:3072
	s_add_u32 s74, s72, 0xfffc0080
	s_addc_u32 s75, s73, -1
	s_cmp_eq_u32 s84, 12
	s_cselect_b32 s77, s5, s75
	s_cselect_b32 s76, s61, s74
	s_cselect_b32 s75, s63, s83
	s_cselect_b32 s74, s71, s82
	v_lshl_add_u64 v[156:157], s[72:73], 0, v[136:137]
	s_mov_b32 m0, s39
	s_nop 0
	global_load_lds_dwordx4 v[232:233], off
	s_mov_b32 m0, s78
	s_nop 0
	global_load_lds_dwordx4 v[234:235], off
	s_add_i32 m0, s28, 0xc000
	ds_read_b128 v[184:187], v164
	ds_read_b128 v[188:191], v164 offset:1024
	ds_read_b128 v[192:195], v164 offset:2048
	ds_read_b128 v[196:199], v164 offset:3072
	ds_read_b128 v[202:205], v164 offset:4096
	ds_read_b128 v[206:209], v164 offset:5120
	ds_read_b128 v[210:213], v164 offset:6144
	ds_read_b128 v[214:217], v164 offset:7168
	global_load_lds_dwordx4 v[156:157], off
	v_lshl_add_u64 v[156:157], s[72:73], 0, v[138:139]
	s_add_i32 m0, s28, 0xe000
	s_nop 0
	global_load_lds_dwordx4 v[156:157], off
	s_waitcnt vmcnt(8)
	s_waitcnt lgkmcnt(0)
	s_barrier
	s_setprio 1
	s_waitcnt lgkmcnt(0)
	v_mfma_f32_16x16x32_bf16 v[124:127], v[140:143], v[184:187], v[124:127]
	v_mfma_f32_16x16x32_bf16 v[120:123], v[148:151], v[184:187], v[120:123]
	v_mfma_f32_16x16x32_bf16 v[108:111], v[140:143], v[192:195], v[108:111]
	v_mfma_f32_16x16x32_bf16 v[104:107], v[148:151], v[192:195], v[104:107]
	v_mfma_f32_16x16x32_bf16 v[92:95], v[140:143], v[202:205], v[92:95]
	v_mfma_f32_16x16x32_bf16 v[88:91], v[148:151], v[202:205], v[88:91]
	v_mfma_f32_16x16x32_bf16 v[76:79], v[140:143], v[210:213], v[76:79]
	v_mfma_f32_16x16x32_bf16 v[72:75], v[148:151], v[210:213], v[72:75]
	v_mfma_f32_16x16x32_bf16 v[124:127], v[144:147], v[188:191], v[124:127]
	v_mfma_f32_16x16x32_bf16 v[120:123], v[152:155], v[188:191], v[120:123]
	v_mfma_f32_16x16x32_bf16 v[108:111], v[144:147], v[196:199], v[108:111]
	v_mfma_f32_16x16x32_bf16 v[104:107], v[152:155], v[196:199], v[104:107]
	v_mfma_f32_16x16x32_bf16 v[92:95], v[144:147], v[206:209], v[92:95]
	v_mfma_f32_16x16x32_bf16 v[88:91], v[152:155], v[206:209], v[88:91]
	v_mfma_f32_16x16x32_bf16 v[76:79], v[144:147], v[214:217], v[76:79]
	v_mfma_f32_16x16x32_bf16 v[72:75], v[152:155], v[214:217], v[72:75]
	s_setprio 0
	s_setprio 1
	v_mfma_f32_16x16x32_bf16 v[116:119], v[168:171], v[184:187], v[116:119]
	v_mfma_f32_16x16x32_bf16 v[112:115], v[176:179], v[184:187], v[112:115]
	v_mfma_f32_16x16x32_bf16 v[100:103], v[168:171], v[192:195], v[100:103]
	v_mfma_f32_16x16x32_bf16 v[96:99], v[176:179], v[192:195], v[96:99]
	v_mfma_f32_16x16x32_bf16 v[84:87], v[168:171], v[202:205], v[84:87]
	v_mfma_f32_16x16x32_bf16 v[80:83], v[176:179], v[202:205], v[80:83]
	v_mfma_f32_16x16x32_bf16 v[68:71], v[168:171], v[210:213], v[68:71]
	v_mfma_f32_16x16x32_bf16 v[64:67], v[176:179], v[210:213], v[64:67]
	v_mfma_f32_16x16x32_bf16 v[116:119], v[172:175], v[188:191], v[116:119]
	v_mfma_f32_16x16x32_bf16 v[112:115], v[180:183], v[188:191], v[112:115]
	v_mfma_f32_16x16x32_bf16 v[100:103], v[172:175], v[196:199], v[100:103]
	v_mfma_f32_16x16x32_bf16 v[96:99], v[180:183], v[196:199], v[96:99]
	v_mfma_f32_16x16x32_bf16 v[84:87], v[172:175], v[206:209], v[84:87]
	v_mfma_f32_16x16x32_bf16 v[80:83], v[180:183], v[206:209], v[80:83]
	v_mfma_f32_16x16x32_bf16 v[68:71], v[172:175], v[214:217], v[68:71]
	v_mfma_f32_16x16x32_bf16 v[64:67], v[180:183], v[214:217], v[64:67]
	s_setprio 0
	s_barrier
	s_add_i32 s85, s79, s21
	v_lshl_add_u64 v[156:157], s[74:75], 0, v[130:131]
	s_mov_b32 m0, s85
	ds_read_b128 v[184:187], v164 offset:16384
	ds_read_b128 v[188:191], v164 offset:17408
	ds_read_b128 v[192:195], v164 offset:18432
	ds_read_b128 v[196:199], v164 offset:19456
	ds_read_b128 v[202:205], v164 offset:20480
	ds_read_b128 v[206:209], v164 offset:21504
	ds_read_b128 v[210:213], v164 offset:22528
	ds_read_b128 v[214:217], v164 offset:23552
	global_load_lds_dwordx4 v[156:157], off
	s_add_i32 m0, s85, 0x2000
	s_add_u32 s86, s74, 0x40000
	v_lshl_add_u64 v[218:219], s[74:75], 0, v[134:135]
	s_addc_u32 s87, s75, 0
	s_add_i32 s85, s80, s21
	global_load_lds_dwordx4 v[218:219], off
	v_lshl_add_u64 v[220:221], s[86:87], 0, v[130:131]
	s_mov_b32 m0, s85
	v_lshl_add_u64 v[222:223], s[76:77], 0, v[132:133]
	global_load_lds_dwordx4 v[220:221], off
	v_lshl_add_u64 v[220:221], s[86:87], 0, v[134:135]
	s_add_i32 m0, s85, 0x2000
	s_nop 0
	global_load_lds_dwordx4 v[220:221], off
	v_lshl_add_u64 v[220:221], s[76:77], 0, v[128:129]
	v_mov_b32_e32 v236, v220
	v_mov_b32_e32 v237, v221
	v_mov_b32_e32 v238, v222
	v_mov_b32_e32 v239, v223
	s_waitcnt vmcnt(6)
	s_waitcnt lgkmcnt(0)
	s_barrier
; #define PG8_STAGE(bufoff, gbase, voff) do { _Pragma("unroll") for (int _i = 0; _i < 2; ++_i) \
;         __builtin_amdgcn_global_load_lds((const unsigned*)((const char*)(gbase) + (voff)[_i]), (PG8_LAS unsigned*)(lds + (bufoff) + ldsw + _i * 8192), 16, 0, 0); } while (0)
; #define PG8_LDA(dst, b, h) do { _Pragma("unroll") for (int m = 0; m < 4; ++m) _Pragma("unroll") for (int k = 0; k < 2; ++k) dst[m][k] = *(const PG8_LAS bf16x8*)(lds + PG8_SA(b, h) + aoff + m * 2048 + k * 1024); } while (0)
; #define PG8_LDB(dst, b, h) do { _Pragma("unroll") for (int n = 0; n < 2; ++n) _Pragma("unroll") for (int k = 0; k < 2; ++k) dst[n][k] = *(const PG8_LAS bf16x8*)(lds + PG8_SB(b, h) + boff + n * 2048 + k * 1024); } while (0)
; #define PG8_MMA(ai, bj, At, Bt) do { __builtin_amdgcn_s_setprio(1); _Pragma("unroll") for (int m = 0; m < 4; ++m) _Pragma("unroll") for (int n = 0; n < 2; ++n) _Pragma("unroll") for (int k = 0; k < 2; ++k) \
;         acc[ai][bj][m][n] = __builtin_amdgcn_mfma_f32_16x16x32_bf16(Bt[n][k], At[m][k], acc[ai][bj][m][n], 0, 0, 0); __builtin_amdgcn_s_setprio(0); } while (0)
; #define PG8_WAIT_V(n) asm volatile("s_waitcnt vmcnt(" #n ")" ::: "memory")
; #define PG8_WAIT_L(n) asm volatile("s_waitcnt lgkmcnt(" #n ")" ::: "memory")
; #define PG8_BAR __builtin_amdgcn_s_barrier()
; #define PG8_SCHED __builtin_amdgcn_sched_barrier(0)
; template <class Epi, class Sched, bool ALIGN_EPI = false, bool SP2 = false>
; __device__ __forceinline__ void gemm_phase(PG8_LAS unsigned char* lds, const Gemm g, const Sched& S, const Epi& E) {
;     ...
;             PG8_WAIT_V(8); PG8_WAIT_L(0); PG8_BAR; PG8_MMA(1, 0, At, B0); PG8_MMA(1, 1, At, B1); PG8_BAR; PG8_SCHED;
;             PG8_LDB(B0, 1, 0); PG8_LDB(B1, 1, 1); PG8_SCHED; PG8_LDA(At, 1, 0); PG8_STAGE(PG8_SA(0, 1), a2 + hstep, voffA);
;             PG8_WAIT_V(8); PG8_WAIT_L(0); PG8_BAR; PG8_MMA(0, 0, At, B0); PG8_MMA(0, 1, At, B1); PG8_BAR; PG8_SCHED;
	s_setprio 1
	s_waitcnt lgkmcnt(0)
	v_mfma_f32_16x16x32_bf16 v[60:63], v[140:143], v[184:187], v[60:63]
	v_mfma_f32_16x16x32_bf16 v[56:59], v[148:151], v[184:187], v[56:59]
	v_mfma_f32_16x16x32_bf16 v[44:47], v[140:143], v[192:195], v[44:47]
	v_mfma_f32_16x16x32_bf16 v[40:43], v[148:151], v[192:195], v[40:43]
	v_mfma_f32_16x16x32_bf16 v[28:31], v[140:143], v[202:205], v[28:31]
	v_mfma_f32_16x16x32_bf16 v[24:27], v[148:151], v[202:205], v[24:27]
	v_mfma_f32_16x16x32_bf16 v[12:15], v[140:143], v[210:213], v[12:15]
	v_mfma_f32_16x16x32_bf16 v[8:11], v[148:151], v[210:213], v[8:11]
	v_mfma_f32_16x16x32_bf16 v[60:63], v[144:147], v[188:191], v[60:63]
	v_mfma_f32_16x16x32_bf16 v[56:59], v[152:155], v[188:191], v[56:59]
	v_mfma_f32_16x16x32_bf16 v[44:47], v[144:147], v[196:199], v[44:47]
	v_mfma_f32_16x16x32_bf16 v[40:43], v[152:155], v[196:199], v[40:43]
	v_mfma_f32_16x16x32_bf16 v[28:31], v[144:147], v[206:209], v[28:31]
	v_mfma_f32_16x16x32_bf16 v[24:27], v[152:155], v[206:209], v[24:27]
	v_mfma_f32_16x16x32_bf16 v[12:15], v[144:147], v[214:217], v[12:15]
	v_mfma_f32_16x16x32_bf16 v[8:11], v[152:155], v[214:217], v[8:11]
	s_setprio 0
	s_setprio 1
	v_mfma_f32_16x16x32_bf16 v[52:55], v[168:171], v[184:187], v[52:55]
	v_mfma_f32_16x16x32_bf16 v[48:51], v[176:179], v[184:187], v[48:51]
	v_mfma_f32_16x16x32_bf16 v[36:39], v[168:171], v[192:195], v[36:39]
	v_mfma_f32_16x16x32_bf16 v[32:35], v[176:179], v[192:195], v[32:35]
	v_mfma_f32_16x16x32_bf16 v[20:23], v[168:171], v[202:205], v[20:23]
	v_mfma_f32_16x16x32_bf16 v[16:19], v[176:179], v[202:205], v[16:19]
	v_mfma_f32_16x16x32_bf16 v[4:7], v[168:171], v[210:213], v[4:7]
	v_mfma_f32_16x16x32_bf16 v[0:3], v[176:179], v[210:213], v[0:3]
	v_mfma_f32_16x16x32_bf16 v[52:55], v[172:175], v[188:191], v[52:55]
	v_mfma_f32_16x16x32_bf16 v[48:51], v[180:183], v[188:191], v[48:51]
	v_mfma_f32_16x16x32_bf16 v[36:39], v[172:175], v[196:199], v[36:39]
	v_mfma_f32_16x16x32_bf16 v[32:35], v[180:183], v[196:199], v[32:35]
	v_mfma_f32_16x16x32_bf16 v[20:23], v[172:175], v[206:209], v[20:23]
	v_mfma_f32_16x16x32_bf16 v[16:19], v[180:183], v[206:209], v[16:19]
	v_mfma_f32_16x16x32_bf16 v[4:7], v[172:175], v[214:217], v[4:7]
	v_mfma_f32_16x16x32_bf16 v[0:3], v[180:183], v[214:217], v[0:3]
	s_setprio 0
	s_barrier
	s_add_i32 s85, 0, 0x18000
	s_add_i32 s86, 0, 0x1c000
	v_add_u32_e32 v152, s85, v160
	v_add_u32_e32 v167, s86, v160
	ds_read_b128 v[140:143], v152
	ds_read_b128 v[144:147], v152 offset:1024
	ds_read_b128 v[148:151], v152 offset:2048
	ds_read_b128 v[152:155], v152 offset:3072
	ds_read_b128 v[168:171], v167
	ds_read_b128 v[172:175], v167 offset:1024
	ds_read_b128 v[176:179], v167 offset:2048
	ds_read_b128 v[180:183], v167 offset:3072
	s_add_u32 s76, s76, 0x40000
	s_addc_u32 s77, s77, 0
	s_mov_b32 m0, s28
	s_nop 0
	global_load_lds_dwordx4 v[236:237], off
	s_mov_b32 m0, s29
	s_nop 0
	global_load_lds_dwordx4 v[238:239], off
	s_mov_b32 m0, s30
	v_lshl_add_u64 v[224:225], s[76:77], 0, v[128:129]
	ds_read_b128 v[184:187], v164 offset:32768
	ds_read_b128 v[188:191], v164 offset:33792
	ds_read_b128 v[192:195], v164 offset:34816
	ds_read_b128 v[196:199], v164 offset:35840
	ds_read_b128 v[202:205], v164 offset:36864
	ds_read_b128 v[206:209], v164 offset:37888
	ds_read_b128 v[210:213], v164 offset:38912
	ds_read_b128 v[214:217], v164 offset:39936
	global_load_lds_dwordx4 v[224:225], off
	v_lshl_add_u64 v[224:225], s[76:77], 0, v[132:133]
	s_mov_b32 m0, s31
	s_nop 0
	global_load_lds_dwordx4 v[224:225], off
	s_waitcnt vmcnt(8)
	s_waitcnt lgkmcnt(0)
	s_barrier
	s_setprio 1
	s_waitcnt lgkmcnt(0)
	v_mfma_f32_16x16x32_bf16 v[124:127], v[140:143], v[184:187], v[124:127]
	v_mfma_f32_16x16x32_bf16 v[120:123], v[148:151], v[184:187], v[120:123]
	v_mfma_f32_16x16x32_bf16 v[108:111], v[140:143], v[192:195], v[108:111]
	v_mfma_f32_16x16x32_bf16 v[104:107], v[148:151], v[192:195], v[104:107]
	v_mfma_f32_16x16x32_bf16 v[92:95], v[140:143], v[202:205], v[92:95]
	v_mfma_f32_16x16x32_bf16 v[88:91], v[148:151], v[202:205], v[88:91]
	v_mfma_f32_16x16x32_bf16 v[76:79], v[140:143], v[210:213], v[76:79]
	v_mfma_f32_16x16x32_bf16 v[72:75], v[148:151], v[210:213], v[72:75]
	v_mfma_f32_16x16x32_bf16 v[124:127], v[144:147], v[188:191], v[124:127]
	v_mfma_f32_16x16x32_bf16 v[120:123], v[152:155], v[188:191], v[120:123]
	v_mfma_f32_16x16x32_bf16 v[108:111], v[144:147], v[196:199], v[108:111]
	v_mfma_f32_16x16x32_bf16 v[104:107], v[152:155], v[196:199], v[104:107]
	v_mfma_f32_16x16x32_bf16 v[92:95], v[144:147], v[206:209], v[92:95]
	v_mfma_f32_16x16x32_bf16 v[88:91], v[152:155], v[206:209], v[88:91]
	v_mfma_f32_16x16x32_bf16 v[76:79], v[144:147], v[214:217], v[76:79]
	v_mfma_f32_16x16x32_bf16 v[72:75], v[152:155], v[214:217], v[72:75]
	s_setprio 0
	s_setprio 1
	v_mfma_f32_16x16x32_bf16 v[116:119], v[168:171], v[184:187], v[116:119]
	v_mfma_f32_16x16x32_bf16 v[112:115], v[176:179], v[184:187], v[112:115]
	v_mfma_f32_16x16x32_bf16 v[100:103], v[168:171], v[192:195], v[100:103]
	v_mfma_f32_16x16x32_bf16 v[96:99], v[176:179], v[192:195], v[96:99]
	v_mfma_f32_16x16x32_bf16 v[84:87], v[168:171], v[202:205], v[84:87]
	v_mfma_f32_16x16x32_bf16 v[80:83], v[176:179], v[202:205], v[80:83]
	v_mfma_f32_16x16x32_bf16 v[68:71], v[168:171], v[210:213], v[68:71]
	v_mfma_f32_16x16x32_bf16 v[64:67], v[176:179], v[210:213], v[64:67]
	v_mfma_f32_16x16x32_bf16 v[116:119], v[172:175], v[188:191], v[116:119]
	v_mfma_f32_16x16x32_bf16 v[112:115], v[180:183], v[188:191], v[112:115]
	v_mfma_f32_16x16x32_bf16 v[100:103], v[172:175], v[196:199], v[100:103]
	v_mfma_f32_16x16x32_bf16 v[96:99], v[180:183], v[196:199], v[96:99]
	v_mfma_f32_16x16x32_bf16 v[84:87], v[172:175], v[206:209], v[84:87]
	v_mfma_f32_16x16x32_bf16 v[80:83], v[180:183], v[206:209], v[80:83]
	v_mfma_f32_16x16x32_bf16 v[68:71], v[172:175], v[214:217], v[68:71]
	v_mfma_f32_16x16x32_bf16 v[64:67], v[180:183], v[214:217], v[64:67]
	s_setprio 0
	s_barrier
; #define PG8_STAGE(bufoff, gbase, voff) do { _Pragma("unroll") for (int _i = 0; _i < 2; ++_i) \
;         __builtin_amdgcn_global_load_lds((const unsigned*)((const char*)(gbase) + (voff)[_i]), (PG8_LAS unsigned*)(lds + (bufoff) + ldsw + _i * 8192), 16, 0, 0); } while (0)
; #define PG8_LDA(dst, b, h) do { _Pragma("unroll") for (int m = 0; m < 4; ++m) _Pragma("unroll") for (int k = 0; k < 2; ++k) dst[m][k] = *(const PG8_LAS bf16x8*)(lds + PG8_SA(b, h) + aoff + m * 2048 + k * 1024); } while (0)
; #define PG8_MMA(ai, bj, At, Bt) do { __builtin_amdgcn_s_setprio(1); _Pragma("unroll") for (int m = 0; m < 4; ++m) _Pragma("unroll") for (int n = 0; n < 2; ++n) _Pragma("unroll") for (int k = 0; k < 2; ++k) \
;         acc[ai][bj][m][n] = __builtin_amdgcn_mfma_f32_16x16x32_bf16(Bt[n][k], At[m][k], acc[ai][bj][m][n], 0, 0, 0); __builtin_amdgcn_s_setprio(0); } while (0)
; #define PG8_WAIT_V(n) asm volatile("s_waitcnt vmcnt(" #n ")" ::: "memory")
; #define PG8_WAIT_L(n) asm volatile("s_waitcnt lgkmcnt(" #n ")" ::: "memory")
; #define PG8_BAR __builtin_amdgcn_s_barrier()
; #define PG8_SCHED __builtin_amdgcn_sched_barrier(0)
; template <class Epi, class Sched, bool ALIGN_EPI = false, bool SP2 = false>
; __device__ __forceinline__ void gemm_phase(PG8_LAS unsigned char* lds, const Gemm g, const Sched& S, const Epi& E) {
;     ...
;         for (int t = 0; t < nt; t += 2) {
;             const bool last = (t == nt - 2);
;             const char* a1 = cA + (size_t)(t + 1) * kstep;
;             const char* a2 = last ? nA : cA + (size_t)(t + 2) * kstep; const char* b2 = last ? nB : cB + (size_t)(t + 2) * kstep;
;     ...
;             PG8_LDA(At, 1, 1); PG8_STAGE(PG8_SB(1, 0), b3, voffB); PG8_STAGE(PG8_SB(1, 1), b3 + hstep, voffB); PG8_STAGE(PG8_SA(1, 0), a3, voffA);
;             PG8_WAIT_V(8); PG8_WAIT_L(0); PG8_BAR; PG8_MMA(1, 0, At, B0); PG8_MMA(1, 1, At, B1); PG8_BAR; PG8_SCHED;
;     ...
;         if constexpr (ALIGN_EPI) { if (wr == 0) PG8_BAR; }
	s_add_i32 s76, s85, s21
	v_lshl_add_u64 v[156:157], v[156:157], 0, s[56:57]
	s_mov_b32 m0, s76
	ds_read_b128 v[184:187], v164 offset:49152
	ds_read_b128 v[188:191], v164 offset:50176
	ds_read_b128 v[192:195], v164 offset:51200
	ds_read_b128 v[196:199], v164 offset:52224
	ds_read_b128 v[202:205], v164 offset:53248
	ds_read_b128 v[206:209], v164 offset:54272
	ds_read_b128 v[210:213], v164 offset:55296
	ds_read_b128 v[214:217], v164 offset:56320
	global_load_lds_dwordx4 v[156:157], off
	s_add_i32 m0, s76, 0x2000
	s_add_u32 s74, s74, 0x40080
	v_lshl_add_u64 v[156:157], v[218:219], 0, s[56:57]
	s_addc_u32 s75, s75, 0
	s_add_i32 s76, s86, s21
	global_load_lds_dwordx4 v[156:157], off
	v_lshl_add_u64 v[156:157], s[74:75], 0, v[130:131]
	s_mov_b32 m0, s76
	s_nop 0
	global_load_lds_dwordx4 v[156:157], off
	v_lshl_add_u64 v[156:157], s[74:75], 0, v[134:135]
	s_add_i32 m0, s76, 0x2000
	s_nop 0
	global_load_lds_dwordx4 v[156:157], off
	v_lshl_add_u64 v[156:157], v[220:221], 0, s[56:57]
	v_mov_b32_e32 v232, v156
	v_mov_b32_e32 v233, v157
	v_lshl_add_u64 v[156:157], v[222:223], 0, s[56:57]
	v_mov_b32_e32 v234, v156
	v_mov_b32_e32 v235, v157
	s_waitcnt vmcnt(6)
	s_waitcnt lgkmcnt(0)
	s_barrier
	s_setprio 1
	s_waitcnt lgkmcnt(0)
	v_mfma_f32_16x16x32_bf16 v[60:63], v[140:143], v[184:187], v[60:63]
	v_mfma_f32_16x16x32_bf16 v[56:59], v[148:151], v[184:187], v[56:59]
	v_mfma_f32_16x16x32_bf16 v[44:47], v[140:143], v[192:195], v[44:47]
	v_mfma_f32_16x16x32_bf16 v[40:43], v[148:151], v[192:195], v[40:43]
	v_mfma_f32_16x16x32_bf16 v[28:31], v[140:143], v[202:205], v[28:31]
	v_mfma_f32_16x16x32_bf16 v[24:27], v[148:151], v[202:205], v[24:27]
	v_mfma_f32_16x16x32_bf16 v[12:15], v[140:143], v[210:213], v[12:15]
	v_mfma_f32_16x16x32_bf16 v[8:11], v[148:151], v[210:213], v[8:11]
	v_mfma_f32_16x16x32_bf16 v[60:63], v[144:147], v[188:191], v[60:63]
	v_mfma_f32_16x16x32_bf16 v[56:59], v[152:155], v[188:191], v[56:59]
	v_mfma_f32_16x16x32_bf16 v[44:47], v[144:147], v[196:199], v[44:47]
	v_mfma_f32_16x16x32_bf16 v[40:43], v[152:155], v[196:199], v[40:43]
	v_mfma_f32_16x16x32_bf16 v[28:31], v[144:147], v[206:209], v[28:31]
	v_mfma_f32_16x16x32_bf16 v[24:27], v[152:155], v[206:209], v[24:27]
	v_mfma_f32_16x16x32_bf16 v[12:15], v[144:147], v[214:217], v[12:15]
	v_mfma_f32_16x16x32_bf16 v[8:11], v[152:155], v[214:217], v[8:11]
	s_setprio 0
	s_setprio 1
	v_mfma_f32_16x16x32_bf16 v[52:55], v[168:171], v[184:187], v[52:55]
	v_mfma_f32_16x16x32_bf16 v[48:51], v[176:179], v[184:187], v[48:51]
	v_mfma_f32_16x16x32_bf16 v[36:39], v[168:171], v[192:195], v[36:39]
	v_mfma_f32_16x16x32_bf16 v[32:35], v[176:179], v[192:195], v[32:35]
	v_mfma_f32_16x16x32_bf16 v[20:23], v[168:171], v[202:205], v[20:23]
	v_mfma_f32_16x16x32_bf16 v[16:19], v[176:179], v[202:205], v[16:19]
	v_mfma_f32_16x16x32_bf16 v[4:7], v[168:171], v[210:213], v[4:7]
	v_mfma_f32_16x16x32_bf16 v[0:3], v[176:179], v[210:213], v[0:3]
	v_mfma_f32_16x16x32_bf16 v[52:55], v[172:175], v[188:191], v[52:55]
	v_mfma_f32_16x16x32_bf16 v[48:51], v[180:183], v[188:191], v[48:51]
	v_mfma_f32_16x16x32_bf16 v[36:39], v[172:175], v[196:199], v[36:39]
	v_mfma_f32_16x16x32_bf16 v[32:35], v[180:183], v[196:199], v[32:35]
	v_mfma_f32_16x16x32_bf16 v[20:23], v[172:175], v[206:209], v[20:23]
	v_mfma_f32_16x16x32_bf16 v[16:19], v[180:183], v[206:209], v[16:19]
	v_mfma_f32_16x16x32_bf16 v[4:7], v[172:175], v[214:217], v[4:7]
	v_mfma_f32_16x16x32_bf16 v[0:3], v[180:183], v[214:217], v[0:3]
	s_setprio 0
	s_barrier
	s_add_i32 s84, s84, 2
	s_add_u32 s72, s72, 0x100
	s_addc_u32 s73, s73, 0
	s_add_u32 s82, s82, 0x100
	s_addc_u32 s83, s83, 0
	s_cmp_gt_u32 s84, 13
	s_cbranch_scc0 .LBB0_325
	s_and_b64 vcc, exec, s[58:59]
	s_cbranch_vccz .LBB0_328
	s_barrier

; #define PG8_STAGE(bufoff, gbase, voff) do { _Pragma("unroll") for (int _i = 0; _i < 2; ++_i) \
;         __builtin_amdgcn_global_load_lds((const unsigned*)((const char*)(gbase) + (voff)[_i]), (PG8_LAS unsigned*)(lds + (bufoff) + ldsw + _i * 8192), 16, 0, 0); } while (0)
; #define PG8_WAIT_V(n) asm volatile("s_waitcnt vmcnt(" #n ")" ::: "memory")
; #define PG8_BAR __builtin_amdgcn_s_barrier()
; template <class Epi, class Sched, bool ALIGN_EPI = false, bool SP2 = false>
; __device__ __forceinline__ void gemm_phase(PG8_LAS unsigned char* lds, const Gemm g, const Sched& S, const Epi& E) {
;     const int tid = threadIdx.x, wid = __builtin_amdgcn_readfirstlane(tid >> 6), lane = tid & 63, wr = wid >> 2, wc = wid & 3, fr = lane & 15, fq = lane >> 4;
;     const int K = g.K, nt = K / BK;
;     unsigned voffA[2], voffB[2];
; #pragma unroll
;     for (int i = 0; i < 2; ++i) { int R, C; stage_rc(tid * 16 + i * 8192, R, C); const int Rb = Epi::PERM ? ((R & ~31) + perm32(R & 31)) : R;
;         voffA[i] = (unsigned)(R * K + C) * 2u; voffB[i] = (unsigned)(Rb * K + C) * 2u; }
;     const size_t kstep = (size_t)(BK * 2);
;     const size_t hstep = (size_t)HALF * K * 2;
;     const size_t tstep = 2 * hstep;
;     const unsigned ldsw = (unsigned)wid * 1024u;
;     const int aoff = lds_byte(wr * 64 + fr, fq * 8), boff = lds_byte(wc * 32 + fr, fq * 8);
;     ...
;         PG8_STAGE(PG8_SB(0, 0), cB, voffB); PG8_STAGE(PG8_SB(0, 1), cB + hstep, voffB); PG8_STAGE(PG8_SA(0, 0), cA, voffA); PG8_STAGE(PG8_SA(0, 1), cA + hstep, voffA);
;         if (wr == 1) PG8_BAR;
;         PG8_WAIT_V(2); PG8_BAR;
;         PG8_STAGE(PG8_SB(1, 0), cB + kstep, voffB); PG8_STAGE(PG8_SA(1, 0), cA + kstep, voffA); PG8_STAGE(PG8_SB(1, 1), cB + hstep + kstep, voffB);
;         PG8_WAIT_V(6); PG8_BAR;
.LBB0_576:
	s_add_u32 s64, s26, 0x80000
	s_addc_u32 s65, s27, 0
	s_lshl_b32 s2, s2, 5
	s_mov_b64 s[66:67], 0x80
	s_and_b32 s58, s2, 0x60
	s_add_i32 m0, s29, 0x18000
	v_lshl_add_u64 v[6:7], v[6:7], 0, s[66:67]
	s_lshl_b32 s5, s4, 13
	s_lshl_b32 s59, s58, 7
	s_waitcnt vmcnt(2)
	s_barrier
	global_load_lds_dwordx4 v[6:7], off
	v_lshl_add_u64 v[4:5], v[4:5], 0, s[66:67]
	s_add_i32 m0, s29, 0x1a000
	s_add_i32 s2, s29, 0x8000
	s_add_i32 s3, s29, 0xa000
	global_load_lds_dwordx4 v[4:5], off
	v_lshl_add_u64 v[0:1], v[0:1], 0, s[66:67]
	s_mov_b32 m0, s2
	s_add_u32 s56, s86, 0x40080
	global_load_lds_dwordx4 v[0:1], off
	v_mov_b32_e32 v232, v0
	v_mov_b32_e32 v233, v1
	v_lshl_add_u64 v[0:1], v[2:3], 0, s[66:67]
	s_mov_b32 m0, s3
	s_addc_u32 s57, s87, 0
	global_load_lds_dwordx4 v[0:1], off
	v_mov_b32_e32 v234, v0
	v_mov_b32_e32 v235, v1
	s_add_i32 m0, s29, 0x1c000
	v_lshl_add_u64 v[0:1], s[56:57], 0, v[148:149]
	global_load_lds_dwordx4 v[0:1], off
	v_lshl_add_u64 v[0:1], s[56:57], 0, v[152:153]
	s_add_i32 m0, s29, 0x1e000
	v_lshlrev_b32_e32 v3, 2, v201
	global_load_lds_dwordx4 v[0:1], off
	v_bfe_u32 v0, v201, 4, 2
	v_and_b32_e32 v1, 15, v201
	v_lshlrev_b32_e32 v2, 4, v0
	v_lshl_or_b32 v145, s4, 6, v1
	v_lshl_or_b32 v1, v1, 6, v2
	v_and_b32_e32 v3, 32, v3
	v_lshlrev_b32_e32 v4, 6, v201
	s_movk_i32 s4, 0x3c0
	v_bitop3_b32 v1, v1, s5, v3 bitop3:0xde
	v_and_or_b32 v2, v4, s4, v2
	v_cmp_eq_u32_e64 s[4:5], 0, v0
	v_lshl_or_b32 v167, v0, 3, s58
	v_lshlrev_b32_e32 v0, 8, v201
	v_bitop3_b32 v166, s59, v2, v3 bitop3:0xf6
	v_and_b32_e32 v0, 0x38000, v0
	v_lshlrev_b32_e32 v2, 11, v10
	v_or3_b32 v0, v8, v0, v2
	v_add_u32_e32 v154, v0, v9
	v_lshlrev_b32_e32 v0, 4, v11
	v_and_b32_e32 v0, 0x78000, v0
	s_waitcnt vmcnt(6)
	s_cmpk_lt_u32 s11, 0x100
	v_or3_b32 v0, v8, v0, v2
	s_cselect_b64 s[68:69], -1, 0
	v_add_u32_e32 v156, v0, v9
	s_add_i32 s11, 0, 0x10000
	s_add_i32 s83, 0, 0x14000
	v_mbcnt_lo_u32_b32 v0, -1, 0
	v_mov_b32_e32 v155, v149
	v_mov_b32_e32 v157, v149
	v_add_u32_e32 v168, s11, v166
	v_add_u32_e32 v169, s83, v166
	v_add_u32_e32 v170, 0, v1
	v_mbcnt_hi_u32_b32 v171, -1, v0
	s_barrier
	s_branch .LBB0_579

; #define PG8_STAGE(bufoff, gbase, voff) do { _Pragma("unroll") for (int _i = 0; _i < 2; ++_i) \
;         __builtin_amdgcn_global_load_lds((const unsigned*)((const char*)(gbase) + (voff)[_i]), (PG8_LAS unsigned*)(lds + (bufoff) + ldsw + _i * 8192), 16, 0, 0); } while (0)
; #define PG8_LDA(dst, b, h) do { _Pragma("unroll") for (int m = 0; m < 4; ++m) _Pragma("unroll") for (int k = 0; k < 2; ++k) dst[m][k] = *(const PG8_LAS bf16x8*)(lds + PG8_SA(b, h) + aoff + m * 2048 + k * 1024); } while (0)
; #define PG8_LDB(dst, b, h) do { _Pragma("unroll") for (int n = 0; n < 2; ++n) _Pragma("unroll") for (int k = 0; k < 2; ++k) dst[n][k] = *(const PG8_LAS bf16x8*)(lds + PG8_SB(b, h) + boff + n * 2048 + k * 1024); } while (0)
; #define PG8_MMA(ai, bj, At, Bt) do { __builtin_amdgcn_s_setprio(1); _Pragma("unroll") for (int m = 0; m < 4; ++m) _Pragma("unroll") for (int n = 0; n < 2; ++n) _Pragma("unroll") for (int k = 0; k < 2; ++k) \
;         acc[ai][bj][m][n] = __builtin_amdgcn_mfma_f32_16x16x32_bf16(Bt[n][k], At[m][k], acc[ai][bj][m][n], 0, 0, 0); __builtin_amdgcn_s_setprio(0); } while (0)
; #define PG8_WAIT_V(n) asm volatile("s_waitcnt vmcnt(" #n ")" ::: "memory")
; #define PG8_WAIT_L(n) asm volatile("s_waitcnt lgkmcnt(" #n ")" ::: "memory")
; #define PG8_BAR __builtin_amdgcn_s_barrier()
; #define PG8_SCHED __builtin_amdgcn_sched_barrier(0)
; template <class Epi, class Sched, bool ALIGN_EPI = false, bool SP2 = false>
; __device__ __forceinline__ void gemm_phase(PG8_LAS unsigned char* lds, const Gemm g, const Sched& S, const Epi& E) {
;     ...
;             PG8_LDB(B0, 0, 0); PG8_LDB(B1, 0, 1); PG8_SCHED; PG8_LDA(At, 0, 0); PG8_STAGE(PG8_SA(1, 1), a1 + hstep, voffA);
;             PG8_WAIT_V(8); PG8_WAIT_L(0); PG8_BAR; PG8_MMA(0, 0, At, B0); PG8_MMA(0, 1, At, B1); PG8_BAR; PG8_SCHED;
;             PG8_LDA(At, 0, 1); PG8_STAGE(PG8_SB(0, 0), b2, voffB); PG8_STAGE(PG8_SB(0, 1), b2 + hstep, voffB); PG8_STAGE(PG8_SA(0, 0), a2, voffA);
;             PG8_WAIT_V(8); PG8_WAIT_L(0); PG8_BAR; PG8_MMA(1, 0, At, B0); PG8_MMA(1, 1, At, B1); PG8_BAR; PG8_SCHED;
.LBB0_582:
	ds_read_b128 v[128:131], v168
	ds_read_b128 v[132:135], v168 offset:1024
	ds_read_b128 v[136:139], v168 offset:2048
	ds_read_b128 v[140:143], v168 offset:3072
	ds_read_b128 v[158:161], v169
	ds_read_b128 v[162:165], v169 offset:1024
	ds_read_b128 v[172:175], v169 offset:2048
	ds_read_b128 v[176:179], v169 offset:3072
	s_add_u32 s58, s84, 0xfffc0080
	s_addc_u32 s59, s85, -1
	s_cmp_eq_u32 s91, 12
	s_cselect_b32 s89, s56, s59
	s_cselect_b32 s88, s57, s58
	s_cselect_b32 s87, s71, s90
	s_cselect_b32 s86, s73, s81
	v_lshl_add_u64 v[218:219], s[84:85], 0, v[154:155]
	s_mov_b32 m0, s2
	s_nop 0
	global_load_lds_dwordx4 v[232:233], off
	s_mov_b32 m0, s3
	s_nop 0
	global_load_lds_dwordx4 v[234:235], off
	s_add_i32 m0, s29, 0xc000
	ds_read_b128 v[180:183], v170
	ds_read_b128 v[184:187], v170 offset:1024
	ds_read_b128 v[188:191], v170 offset:2048
	ds_read_b128 v[192:195], v170 offset:3072
	ds_read_b128 v[196:199], v170 offset:4096
	ds_read_b128 v[206:209], v170 offset:5120
	ds_read_b128 v[210:213], v170 offset:6144
	ds_read_b128 v[214:217], v170 offset:7168
	global_load_lds_dwordx4 v[218:219], off
	v_lshl_add_u64 v[218:219], s[84:85], 0, v[156:157]
	s_add_i32 m0, s29, 0xe000
	s_nop 0
	global_load_lds_dwordx4 v[218:219], off
	s_waitcnt vmcnt(8)
	s_waitcnt lgkmcnt(0)
	s_barrier
	s_setprio 1
	s_waitcnt lgkmcnt(0)
	v_mfma_f32_16x16x32_bf16 v[124:127], v[128:131], v[180:183], v[124:127]
	v_mfma_f32_16x16x32_bf16 v[120:123], v[136:139], v[180:183], v[120:123]
	v_mfma_f32_16x16x32_bf16 v[108:111], v[128:131], v[188:191], v[108:111]
	v_mfma_f32_16x16x32_bf16 v[104:107], v[136:139], v[188:191], v[104:107]
	v_mfma_f32_16x16x32_bf16 v[96:99], v[128:131], v[196:199], v[96:99]
	v_mfma_f32_16x16x32_bf16 v[88:91], v[136:139], v[196:199], v[88:91]
	v_mfma_f32_16x16x32_bf16 v[80:83], v[128:131], v[210:213], v[80:83]
	v_mfma_f32_16x16x32_bf16 v[72:75], v[136:139], v[210:213], v[72:75]
	v_mfma_f32_16x16x32_bf16 v[124:127], v[132:135], v[184:187], v[124:127]
	v_mfma_f32_16x16x32_bf16 v[120:123], v[140:143], v[184:187], v[120:123]
	v_mfma_f32_16x16x32_bf16 v[108:111], v[132:135], v[192:195], v[108:111]
	v_mfma_f32_16x16x32_bf16 v[104:107], v[140:143], v[192:195], v[104:107]
	v_mfma_f32_16x16x32_bf16 v[96:99], v[132:135], v[206:209], v[96:99]
	v_mfma_f32_16x16x32_bf16 v[88:91], v[140:143], v[206:209], v[88:91]
	v_mfma_f32_16x16x32_bf16 v[80:83], v[132:135], v[214:217], v[80:83]
	v_mfma_f32_16x16x32_bf16 v[72:75], v[140:143], v[214:217], v[72:75]
	s_setprio 0
	s_setprio 1
	v_mfma_f32_16x16x32_bf16 v[116:119], v[158:161], v[180:183], v[116:119]
	v_mfma_f32_16x16x32_bf16 v[112:115], v[172:175], v[180:183], v[112:115]
	v_mfma_f32_16x16x32_bf16 v[100:103], v[158:161], v[188:191], v[100:103]
	v_mfma_f32_16x16x32_bf16 v[92:95], v[172:175], v[188:191], v[92:95]
	v_mfma_f32_16x16x32_bf16 v[84:87], v[158:161], v[196:199], v[84:87]
	v_mfma_f32_16x16x32_bf16 v[76:79], v[172:175], v[196:199], v[76:79]
	v_mfma_f32_16x16x32_bf16 v[68:71], v[158:161], v[210:213], v[68:71]
	v_mfma_f32_16x16x32_bf16 v[64:67], v[172:175], v[210:213], v[64:67]
	v_mfma_f32_16x16x32_bf16 v[116:119], v[162:165], v[184:187], v[116:119]
	v_mfma_f32_16x16x32_bf16 v[112:115], v[176:179], v[184:187], v[112:115]
	v_mfma_f32_16x16x32_bf16 v[100:103], v[162:165], v[192:195], v[100:103]
	v_mfma_f32_16x16x32_bf16 v[92:95], v[176:179], v[192:195], v[92:95]
	v_mfma_f32_16x16x32_bf16 v[84:87], v[162:165], v[206:209], v[84:87]
	v_mfma_f32_16x16x32_bf16 v[76:79], v[176:179], v[206:209], v[76:79]
	v_mfma_f32_16x16x32_bf16 v[68:71], v[162:165], v[214:217], v[68:71]
	v_mfma_f32_16x16x32_bf16 v[64:67], v[176:179], v[214:217], v[64:67]
	s_setprio 0
	s_barrier
	s_add_i32 s58, s11, s28
	v_lshl_add_u64 v[218:219], s[86:87], 0, v[148:149]
	s_mov_b32 m0, s58
	ds_read_b128 v[180:183], v170 offset:16384
	ds_read_b128 v[184:187], v170 offset:17408
	ds_read_b128 v[188:191], v170 offset:18432
	ds_read_b128 v[192:195], v170 offset:19456
	ds_read_b128 v[196:199], v170 offset:20480
	ds_read_b128 v[206:209], v170 offset:21504
	ds_read_b128 v[210:213], v170 offset:22528
	ds_read_b128 v[214:217], v170 offset:23552
	global_load_lds_dwordx4 v[218:219], off
	s_add_i32 m0, s58, 0x2000
	s_add_u32 s58, s86, 0x40000
	v_lshl_add_u64 v[220:221], s[86:87], 0, v[152:153]
	s_addc_u32 s59, s87, 0
	s_add_i32 s60, s83, s28
	global_load_lds_dwordx4 v[220:221], off
	v_lshl_add_u64 v[222:223], s[58:59], 0, v[148:149]
	s_mov_b32 m0, s60
	v_lshl_add_u64 v[224:225], s[88:89], 0, v[150:151]
	global_load_lds_dwordx4 v[222:223], off
	v_lshl_add_u64 v[222:223], s[58:59], 0, v[152:153]
	s_add_i32 m0, s60, 0x2000
	s_nop 0
	global_load_lds_dwordx4 v[222:223], off
	v_lshl_add_u64 v[222:223], s[88:89], 0, v[146:147]
	v_mov_b32_e32 v236, v222
	v_mov_b32_e32 v237, v223
	v_mov_b32_e32 v238, v224
	v_mov_b32_e32 v239, v225
	s_waitcnt vmcnt(6)
	s_waitcnt lgkmcnt(0)
	s_barrier
; #define PG8_STAGE(bufoff, gbase, voff) do { _Pragma("unroll") for (int _i = 0; _i < 2; ++_i) \
;         __builtin_amdgcn_global_load_lds((const unsigned*)((const char*)(gbase) + (voff)[_i]), (PG8_LAS unsigned*)(lds + (bufoff) + ldsw + _i * 8192), 16, 0, 0); } while (0)
; #define PG8_LDA(dst, b, h) do { _Pragma("unroll") for (int m = 0; m < 4; ++m) _Pragma("unroll") for (int k = 0; k < 2; ++k) dst[m][k] = *(const PG8_LAS bf16x8*)(lds + PG8_SA(b, h) + aoff + m * 2048 + k * 1024); } while (0)
; #define PG8_LDB(dst, b, h) do { _Pragma("unroll") for (int n = 0; n < 2; ++n) _Pragma("unroll") for (int k = 0; k < 2; ++k) dst[n][k] = *(const PG8_LAS bf16x8*)(lds + PG8_SB(b, h) + boff + n * 2048 + k * 1024); } while (0)
; #define PG8_MMA(ai, bj, At, Bt) do { __builtin_amdgcn_s_setprio(1); _Pragma("unroll") for (int m = 0; m < 4; ++m) _Pragma("unroll") for (int n = 0; n < 2; ++n) _Pragma("unroll") for (int k = 0; k < 2; ++k) \
;         acc[ai][bj][m][n] = __builtin_amdgcn_mfma_f32_16x16x32_bf16(Bt[n][k], At[m][k], acc[ai][bj][m][n], 0, 0, 0); __builtin_amdgcn_s_setprio(0); } while (0)
; #define PG8_WAIT_V(n) asm volatile("s_waitcnt vmcnt(" #n ")" ::: "memory")
; #define PG8_WAIT_L(n) asm volatile("s_waitcnt lgkmcnt(" #n ")" ::: "memory")
; #define PG8_BAR __builtin_amdgcn_s_barrier()
; #define PG8_SCHED __builtin_amdgcn_sched_barrier(0)
; template <class Epi, class Sched, bool ALIGN_EPI = false, bool SP2 = false>
; __device__ __forceinline__ void gemm_phase(PG8_LAS unsigned char* lds, const Gemm g, const Sched& S, const Epi& E) {
;     ...
;             PG8_WAIT_V(8); PG8_WAIT_L(0); PG8_BAR; PG8_MMA(1, 0, At, B0); PG8_MMA(1, 1, At, B1); PG8_BAR; PG8_SCHED;
;             PG8_LDB(B0, 1, 0); PG8_LDB(B1, 1, 1); PG8_SCHED; PG8_LDA(At, 1, 0); PG8_STAGE(PG8_SA(0, 1), a2 + hstep, voffA);
;             PG8_WAIT_V(8); PG8_WAIT_L(0); PG8_BAR; PG8_MMA(0, 0, At, B0); PG8_MMA(0, 1, At, B1); PG8_BAR; PG8_SCHED;
	s_setprio 1
	s_waitcnt lgkmcnt(0)
	v_mfma_f32_16x16x32_bf16 v[60:63], v[128:131], v[180:183], v[60:63]
	v_mfma_f32_16x16x32_bf16 v[56:59], v[136:139], v[180:183], v[56:59]
	v_mfma_f32_16x16x32_bf16 v[48:51], v[128:131], v[188:191], v[48:51]
	v_mfma_f32_16x16x32_bf16 v[40:43], v[136:139], v[188:191], v[40:43]
	v_mfma_f32_16x16x32_bf16 v[32:35], v[128:131], v[196:199], v[32:35]
	v_mfma_f32_16x16x32_bf16 v[24:27], v[136:139], v[196:199], v[24:27]
	v_mfma_f32_16x16x32_bf16 v[16:19], v[128:131], v[210:213], v[16:19]
	v_mfma_f32_16x16x32_bf16 v[8:11], v[136:139], v[210:213], v[8:11]
	v_mfma_f32_16x16x32_bf16 v[60:63], v[132:135], v[184:187], v[60:63]
	v_mfma_f32_16x16x32_bf16 v[56:59], v[140:143], v[184:187], v[56:59]
	v_mfma_f32_16x16x32_bf16 v[48:51], v[132:135], v[192:195], v[48:51]
	v_mfma_f32_16x16x32_bf16 v[40:43], v[140:143], v[192:195], v[40:43]
	v_mfma_f32_16x16x32_bf16 v[32:35], v[132:135], v[206:209], v[32:35]
	v_mfma_f32_16x16x32_bf16 v[24:27], v[140:143], v[206:209], v[24:27]
	v_mfma_f32_16x16x32_bf16 v[16:19], v[132:135], v[214:217], v[16:19]
	v_mfma_f32_16x16x32_bf16 v[8:11], v[140:143], v[214:217], v[8:11]
	s_setprio 0
	s_setprio 1
	v_mfma_f32_16x16x32_bf16 v[52:55], v[158:161], v[180:183], v[52:55]
	v_mfma_f32_16x16x32_bf16 v[44:47], v[172:175], v[180:183], v[44:47]
	v_mfma_f32_16x16x32_bf16 v[36:39], v[158:161], v[188:191], v[36:39]
	v_mfma_f32_16x16x32_bf16 v[28:31], v[172:175], v[188:191], v[28:31]
	v_mfma_f32_16x16x32_bf16 v[20:23], v[158:161], v[196:199], v[20:23]
	v_mfma_f32_16x16x32_bf16 v[12:15], v[172:175], v[196:199], v[12:15]
	v_mfma_f32_16x16x32_bf16 v[4:7], v[158:161], v[210:213], v[4:7]
	v_mfma_f32_16x16x32_bf16 v[0:3], v[172:175], v[210:213], v[0:3]
	v_mfma_f32_16x16x32_bf16 v[52:55], v[162:165], v[184:187], v[52:55]
	v_mfma_f32_16x16x32_bf16 v[44:47], v[176:179], v[184:187], v[44:47]
	v_mfma_f32_16x16x32_bf16 v[36:39], v[162:165], v[192:195], v[36:39]
	v_mfma_f32_16x16x32_bf16 v[28:31], v[176:179], v[192:195], v[28:31]
	v_mfma_f32_16x16x32_bf16 v[20:23], v[162:165], v[206:209], v[20:23]
	v_mfma_f32_16x16x32_bf16 v[12:15], v[176:179], v[206:209], v[12:15]
	v_mfma_f32_16x16x32_bf16 v[4:7], v[162:165], v[214:217], v[4:7]
	v_mfma_f32_16x16x32_bf16 v[0:3], v[176:179], v[214:217], v[0:3]
	s_setprio 0
	s_barrier
	s_add_i32 s60, 0, 0x18000
	s_add_i32 s61, 0, 0x1c000
	v_add_u32_e32 v140, s60, v166
	v_add_u32_e32 v176, s61, v166
	ds_read_b128 v[128:131], v140
	ds_read_b128 v[132:135], v140 offset:1024
	ds_read_b128 v[136:139], v140 offset:2048
	ds_read_b128 v[140:143], v140 offset:3072
	ds_read_b128 v[158:161], v176
	ds_read_b128 v[162:165], v176 offset:1024
	ds_read_b128 v[172:175], v176 offset:2048
	ds_read_b128 v[176:179], v176 offset:3072
	s_add_u32 s58, s88, 0x40000
	s_addc_u32 s59, s89, 0
	s_mov_b32 m0, s29
	s_nop 0
	global_load_lds_dwordx4 v[236:237], off
	s_mov_b32 m0, s30
	s_nop 0
	global_load_lds_dwordx4 v[238:239], off
	s_mov_b32 m0, s31
	v_lshl_add_u64 v[226:227], s[58:59], 0, v[146:147]
	ds_read_b128 v[180:183], v170 offset:32768
	ds_read_b128 v[184:187], v170 offset:33792
	ds_read_b128 v[188:191], v170 offset:34816
	ds_read_b128 v[192:195], v170 offset:35840
	ds_read_b128 v[196:199], v170 offset:36864
	ds_read_b128 v[206:209], v170 offset:37888
	ds_read_b128 v[210:213], v170 offset:38912
	ds_read_b128 v[214:217], v170 offset:39936
	global_load_lds_dwordx4 v[226:227], off
	v_lshl_add_u64 v[226:227], s[58:59], 0, v[150:151]
	s_mov_b32 m0, s37
	s_nop 0
	global_load_lds_dwordx4 v[226:227], off
	s_waitcnt vmcnt(8)
	s_waitcnt lgkmcnt(0)
	s_barrier
	s_setprio 1
	s_waitcnt lgkmcnt(0)
	v_mfma_f32_16x16x32_bf16 v[124:127], v[128:131], v[180:183], v[124:127]
	v_mfma_f32_16x16x32_bf16 v[120:123], v[136:139], v[180:183], v[120:123]
	v_mfma_f32_16x16x32_bf16 v[108:111], v[128:131], v[188:191], v[108:111]
	v_mfma_f32_16x16x32_bf16 v[104:107], v[136:139], v[188:191], v[104:107]
	v_mfma_f32_16x16x32_bf16 v[96:99], v[128:131], v[196:199], v[96:99]
	v_mfma_f32_16x16x32_bf16 v[88:91], v[136:139], v[196:199], v[88:91]
	v_mfma_f32_16x16x32_bf16 v[80:83], v[128:131], v[210:213], v[80:83]
	v_mfma_f32_16x16x32_bf16 v[72:75], v[136:139], v[210:213], v[72:75]
	v_mfma_f32_16x16x32_bf16 v[124:127], v[132:135], v[184:187], v[124:127]
	v_mfma_f32_16x16x32_bf16 v[120:123], v[140:143], v[184:187], v[120:123]
	v_mfma_f32_16x16x32_bf16 v[108:111], v[132:135], v[192:195], v[108:111]
	v_mfma_f32_16x16x32_bf16 v[104:107], v[140:143], v[192:195], v[104:107]
	v_mfma_f32_16x16x32_bf16 v[96:99], v[132:135], v[206:209], v[96:99]
	v_mfma_f32_16x16x32_bf16 v[88:91], v[140:143], v[206:209], v[88:91]
	v_mfma_f32_16x16x32_bf16 v[80:83], v[132:135], v[214:217], v[80:83]
	v_mfma_f32_16x16x32_bf16 v[72:75], v[140:143], v[214:217], v[72:75]
	s_setprio 0
	s_setprio 1
	v_mfma_f32_16x16x32_bf16 v[116:119], v[158:161], v[180:183], v[116:119]
	v_mfma_f32_16x16x32_bf16 v[112:115], v[172:175], v[180:183], v[112:115]
	v_mfma_f32_16x16x32_bf16 v[100:103], v[158:161], v[188:191], v[100:103]
	v_mfma_f32_16x16x32_bf16 v[92:95], v[172:175], v[188:191], v[92:95]
	v_mfma_f32_16x16x32_bf16 v[84:87], v[158:161], v[196:199], v[84:87]
	v_mfma_f32_16x16x32_bf16 v[76:79], v[172:175], v[196:199], v[76:79]
	v_mfma_f32_16x16x32_bf16 v[68:71], v[158:161], v[210:213], v[68:71]
	v_mfma_f32_16x16x32_bf16 v[64:67], v[172:175], v[210:213], v[64:67]
	v_mfma_f32_16x16x32_bf16 v[116:119], v[162:165], v[184:187], v[116:119]
	v_mfma_f32_16x16x32_bf16 v[112:115], v[176:179], v[184:187], v[112:115]
	v_mfma_f32_16x16x32_bf16 v[100:103], v[162:165], v[192:195], v[100:103]
	v_mfma_f32_16x16x32_bf16 v[92:95], v[176:179], v[192:195], v[92:95]
	v_mfma_f32_16x16x32_bf16 v[84:87], v[162:165], v[206:209], v[84:87]
	v_mfma_f32_16x16x32_bf16 v[76:79], v[176:179], v[206:209], v[76:79]
	v_mfma_f32_16x16x32_bf16 v[68:71], v[162:165], v[214:217], v[68:71]
	v_mfma_f32_16x16x32_bf16 v[64:67], v[176:179], v[214:217], v[64:67]
	s_setprio 0
	s_barrier
; #define PG8_STAGE(bufoff, gbase, voff) do { _Pragma("unroll") for (int _i = 0; _i < 2; ++_i) \
;         __builtin_amdgcn_global_load_lds((const unsigned*)((const char*)(gbase) + (voff)[_i]), (PG8_LAS unsigned*)(lds + (bufoff) + ldsw + _i * 8192), 16, 0, 0); } while (0)
; #define PG8_LDA(dst, b, h) do { _Pragma("unroll") for (int m = 0; m < 4; ++m) _Pragma("unroll") for (int k = 0; k < 2; ++k) dst[m][k] = *(const PG8_LAS bf16x8*)(lds + PG8_SA(b, h) + aoff + m * 2048 + k * 1024); } while (0)
; #define PG8_MMA(ai, bj, At, Bt) do { __builtin_amdgcn_s_setprio(1); _Pragma("unroll") for (int m = 0; m < 4; ++m) _Pragma("unroll") for (int n = 0; n < 2; ++n) _Pragma("unroll") for (int k = 0; k < 2; ++k) \
;         acc[ai][bj][m][n] = __builtin_amdgcn_mfma_f32_16x16x32_bf16(Bt[n][k], At[m][k], acc[ai][bj][m][n], 0, 0, 0); __builtin_amdgcn_s_setprio(0); } while (0)
; #define PG8_WAIT_V(n) asm volatile("s_waitcnt vmcnt(" #n ")" ::: "memory")
; #define PG8_WAIT_L(n) asm volatile("s_waitcnt lgkmcnt(" #n ")" ::: "memory")
; #define PG8_BAR __builtin_amdgcn_s_barrier()
; #define PG8_SCHED __builtin_amdgcn_sched_barrier(0)
; template <class Epi, class Sched, bool ALIGN_EPI = false, bool SP2 = false>
; __device__ __forceinline__ void gemm_phase(PG8_LAS unsigned char* lds, const Gemm g, const Sched& S, const Epi& E) {
;     ...
;         for (int t = 0; t < nt; t += 2) {
;             const bool last = (t == nt - 2);
;             const char* a1 = cA + (size_t)(t + 1) * kstep;
;             const char* a2 = last ? nA : cA + (size_t)(t + 2) * kstep; const char* b2 = last ? nB : cB + (size_t)(t + 2) * kstep;
;     ...
;             PG8_LDA(At, 1, 1); PG8_STAGE(PG8_SB(1, 0), b3, voffB); PG8_STAGE(PG8_SB(1, 1), b3 + hstep, voffB); PG8_STAGE(PG8_SA(1, 0), a3, voffA);
;             PG8_WAIT_V(8); PG8_WAIT_L(0); PG8_BAR; PG8_MMA(1, 0, At, B0); PG8_MMA(1, 1, At, B1); PG8_BAR; PG8_SCHED;
;     ...
;         if constexpr (ALIGN_EPI) { if (wr == 0) PG8_BAR; }
	s_add_i32 s58, s60, s28
	v_lshl_add_u64 v[218:219], v[218:219], 0, s[66:67]
	s_mov_b32 m0, s58
	ds_read_b128 v[180:183], v170 offset:49152
	ds_read_b128 v[184:187], v170 offset:50176
	ds_read_b128 v[188:191], v170 offset:51200
	ds_read_b128 v[192:195], v170 offset:52224
	ds_read_b128 v[196:199], v170 offset:53248
	ds_read_b128 v[206:209], v170 offset:54272
	ds_read_b128 v[210:213], v170 offset:55296
	ds_read_b128 v[214:217], v170 offset:56320
	global_load_lds_dwordx4 v[218:219], off
	s_add_i32 m0, s58, 0x2000
	s_add_u32 s58, s86, 0x40080
	v_lshl_add_u64 v[218:219], v[220:221], 0, s[66:67]
	s_addc_u32 s59, s87, 0
	s_add_i32 s60, s61, s28
	global_load_lds_dwordx4 v[218:219], off
	v_lshl_add_u64 v[218:219], s[58:59], 0, v[148:149]
	s_mov_b32 m0, s60
	s_nop 0
	global_load_lds_dwordx4 v[218:219], off
	v_lshl_add_u64 v[218:219], s[58:59], 0, v[152:153]
	s_add_i32 m0, s60, 0x2000
	s_nop 0
	global_load_lds_dwordx4 v[218:219], off
	v_lshl_add_u64 v[218:219], v[222:223], 0, s[66:67]
	v_mov_b32_e32 v232, v218
	v_mov_b32_e32 v233, v219
	v_lshl_add_u64 v[218:219], v[224:225], 0, s[66:67]
	v_mov_b32_e32 v234, v218
	v_mov_b32_e32 v235, v219
	s_waitcnt vmcnt(6)
	s_waitcnt lgkmcnt(0)
	s_barrier
	s_setprio 1
	s_waitcnt lgkmcnt(0)
	v_mfma_f32_16x16x32_bf16 v[60:63], v[128:131], v[180:183], v[60:63]
	v_mfma_f32_16x16x32_bf16 v[56:59], v[136:139], v[180:183], v[56:59]
	v_mfma_f32_16x16x32_bf16 v[48:51], v[128:131], v[188:191], v[48:51]
	v_mfma_f32_16x16x32_bf16 v[40:43], v[136:139], v[188:191], v[40:43]
	v_mfma_f32_16x16x32_bf16 v[32:35], v[128:131], v[196:199], v[32:35]
	v_mfma_f32_16x16x32_bf16 v[24:27], v[136:139], v[196:199], v[24:27]
	v_mfma_f32_16x16x32_bf16 v[16:19], v[128:131], v[210:213], v[16:19]
	v_mfma_f32_16x16x32_bf16 v[8:11], v[136:139], v[210:213], v[8:11]
	v_mfma_f32_16x16x32_bf16 v[60:63], v[132:135], v[184:187], v[60:63]
	v_mfma_f32_16x16x32_bf16 v[56:59], v[140:143], v[184:187], v[56:59]
	v_mfma_f32_16x16x32_bf16 v[48:51], v[132:135], v[192:195], v[48:51]
	v_mfma_f32_16x16x32_bf16 v[40:43], v[140:143], v[192:195], v[40:43]
	v_mfma_f32_16x16x32_bf16 v[32:35], v[132:135], v[206:209], v[32:35]
	v_mfma_f32_16x16x32_bf16 v[24:27], v[140:143], v[206:209], v[24:27]
	v_mfma_f32_16x16x32_bf16 v[16:19], v[132:135], v[214:217], v[16:19]
	v_mfma_f32_16x16x32_bf16 v[8:11], v[140:143], v[214:217], v[8:11]
	s_setprio 0
	s_setprio 1
	v_mfma_f32_16x16x32_bf16 v[52:55], v[158:161], v[180:183], v[52:55]
	v_mfma_f32_16x16x32_bf16 v[44:47], v[172:175], v[180:183], v[44:47]
	v_mfma_f32_16x16x32_bf16 v[36:39], v[158:161], v[188:191], v[36:39]
	v_mfma_f32_16x16x32_bf16 v[28:31], v[172:175], v[188:191], v[28:31]
	v_mfma_f32_16x16x32_bf16 v[20:23], v[158:161], v[196:199], v[20:23]
	v_mfma_f32_16x16x32_bf16 v[12:15], v[172:175], v[196:199], v[12:15]
	v_mfma_f32_16x16x32_bf16 v[4:7], v[158:161], v[210:213], v[4:7]
	v_mfma_f32_16x16x32_bf16 v[0:3], v[172:175], v[210:213], v[0:3]
	v_mfma_f32_16x16x32_bf16 v[52:55], v[162:165], v[184:187], v[52:55]
	v_mfma_f32_16x16x32_bf16 v[44:47], v[176:179], v[184:187], v[44:47]
	v_mfma_f32_16x16x32_bf16 v[36:39], v[162:165], v[192:195], v[36:39]
	v_mfma_f32_16x16x32_bf16 v[28:31], v[176:179], v[192:195], v[28:31]
	v_mfma_f32_16x16x32_bf16 v[20:23], v[162:165], v[206:209], v[20:23]
	v_mfma_f32_16x16x32_bf16 v[12:15], v[176:179], v[206:209], v[12:15]
	v_mfma_f32_16x16x32_bf16 v[4:7], v[162:165], v[214:217], v[4:7]
	v_mfma_f32_16x16x32_bf16 v[0:3], v[176:179], v[214:217], v[0:3]
	s_setprio 0
	s_barrier
	s_add_i32 s91, s91, 2
	s_add_u32 s84, s84, 0x100
	s_addc_u32 s85, s85, 0
	s_add_u32 s81, s81, 0x100
	s_addc_u32 s90, s90, 0
	s_cmp_gt_u32 s91, 13
	s_cbranch_scc0 .LBB0_582
	s_and_b64 vcc, exec, s[68:69]
	s_cbranch_vccz .LBB0_585
	s_barrier

; #define PG8_STAGE(bufoff, gbase, voff) do { _Pragma("unroll") for (int _i = 0; _i < 2; ++_i) \
;         __builtin_amdgcn_global_load_lds((const unsigned*)((const char*)(gbase) + (voff)[_i]), (PG8_LAS unsigned*)(lds + (bufoff) + ldsw + _i * 8192), 16, 0, 0); } while (0)
; #define PG8_WAIT_V(n) asm volatile("s_waitcnt vmcnt(" #n ")" ::: "memory")
; #define PG8_BAR __builtin_amdgcn_s_barrier()
; template <class Epi, class Sched, bool ALIGN_EPI = false, bool SP2 = false>
; __device__ __forceinline__ void gemm_phase(PG8_LAS unsigned char* lds, const Gemm g, const Sched& S, const Epi& E) {
;     const int tid = threadIdx.x, wid = __builtin_amdgcn_readfirstlane(tid >> 6), lane = tid & 63, wr = wid >> 2, wc = wid & 3, fr = lane & 15, fq = lane >> 4;
;     const int K = g.K, nt = K / BK;
;     unsigned voffA[2], voffB[2];
; #pragma unroll
;     for (int i = 0; i < 2; ++i) { int R, C; stage_rc(tid * 16 + i * 8192, R, C); const int Rb = Epi::PERM ? ((R & ~31) + perm32(R & 31)) : R;
;         voffA[i] = (unsigned)(R * K + C) * 2u; voffB[i] = (unsigned)(Rb * K + C) * 2u; }
;     const size_t kstep = (size_t)(BK * 2);
;     const size_t hstep = (size_t)HALF * K * 2;
;     const size_t tstep = 2 * hstep;
;     const unsigned ldsw = (unsigned)wid * 1024u;
;     const int aoff = lds_byte(wr * 64 + fr, fq * 8), boff = lds_byte(wc * 32 + fr, fq * 8);
;     ...
;         PG8_STAGE(PG8_SB(0, 0), cB, voffB); PG8_STAGE(PG8_SB(0, 1), cB + hstep, voffB); PG8_STAGE(PG8_SA(0, 0), cA, voffA); PG8_STAGE(PG8_SA(0, 1), cA + hstep, voffA);
;         if (wr == 1) PG8_BAR;
;         PG8_WAIT_V(2); PG8_BAR;
;         PG8_STAGE(PG8_SB(1, 0), cB + kstep, voffB); PG8_STAGE(PG8_SA(1, 0), cA + kstep, voffA); PG8_STAGE(PG8_SB(1, 1), cB + hstep + kstep, voffB);
;         PG8_WAIT_V(6); PG8_BAR;
.LBB0_654:
	s_add_u32 s64, s26, 0x80000
	s_addc_u32 s65, s27, 0
	s_lshl_b32 s31, s31, 5
	s_mov_b64 s[66:67], 0x80
	s_and_b32 s57, s31, 0x60
	s_add_i32 m0, s20, 0x18000
	v_lshl_add_u64 v[6:7], v[6:7], 0, s[66:67]
	s_lshl_b32 s5, s56, 13
	s_lshl_b32 s60, s57, 7
	s_waitcnt vmcnt(2)
	s_barrier
	global_load_lds_dwordx4 v[6:7], off
	v_lshl_add_u64 v[4:5], v[4:5], 0, s[66:67]
	s_add_i32 m0, s20, 0x1a000
	s_add_i32 s31, s20, 0x8000
	s_add_i32 s37, s20, 0xa000
	global_load_lds_dwordx4 v[4:5], off
	v_lshl_add_u64 v[0:1], v[0:1], 0, s[66:67]
	s_mov_b32 m0, s31
	s_add_u32 s58, s82, 0x40080
	global_load_lds_dwordx4 v[0:1], off
	v_mov_b32_e32 v232, v0
	v_mov_b32_e32 v233, v1
	v_lshl_add_u64 v[0:1], v[2:3], 0, s[66:67]
	s_mov_b32 m0, s37
	s_addc_u32 s59, s83, 0
	global_load_lds_dwordx4 v[0:1], off
	v_mov_b32_e32 v234, v0
	v_mov_b32_e32 v235, v1
	s_add_i32 m0, s20, 0x1c000
	v_lshl_add_u64 v[0:1], s[58:59], 0, v[132:133]
	global_load_lds_dwordx4 v[0:1], off
	v_lshl_add_u64 v[0:1], s[58:59], 0, v[128:129]
	s_add_i32 m0, s20, 0x1e000
	v_lshlrev_b32_e32 v2, 2, v201
	global_load_lds_dwordx4 v[0:1], off
	v_and_b32_e32 v0, 15, v201
	v_lshlrev_b32_e32 v1, 1, v11
	v_lshl_or_b32 v145, s56, 6, v0
	v_lshl_or_b32 v0, v0, 6, v1
	v_and_b32_e32 v2, 32, v2
	v_bitop3_b32 v0, v0, s5, v2 bitop3:0xde
	v_lshlrev_b32_e32 v3, 6, v201
	s_movk_i32 s5, 0x3c0
	v_and_or_b32 v1, v3, s5, v1
	v_bitop3_b32 v188, s60, v1, v2 bitop3:0xf6
	v_lshlrev_b32_e32 v1, 8, v201
	v_and_b32_e32 v1, 0x38000, v1
	v_lshlrev_b32_e32 v2, 11, v12
	v_or3_b32 v1, v9, v1, v2
	v_add_u32_e32 v136, v1, v10
	v_lshlrev_b32_e32 v1, 4, v8
	s_waitcnt vmcnt(6)
	s_cmpk_lt_u32 s39, 0x100
	v_and_b32_e32 v1, 0x78000, v1
	s_sext_i32_i8 s86, s68
	s_cselect_b64 s[68:69], -1, 0
	v_or3_b32 v1, v9, v1, v2
	s_add_i32 s39, 0, 0x10000
	s_add_i32 s56, 0, 0x14000
	v_or_b32_e32 v189, s57, v11
	v_mov_b32_e32 v137, v133
	v_add_u32_e32 v138, v1, v10
	v_mov_b32_e32 v139, v133
	v_add_u32_e32 v190, s39, v188
	v_add_u32_e32 v191, s56, v188
	v_add_u32_e32 v192, 0, v0
	v_mov_b32_e32 v193, 0x358637bd
	s_movk_i32 s57, 0x1600
	s_barrier
	s_branch .LBB0_657

; #define PG8_STAGE(bufoff, gbase, voff) do { _Pragma("unroll") for (int _i = 0; _i < 2; ++_i) \
;         __builtin_amdgcn_global_load_lds((const unsigned*)((const char*)(gbase) + (voff)[_i]), (PG8_LAS unsigned*)(lds + (bufoff) + ldsw + _i * 8192), 16, 0, 0); } while (0)
; #define PG8_LDA(dst, b, h) do { _Pragma("unroll") for (int m = 0; m < 4; ++m) _Pragma("unroll") for (int k = 0; k < 2; ++k) dst[m][k] = *(const PG8_LAS bf16x8*)(lds + PG8_SA(b, h) + aoff + m * 2048 + k * 1024); } while (0)
; #define PG8_LDB(dst, b, h) do { _Pragma("unroll") for (int n = 0; n < 2; ++n) _Pragma("unroll") for (int k = 0; k < 2; ++k) dst[n][k] = *(const PG8_LAS bf16x8*)(lds + PG8_SB(b, h) + boff + n * 2048 + k * 1024); } while (0)
; #define PG8_MMA(ai, bj, At, Bt) do { __builtin_amdgcn_s_setprio(1); _Pragma("unroll") for (int m = 0; m < 4; ++m) _Pragma("unroll") for (int n = 0; n < 2; ++n) _Pragma("unroll") for (int k = 0; k < 2; ++k) \
;         acc[ai][bj][m][n] = __builtin_amdgcn_mfma_f32_16x16x32_bf16(Bt[n][k], At[m][k], acc[ai][bj][m][n], 0, 0, 0); __builtin_amdgcn_s_setprio(0); } while (0)
; #define PG8_WAIT_V(n) asm volatile("s_waitcnt vmcnt(" #n ")" ::: "memory")
; #define PG8_WAIT_L(n) asm volatile("s_waitcnt lgkmcnt(" #n ")" ::: "memory")
; #define PG8_BAR __builtin_amdgcn_s_barrier()
; #define PG8_SCHED __builtin_amdgcn_sched_barrier(0)
; template <class Epi, class Sched, bool ALIGN_EPI = false, bool SP2 = false>
; __device__ __forceinline__ void gemm_phase(PG8_LAS unsigned char* lds, const Gemm g, const Sched& S, const Epi& E) {
;     ...
;             PG8_LDB(B0, 0, 0); PG8_LDB(B1, 0, 1); PG8_SCHED; PG8_LDA(At, 0, 0); PG8_STAGE(PG8_SA(1, 1), a1 + hstep, voffA);
;             PG8_WAIT_V(8); PG8_WAIT_L(0); PG8_BAR; PG8_MMA(0, 0, At, B0); PG8_MMA(0, 1, At, B1); PG8_BAR; PG8_SCHED;
;             PG8_LDA(At, 0, 1); PG8_STAGE(PG8_SB(0, 0), b2, voffB); PG8_STAGE(PG8_SB(0, 1), b2 + hstep, voffB); PG8_STAGE(PG8_SA(0, 0), a2, voffA);
;             PG8_WAIT_V(8); PG8_WAIT_L(0); PG8_BAR; PG8_MMA(1, 0, At, B0); PG8_MMA(1, 1, At, B1); PG8_BAR; PG8_SCHED;
.LBB0_660:
	ds_read_b128 v[140:143], v190
	ds_read_b128 v[146:149], v190 offset:1024
	ds_read_b128 v[150:153], v190 offset:2048
	ds_read_b128 v[154:157], v190 offset:3072
	ds_read_b128 v[158:161], v191
	ds_read_b128 v[162:165], v191 offset:1024
	ds_read_b128 v[166:169], v191 offset:2048
	ds_read_b128 v[170:173], v191 offset:3072
	s_add_u32 s58, s80, 0xfffc0080
	s_addc_u32 s59, s81, -1
	s_cmp_eq_u32 s90, 12
	s_cselect_b32 s85, s5, s59
	s_cselect_b32 s84, s71, s58
	s_cselect_b32 s83, s73, s89
	s_cselect_b32 s82, s87, s88
	v_lshl_add_u64 v[186:187], s[80:81], 0, v[136:137]
	s_mov_b32 m0, s31
	s_nop 0
	global_load_lds_dwordx4 v[232:233], off
	s_mov_b32 m0, s37
	s_nop 0
	global_load_lds_dwordx4 v[234:235], off
	s_add_i32 m0, s20, 0xc000
	ds_read_b128 v[174:177], v192
	ds_read_b128 v[178:181], v192 offset:1024
	ds_read_b128 v[182:185], v192 offset:2048
	ds_read_b128 v[194:197], v192 offset:3072
	ds_read_b128 v[206:209], v192 offset:4096
	ds_read_b128 v[210:213], v192 offset:5120
	ds_read_b128 v[214:217], v192 offset:6144
	ds_read_b128 v[218:221], v192 offset:7168
	global_load_lds_dwordx4 v[186:187], off
	v_lshl_add_u64 v[186:187], s[80:81], 0, v[138:139]
	s_add_i32 m0, s20, 0xe000
	s_nop 0
	global_load_lds_dwordx4 v[186:187], off
	s_waitcnt vmcnt(8)
	s_waitcnt lgkmcnt(0)
	s_barrier
	s_setprio 1
	s_waitcnt lgkmcnt(0)
	v_mfma_f32_16x16x32_bf16 v[124:127], v[140:143], v[174:177], v[124:127]
	v_mfma_f32_16x16x32_bf16 v[120:123], v[150:153], v[174:177], v[120:123]
	v_mfma_f32_16x16x32_bf16 v[108:111], v[140:143], v[182:185], v[108:111]
	v_mfma_f32_16x16x32_bf16 v[104:107], v[150:153], v[182:185], v[104:107]
	v_mfma_f32_16x16x32_bf16 v[92:95], v[140:143], v[206:209], v[92:95]
	v_mfma_f32_16x16x32_bf16 v[88:91], v[150:153], v[206:209], v[88:91]
	v_mfma_f32_16x16x32_bf16 v[76:79], v[140:143], v[214:217], v[76:79]
	v_mfma_f32_16x16x32_bf16 v[72:75], v[150:153], v[214:217], v[72:75]
	v_mfma_f32_16x16x32_bf16 v[124:127], v[146:149], v[178:181], v[124:127]
	v_mfma_f32_16x16x32_bf16 v[120:123], v[154:157], v[178:181], v[120:123]
	v_mfma_f32_16x16x32_bf16 v[108:111], v[146:149], v[194:197], v[108:111]
	v_mfma_f32_16x16x32_bf16 v[104:107], v[154:157], v[194:197], v[104:107]
	v_mfma_f32_16x16x32_bf16 v[92:95], v[146:149], v[210:213], v[92:95]
	v_mfma_f32_16x16x32_bf16 v[88:91], v[154:157], v[210:213], v[88:91]
	v_mfma_f32_16x16x32_bf16 v[76:79], v[146:149], v[218:221], v[76:79]
	v_mfma_f32_16x16x32_bf16 v[72:75], v[154:157], v[218:221], v[72:75]
	s_setprio 0
	s_setprio 1
	v_mfma_f32_16x16x32_bf16 v[116:119], v[158:161], v[174:177], v[116:119]
	v_mfma_f32_16x16x32_bf16 v[112:115], v[166:169], v[174:177], v[112:115]
	v_mfma_f32_16x16x32_bf16 v[100:103], v[158:161], v[182:185], v[100:103]
	v_mfma_f32_16x16x32_bf16 v[96:99], v[166:169], v[182:185], v[96:99]
	v_mfma_f32_16x16x32_bf16 v[84:87], v[158:161], v[206:209], v[84:87]
	v_mfma_f32_16x16x32_bf16 v[80:83], v[166:169], v[206:209], v[80:83]
	v_mfma_f32_16x16x32_bf16 v[68:71], v[158:161], v[214:217], v[68:71]
	v_mfma_f32_16x16x32_bf16 v[64:67], v[166:169], v[214:217], v[64:67]
	v_mfma_f32_16x16x32_bf16 v[116:119], v[162:165], v[178:181], v[116:119]
	v_mfma_f32_16x16x32_bf16 v[112:115], v[170:173], v[178:181], v[112:115]
	v_mfma_f32_16x16x32_bf16 v[100:103], v[162:165], v[194:197], v[100:103]
	v_mfma_f32_16x16x32_bf16 v[96:99], v[170:173], v[194:197], v[96:99]
	v_mfma_f32_16x16x32_bf16 v[84:87], v[162:165], v[210:213], v[84:87]
	v_mfma_f32_16x16x32_bf16 v[80:83], v[170:173], v[210:213], v[80:83]
	v_mfma_f32_16x16x32_bf16 v[68:71], v[162:165], v[218:221], v[68:71]
	v_mfma_f32_16x16x32_bf16 v[64:67], v[170:173], v[218:221], v[64:67]
	s_setprio 0
	s_barrier
	s_add_i32 s58, s39, s11
	v_lshl_add_u64 v[186:187], s[82:83], 0, v[132:133]
	s_mov_b32 m0, s58
	ds_read_b128 v[174:177], v192 offset:16384
	ds_read_b128 v[178:181], v192 offset:17408
	ds_read_b128 v[182:185], v192 offset:18432
	ds_read_b128 v[194:197], v192 offset:19456
	ds_read_b128 v[206:209], v192 offset:20480
	ds_read_b128 v[210:213], v192 offset:21504
	ds_read_b128 v[214:217], v192 offset:22528
	ds_read_b128 v[218:221], v192 offset:23552
	global_load_lds_dwordx4 v[186:187], off
	s_add_i32 m0, s58, 0x2000
	s_add_u32 s58, s82, 0x40000
	v_lshl_add_u64 v[198:199], s[82:83], 0, v[128:129]
	s_addc_u32 s59, s83, 0
	s_add_i32 s60, s56, s11
	global_load_lds_dwordx4 v[198:199], off
	v_lshl_add_u64 v[222:223], s[58:59], 0, v[132:133]
	s_mov_b32 m0, s60
	v_lshl_add_u64 v[224:225], s[84:85], 0, v[130:131]
	global_load_lds_dwordx4 v[222:223], off
	v_lshl_add_u64 v[222:223], s[58:59], 0, v[128:129]
	s_add_i32 m0, s60, 0x2000
	s_nop 0
	global_load_lds_dwordx4 v[222:223], off
	v_lshl_add_u64 v[222:223], s[84:85], 0, v[134:135]
	v_mov_b32_e32 v236, v222
	v_mov_b32_e32 v237, v223
	v_mov_b32_e32 v238, v224
	v_mov_b32_e32 v239, v225
	s_waitcnt vmcnt(6)
	s_waitcnt lgkmcnt(0)
	s_barrier
; #define PG8_STAGE(bufoff, gbase, voff) do { _Pragma("unroll") for (int _i = 0; _i < 2; ++_i) \
;         __builtin_amdgcn_global_load_lds((const unsigned*)((const char*)(gbase) + (voff)[_i]), (PG8_LAS unsigned*)(lds + (bufoff) + ldsw + _i * 8192), 16, 0, 0); } while (0)
; #define PG8_LDA(dst, b, h) do { _Pragma("unroll") for (int m = 0; m < 4; ++m) _Pragma("unroll") for (int k = 0; k < 2; ++k) dst[m][k] = *(const PG8_LAS bf16x8*)(lds + PG8_SA(b, h) + aoff + m * 2048 + k * 1024); } while (0)
; #define PG8_LDB(dst, b, h) do { _Pragma("unroll") for (int n = 0; n < 2; ++n) _Pragma("unroll") for (int k = 0; k < 2; ++k) dst[n][k] = *(const PG8_LAS bf16x8*)(lds + PG8_SB(b, h) + boff + n * 2048 + k * 1024); } while (0)
; #define PG8_MMA(ai, bj, At, Bt) do { __builtin_amdgcn_s_setprio(1); _Pragma("unroll") for (int m = 0; m < 4; ++m) _Pragma("unroll") for (int n = 0; n < 2; ++n) _Pragma("unroll") for (int k = 0; k < 2; ++k) \
;         acc[ai][bj][m][n] = __builtin_amdgcn_mfma_f32_16x16x32_bf16(Bt[n][k], At[m][k], acc[ai][bj][m][n], 0, 0, 0); __builtin_amdgcn_s_setprio(0); } while (0)
; #define PG8_WAIT_V(n) asm volatile("s_waitcnt vmcnt(" #n ")" ::: "memory")
; #define PG8_WAIT_L(n) asm volatile("s_waitcnt lgkmcnt(" #n ")" ::: "memory")
; #define PG8_BAR __builtin_amdgcn_s_barrier()
; #define PG8_SCHED __builtin_amdgcn_sched_barrier(0)
; template <class Epi, class Sched, bool ALIGN_EPI = false, bool SP2 = false>
; __device__ __forceinline__ void gemm_phase(PG8_LAS unsigned char* lds, const Gemm g, const Sched& S, const Epi& E) {
;     ...
;             PG8_WAIT_V(8); PG8_WAIT_L(0); PG8_BAR; PG8_MMA(1, 0, At, B0); PG8_MMA(1, 1, At, B1); PG8_BAR; PG8_SCHED;
;             PG8_LDB(B0, 1, 0); PG8_LDB(B1, 1, 1); PG8_SCHED; PG8_LDA(At, 1, 0); PG8_STAGE(PG8_SA(0, 1), a2 + hstep, voffA);
;             PG8_WAIT_V(8); PG8_WAIT_L(0); PG8_BAR; PG8_MMA(0, 0, At, B0); PG8_MMA(0, 1, At, B1); PG8_BAR; PG8_SCHED;
	s_setprio 1
	s_waitcnt lgkmcnt(0)
	v_mfma_f32_16x16x32_bf16 v[60:63], v[140:143], v[174:177], v[60:63]
	v_mfma_f32_16x16x32_bf16 v[56:59], v[150:153], v[174:177], v[56:59]
	v_mfma_f32_16x16x32_bf16 v[44:47], v[140:143], v[182:185], v[44:47]
	v_mfma_f32_16x16x32_bf16 v[40:43], v[150:153], v[182:185], v[40:43]
	v_mfma_f32_16x16x32_bf16 v[28:31], v[140:143], v[206:209], v[28:31]
	v_mfma_f32_16x16x32_bf16 v[24:27], v[150:153], v[206:209], v[24:27]
	v_mfma_f32_16x16x32_bf16 v[12:15], v[140:143], v[214:217], v[12:15]
	v_mfma_f32_16x16x32_bf16 v[8:11], v[150:153], v[214:217], v[8:11]
	v_mfma_f32_16x16x32_bf16 v[60:63], v[146:149], v[178:181], v[60:63]
	v_mfma_f32_16x16x32_bf16 v[56:59], v[154:157], v[178:181], v[56:59]
	v_mfma_f32_16x16x32_bf16 v[44:47], v[146:149], v[194:197], v[44:47]
	v_mfma_f32_16x16x32_bf16 v[40:43], v[154:157], v[194:197], v[40:43]
	v_mfma_f32_16x16x32_bf16 v[28:31], v[146:149], v[210:213], v[28:31]
	v_mfma_f32_16x16x32_bf16 v[24:27], v[154:157], v[210:213], v[24:27]
	v_mfma_f32_16x16x32_bf16 v[12:15], v[146:149], v[218:221], v[12:15]
	v_mfma_f32_16x16x32_bf16 v[8:11], v[154:157], v[218:221], v[8:11]
	s_setprio 0
	s_setprio 1
	v_mfma_f32_16x16x32_bf16 v[52:55], v[158:161], v[174:177], v[52:55]
	v_mfma_f32_16x16x32_bf16 v[48:51], v[166:169], v[174:177], v[48:51]
	v_mfma_f32_16x16x32_bf16 v[36:39], v[158:161], v[182:185], v[36:39]
	v_mfma_f32_16x16x32_bf16 v[32:35], v[166:169], v[182:185], v[32:35]
	v_mfma_f32_16x16x32_bf16 v[20:23], v[158:161], v[206:209], v[20:23]
	v_mfma_f32_16x16x32_bf16 v[16:19], v[166:169], v[206:209], v[16:19]
	v_mfma_f32_16x16x32_bf16 v[4:7], v[158:161], v[214:217], v[4:7]
	v_mfma_f32_16x16x32_bf16 v[0:3], v[166:169], v[214:217], v[0:3]
	v_mfma_f32_16x16x32_bf16 v[52:55], v[162:165], v[178:181], v[52:55]
	v_mfma_f32_16x16x32_bf16 v[48:51], v[170:173], v[178:181], v[48:51]
	v_mfma_f32_16x16x32_bf16 v[36:39], v[162:165], v[194:197], v[36:39]
	v_mfma_f32_16x16x32_bf16 v[32:35], v[170:173], v[194:197], v[32:35]
	v_mfma_f32_16x16x32_bf16 v[20:23], v[162:165], v[210:213], v[20:23]
	v_mfma_f32_16x16x32_bf16 v[16:19], v[170:173], v[210:213], v[16:19]
	v_mfma_f32_16x16x32_bf16 v[4:7], v[162:165], v[218:221], v[4:7]
	v_mfma_f32_16x16x32_bf16 v[0:3], v[170:173], v[218:221], v[0:3]
	s_setprio 0
	s_barrier
	s_add_i32 s60, 0, 0x18000
	s_add_i32 s61, 0, 0x1c000
	v_add_u32_e32 v154, s60, v188
	v_add_u32_e32 v170, s61, v188
	ds_read_b128 v[140:143], v154
	ds_read_b128 v[146:149], v154 offset:1024
	ds_read_b128 v[150:153], v154 offset:2048
	ds_read_b128 v[154:157], v154 offset:3072
	ds_read_b128 v[158:161], v170
	ds_read_b128 v[162:165], v170 offset:1024
	ds_read_b128 v[166:169], v170 offset:2048
	ds_read_b128 v[170:173], v170 offset:3072
	s_add_u32 s58, s84, 0x40000
	s_addc_u32 s59, s85, 0
	s_mov_b32 m0, s20
	s_nop 0
	global_load_lds_dwordx4 v[236:237], off
	s_mov_b32 m0, s21
	s_nop 0
	global_load_lds_dwordx4 v[238:239], off
	s_mov_b32 m0, s28
	v_lshl_add_u64 v[226:227], s[58:59], 0, v[134:135]
	ds_read_b128 v[174:177], v192 offset:32768
	ds_read_b128 v[178:181], v192 offset:33792
	ds_read_b128 v[182:185], v192 offset:34816
	ds_read_b128 v[194:197], v192 offset:35840
	ds_read_b128 v[206:209], v192 offset:36864
	ds_read_b128 v[210:213], v192 offset:37888
	ds_read_b128 v[214:217], v192 offset:38912
	ds_read_b128 v[218:221], v192 offset:39936
	global_load_lds_dwordx4 v[226:227], off
	v_lshl_add_u64 v[226:227], s[58:59], 0, v[130:131]
	s_mov_b32 m0, s29
	s_nop 0
	global_load_lds_dwordx4 v[226:227], off
	s_waitcnt vmcnt(8)
	s_waitcnt lgkmcnt(0)
	s_barrier
	s_setprio 1
	s_waitcnt lgkmcnt(0)
	v_mfma_f32_16x16x32_bf16 v[124:127], v[140:143], v[174:177], v[124:127]
	v_mfma_f32_16x16x32_bf16 v[120:123], v[150:153], v[174:177], v[120:123]
	v_mfma_f32_16x16x32_bf16 v[108:111], v[140:143], v[182:185], v[108:111]
	v_mfma_f32_16x16x32_bf16 v[104:107], v[150:153], v[182:185], v[104:107]
	v_mfma_f32_16x16x32_bf16 v[92:95], v[140:143], v[206:209], v[92:95]
	v_mfma_f32_16x16x32_bf16 v[88:91], v[150:153], v[206:209], v[88:91]
	v_mfma_f32_16x16x32_bf16 v[76:79], v[140:143], v[214:217], v[76:79]
	v_mfma_f32_16x16x32_bf16 v[72:75], v[150:153], v[214:217], v[72:75]
	v_mfma_f32_16x16x32_bf16 v[124:127], v[146:149], v[178:181], v[124:127]
	v_mfma_f32_16x16x32_bf16 v[120:123], v[154:157], v[178:181], v[120:123]
	v_mfma_f32_16x16x32_bf16 v[108:111], v[146:149], v[194:197], v[108:111]
	v_mfma_f32_16x16x32_bf16 v[104:107], v[154:157], v[194:197], v[104:107]
	v_mfma_f32_16x16x32_bf16 v[92:95], v[146:149], v[210:213], v[92:95]
	v_mfma_f32_16x16x32_bf16 v[88:91], v[154:157], v[210:213], v[88:91]
	v_mfma_f32_16x16x32_bf16 v[76:79], v[146:149], v[218:221], v[76:79]
	v_mfma_f32_16x16x32_bf16 v[72:75], v[154:157], v[218:221], v[72:75]
	s_setprio 0
	s_setprio 1
	v_mfma_f32_16x16x32_bf16 v[116:119], v[158:161], v[174:177], v[116:119]
	v_mfma_f32_16x16x32_bf16 v[112:115], v[166:169], v[174:177], v[112:115]
	v_mfma_f32_16x16x32_bf16 v[100:103], v[158:161], v[182:185], v[100:103]
	v_mfma_f32_16x16x32_bf16 v[96:99], v[166:169], v[182:185], v[96:99]
	v_mfma_f32_16x16x32_bf16 v[84:87], v[158:161], v[206:209], v[84:87]
	v_mfma_f32_16x16x32_bf16 v[80:83], v[166:169], v[206:209], v[80:83]
	v_mfma_f32_16x16x32_bf16 v[68:71], v[158:161], v[214:217], v[68:71]
	v_mfma_f32_16x16x32_bf16 v[64:67], v[166:169], v[214:217], v[64:67]
	v_mfma_f32_16x16x32_bf16 v[116:119], v[162:165], v[178:181], v[116:119]
	v_mfma_f32_16x16x32_bf16 v[112:115], v[170:173], v[178:181], v[112:115]
	v_mfma_f32_16x16x32_bf16 v[100:103], v[162:165], v[194:197], v[100:103]
	v_mfma_f32_16x16x32_bf16 v[96:99], v[170:173], v[194:197], v[96:99]
	v_mfma_f32_16x16x32_bf16 v[84:87], v[162:165], v[210:213], v[84:87]
	v_mfma_f32_16x16x32_bf16 v[80:83], v[170:173], v[210:213], v[80:83]
	v_mfma_f32_16x16x32_bf16 v[68:71], v[162:165], v[218:221], v[68:71]
	v_mfma_f32_16x16x32_bf16 v[64:67], v[170:173], v[218:221], v[64:67]
	s_setprio 0
	s_barrier
; #define PG8_STAGE(bufoff, gbase, voff) do { _Pragma("unroll") for (int _i = 0; _i < 2; ++_i) \
;         __builtin_amdgcn_global_load_lds((const unsigned*)((const char*)(gbase) + (voff)[_i]), (PG8_LAS unsigned*)(lds + (bufoff) + ldsw + _i * 8192), 16, 0, 0); } while (0)
; #define PG8_LDA(dst, b, h) do { _Pragma("unroll") for (int m = 0; m < 4; ++m) _Pragma("unroll") for (int k = 0; k < 2; ++k) dst[m][k] = *(const PG8_LAS bf16x8*)(lds + PG8_SA(b, h) + aoff + m * 2048 + k * 1024); } while (0)
; #define PG8_MMA(ai, bj, At, Bt) do { __builtin_amdgcn_s_setprio(1); _Pragma("unroll") for (int m = 0; m < 4; ++m) _Pragma("unroll") for (int n = 0; n < 2; ++n) _Pragma("unroll") for (int k = 0; k < 2; ++k) \
;         acc[ai][bj][m][n] = __builtin_amdgcn_mfma_f32_16x16x32_bf16(Bt[n][k], At[m][k], acc[ai][bj][m][n], 0, 0, 0); __builtin_amdgcn_s_setprio(0); } while (0)
; #define PG8_WAIT_V(n) asm volatile("s_waitcnt vmcnt(" #n ")" ::: "memory")
; #define PG8_WAIT_L(n) asm volatile("s_waitcnt lgkmcnt(" #n ")" ::: "memory")
; #define PG8_BAR __builtin_amdgcn_s_barrier()
; #define PG8_SCHED __builtin_amdgcn_sched_barrier(0)
; template <class Epi, class Sched, bool ALIGN_EPI = false, bool SP2 = false>
; __device__ __forceinline__ void gemm_phase(PG8_LAS unsigned char* lds, const Gemm g, const Sched& S, const Epi& E) {
;     ...
;         for (int t = 0; t < nt; t += 2) {
;             const bool last = (t == nt - 2);
;             const char* a1 = cA + (size_t)(t + 1) * kstep;
;             const char* a2 = last ? nA : cA + (size_t)(t + 2) * kstep; const char* b2 = last ? nB : cB + (size_t)(t + 2) * kstep;
;     ...
;             PG8_LDA(At, 1, 1); PG8_STAGE(PG8_SB(1, 0), b3, voffB); PG8_STAGE(PG8_SB(1, 1), b3 + hstep, voffB); PG8_STAGE(PG8_SA(1, 0), a3, voffA);
;             PG8_WAIT_V(8); PG8_WAIT_L(0); PG8_BAR; PG8_MMA(1, 0, At, B0); PG8_MMA(1, 1, At, B1); PG8_BAR; PG8_SCHED;
;     ...
;         if constexpr (ALIGN_EPI) { if (wr == 0) PG8_BAR; }
	s_add_i32 s58, s60, s11
	v_lshl_add_u64 v[186:187], v[186:187], 0, s[66:67]
	s_mov_b32 m0, s58
	ds_read_b128 v[174:177], v192 offset:49152
	ds_read_b128 v[178:181], v192 offset:50176
	ds_read_b128 v[182:185], v192 offset:51200
	ds_read_b128 v[194:197], v192 offset:52224
	ds_read_b128 v[206:209], v192 offset:53248
	ds_read_b128 v[210:213], v192 offset:54272
	ds_read_b128 v[214:217], v192 offset:55296
	ds_read_b128 v[218:221], v192 offset:56320
	global_load_lds_dwordx4 v[186:187], off
	s_add_i32 m0, s58, 0x2000
	s_add_u32 s58, s82, 0x40080
	v_lshl_add_u64 v[186:187], v[198:199], 0, s[66:67]
	s_addc_u32 s59, s83, 0
	s_add_i32 s60, s61, s11
	global_load_lds_dwordx4 v[186:187], off
	v_lshl_add_u64 v[186:187], s[58:59], 0, v[132:133]
	s_mov_b32 m0, s60
	s_nop 0
	global_load_lds_dwordx4 v[186:187], off
	v_lshl_add_u64 v[186:187], s[58:59], 0, v[128:129]
	s_add_i32 m0, s60, 0x2000
	s_nop 0
	global_load_lds_dwordx4 v[186:187], off
	v_lshl_add_u64 v[186:187], v[222:223], 0, s[66:67]
	v_mov_b32_e32 v232, v186
	v_mov_b32_e32 v233, v187
	v_lshl_add_u64 v[186:187], v[224:225], 0, s[66:67]
	v_mov_b32_e32 v234, v186
	v_mov_b32_e32 v235, v187
	s_waitcnt vmcnt(6)
	s_waitcnt lgkmcnt(0)
	s_barrier
	s_setprio 1
	s_waitcnt lgkmcnt(0)
	v_mfma_f32_16x16x32_bf16 v[60:63], v[140:143], v[174:177], v[60:63]
	v_mfma_f32_16x16x32_bf16 v[56:59], v[150:153], v[174:177], v[56:59]
	v_mfma_f32_16x16x32_bf16 v[44:47], v[140:143], v[182:185], v[44:47]
	v_mfma_f32_16x16x32_bf16 v[40:43], v[150:153], v[182:185], v[40:43]
	v_mfma_f32_16x16x32_bf16 v[28:31], v[140:143], v[206:209], v[28:31]
	v_mfma_f32_16x16x32_bf16 v[24:27], v[150:153], v[206:209], v[24:27]
	v_mfma_f32_16x16x32_bf16 v[12:15], v[140:143], v[214:217], v[12:15]
	v_mfma_f32_16x16x32_bf16 v[8:11], v[150:153], v[214:217], v[8:11]
	v_mfma_f32_16x16x32_bf16 v[60:63], v[146:149], v[178:181], v[60:63]
	v_mfma_f32_16x16x32_bf16 v[56:59], v[154:157], v[178:181], v[56:59]
	v_mfma_f32_16x16x32_bf16 v[44:47], v[146:149], v[194:197], v[44:47]
	v_mfma_f32_16x16x32_bf16 v[40:43], v[154:157], v[194:197], v[40:43]
	v_mfma_f32_16x16x32_bf16 v[28:31], v[146:149], v[210:213], v[28:31]
	v_mfma_f32_16x16x32_bf16 v[24:27], v[154:157], v[210:213], v[24:27]
	v_mfma_f32_16x16x32_bf16 v[12:15], v[146:149], v[218:221], v[12:15]
	v_mfma_f32_16x16x32_bf16 v[8:11], v[154:157], v[218:221], v[8:11]
	s_setprio 0
	s_setprio 1
	v_mfma_f32_16x16x32_bf16 v[52:55], v[158:161], v[174:177], v[52:55]
	v_mfma_f32_16x16x32_bf16 v[48:51], v[166:169], v[174:177], v[48:51]
	v_mfma_f32_16x16x32_bf16 v[36:39], v[158:161], v[182:185], v[36:39]
	v_mfma_f32_16x16x32_bf16 v[32:35], v[166:169], v[182:185], v[32:35]
	v_mfma_f32_16x16x32_bf16 v[20:23], v[158:161], v[206:209], v[20:23]
	v_mfma_f32_16x16x32_bf16 v[16:19], v[166:169], v[206:209], v[16:19]
	v_mfma_f32_16x16x32_bf16 v[4:7], v[158:161], v[214:217], v[4:7]
	v_mfma_f32_16x16x32_bf16 v[0:3], v[166:169], v[214:217], v[0:3]
	v_mfma_f32_16x16x32_bf16 v[52:55], v[162:165], v[178:181], v[52:55]
	v_mfma_f32_16x16x32_bf16 v[48:51], v[170:173], v[178:181], v[48:51]
	v_mfma_f32_16x16x32_bf16 v[36:39], v[162:165], v[194:197], v[36:39]
	v_mfma_f32_16x16x32_bf16 v[32:35], v[170:173], v[194:197], v[32:35]
	v_mfma_f32_16x16x32_bf16 v[20:23], v[162:165], v[210:213], v[20:23]
	v_mfma_f32_16x16x32_bf16 v[16:19], v[170:173], v[210:213], v[16:19]
	v_mfma_f32_16x16x32_bf16 v[4:7], v[162:165], v[218:221], v[4:7]
	v_mfma_f32_16x16x32_bf16 v[0:3], v[170:173], v[218:221], v[0:3]
	s_setprio 0
	s_barrier
	s_add_i32 s90, s90, 2
	s_add_u32 s80, s80, 0x100
	s_addc_u32 s81, s81, 0
	s_add_u32 s88, s88, 0x100
	s_addc_u32 s89, s89, 0
	s_cmp_gt_u32 s90, 13
	s_cbranch_scc0 .LBB0_660
	s_and_b64 vcc, exec, s[68:69]
	s_cbranch_vccz .LBB0_663
	s_barrier

; #define PG8_STAGE(bufoff, gbase, voff) do { _Pragma("unroll") for (int _i = 0; _i < 2; ++_i) \
;         __builtin_amdgcn_global_load_lds((const unsigned*)((const char*)(gbase) + (voff)[_i]), (PG8_LAS unsigned*)(lds + (bufoff) + ldsw + _i * 8192), 16, 0, 0); } while (0)
; #define PG8_WAIT_V(n) asm volatile("s_waitcnt vmcnt(" #n ")" ::: "memory")
; #define PG8_BAR __builtin_amdgcn_s_barrier()
; template <class Epi, class Sched, bool ALIGN_EPI = false, bool SP2 = false>
; __device__ __forceinline__ void gemm_phase(PG8_LAS unsigned char* lds, const Gemm g, const Sched& S, const Epi& E) {
;     const int tid = threadIdx.x, wid = __builtin_amdgcn_readfirstlane(tid >> 6), lane = tid & 63, wr = wid >> 2, wc = wid & 3, fr = lane & 15, fq = lane >> 4;
;     const int K = g.K, nt = K / BK;
;     unsigned voffA[2], voffB[2];
; #pragma unroll
;     for (int i = 0; i < 2; ++i) { int R, C; stage_rc(tid * 16 + i * 8192, R, C); const int Rb = Epi::PERM ? ((R & ~31) + perm32(R & 31)) : R;
;         voffA[i] = (unsigned)(R * K + C) * 2u; voffB[i] = (unsigned)(Rb * K + C) * 2u; }
;     const size_t kstep = (size_t)(BK * 2);
;     const size_t hstep = (size_t)HALF * K * 2;
;     const size_t tstep = 2 * hstep;
;     const unsigned ldsw = (unsigned)wid * 1024u;
;     const int aoff = lds_byte(wr * 64 + fr, fq * 8), boff = lds_byte(wc * 32 + fr, fq * 8);
;     ...
;         PG8_STAGE(PG8_SB(0, 0), cB, voffB); PG8_STAGE(PG8_SB(0, 1), cB + hstep, voffB); PG8_STAGE(PG8_SA(0, 0), cA, voffA); PG8_STAGE(PG8_SA(0, 1), cA + hstep, voffA);
;         if (wr == 1) PG8_BAR;
;         PG8_WAIT_V(2); PG8_BAR;
;         PG8_STAGE(PG8_SB(1, 0), cB + kstep, voffB); PG8_STAGE(PG8_SA(1, 0), cA + kstep, voffA); PG8_STAGE(PG8_SB(1, 1), cB + hstep + kstep, voffB);
;         PG8_WAIT_V(6); PG8_BAR;
.LBB0_720:
	s_add_u32 s66, s26, 0xc0000
	s_addc_u32 s67, s27, 0
	s_lshl_b32 s5, s5, 5
	s_mov_b64 s[68:69], 0x80
	s_and_b32 s57, s5, 0x60
	s_add_i32 m0, s29, 0x18000
	v_lshl_add_u64 v[6:7], v[6:7], 0, s[68:69]
	s_lshl_b32 s11, s4, 13
	s_lshl_b32 s5, s57, 7
	s_waitcnt vmcnt(2)
	s_barrier
	global_load_lds_dwordx4 v[6:7], off
	v_lshl_add_u64 v[4:5], v[4:5], 0, s[68:69]
	s_add_i32 m0, s29, 0x1a000
	s_add_i32 s82, s29, 0x8000
	s_add_i32 s83, s29, 0xa000
	global_load_lds_dwordx4 v[4:5], off
	v_lshl_add_u64 v[0:1], v[0:1], 0, s[68:69]
	s_mov_b32 m0, s82
	s_add_u32 s6, s78, 0xb0080
	global_load_lds_dwordx4 v[0:1], off
	v_mov_b32_e32 v232, v0
	v_mov_b32_e32 v233, v1
	v_lshl_add_u64 v[0:1], v[2:3], 0, s[68:69]
	s_mov_b32 m0, s83
	s_addc_u32 s7, s79, 0
	global_load_lds_dwordx4 v[0:1], off
	v_mov_b32_e32 v234, v0
	v_mov_b32_e32 v235, v1
	s_add_i32 m0, s29, 0x1c000
	v_lshl_add_u64 v[0:1], s[6:7], 0, v[148:149]
	global_load_lds_dwordx4 v[0:1], off
	v_lshl_add_u64 v[0:1], s[6:7], 0, v[152:153]
	s_add_i32 m0, s29, 0x1e000
	v_lshlrev_b32_e32 v3, 2, v201
	global_load_lds_dwordx4 v[0:1], off
	v_bfe_u32 v0, v201, 4, 2
	v_and_b32_e32 v1, 15, v201
	v_lshl_or_b32 v145, s4, 6, v1
	v_lshlrev_b32_e32 v2, 4, v0
	v_lshlrev_b32_e32 v4, 6, v201
	s_movk_i32 s4, 0x3c0
	v_lshl_or_b32 v1, v1, 6, v2
	v_and_b32_e32 v3, 32, v3
	v_and_or_b32 v2, v4, s4, v2
	v_bitop3_b32 v2, s5, v2, v3 bitop3:0xf6
	s_cmpk_lt_u32 s2, 0x100
	v_cmp_eq_u32_e64 s[4:5], 0, v0
	v_lshl_or_b32 v166, v0, 3, s57
	v_add_u16_e32 v0, v8, v9
	s_waitcnt vmcnt(6)
	s_cselect_b64 s[70:71], -1, 0
	v_lshrrev_b16_e32 v0, 1, v0
	s_add_i32 s86, 0, 0x10000
	s_add_i32 s88, 0, 0x14000
	v_bitop3_b32 v1, v1, s11, v3 bitop3:0xde
	v_add_lshl_u32 v154, v10, v0, 1
	v_add_lshl_u32 v156, v11, v0, 1
	v_add_u32_e32 v167, s86, v2
	v_add_u32_e32 v168, s88, v2
	v_mbcnt_lo_u32_b32 v0, -1, 0
	s_add_i32 s86, s86, s28
	s_add_i32 s88, s88, s28
	s_add_i32 s90, 0, 0x18000
	s_add_i32 s91, 0, 0x1c000
	v_mov_b32_e32 v155, v149
	v_mov_b32_e32 v157, v149
	v_add_u32_e32 v169, 0, v1
	v_mbcnt_hi_u32_b32 v170, -1, v0
	s_add_i32 s84, s29, 0xc000
	s_add_i32 s85, s29, 0xe000
	s_add_i32 s87, s86, 0x2000
	s_add_i32 s89, s88, 0x2000
	v_add_u32_e32 v171, s90, v2
	v_add_u32_e32 v172, s91, v2
	s_barrier
	s_branch .LBB0_723

; #define PG8_STAGE(bufoff, gbase, voff) do { _Pragma("unroll") for (int _i = 0; _i < 2; ++_i) \
;         __builtin_amdgcn_global_load_lds((const unsigned*)((const char*)(gbase) + (voff)[_i]), (PG8_LAS unsigned*)(lds + (bufoff) + ldsw + _i * 8192), 16, 0, 0); } while (0)
; #define PG8_LDA(dst, b, h) do { _Pragma("unroll") for (int m = 0; m < 4; ++m) _Pragma("unroll") for (int k = 0; k < 2; ++k) dst[m][k] = *(const PG8_LAS bf16x8*)(lds + PG8_SA(b, h) + aoff + m * 2048 + k * 1024); } while (0)
; #define PG8_LDB(dst, b, h) do { _Pragma("unroll") for (int n = 0; n < 2; ++n) _Pragma("unroll") for (int k = 0; k < 2; ++k) dst[n][k] = *(const PG8_LAS bf16x8*)(lds + PG8_SB(b, h) + boff + n * 2048 + k * 1024); } while (0)
; #define PG8_MMA(ai, bj, At, Bt) do { __builtin_amdgcn_s_setprio(1); _Pragma("unroll") for (int m = 0; m < 4; ++m) _Pragma("unroll") for (int n = 0; n < 2; ++n) _Pragma("unroll") for (int k = 0; k < 2; ++k) \
;         acc[ai][bj][m][n] = __builtin_amdgcn_mfma_f32_16x16x32_bf16(Bt[n][k], At[m][k], acc[ai][bj][m][n], 0, 0, 0); __builtin_amdgcn_s_setprio(0); } while (0)
; #define PG8_WAIT_V(n) asm volatile("s_waitcnt vmcnt(" #n ")" ::: "memory")
; #define PG8_WAIT_L(n) asm volatile("s_waitcnt lgkmcnt(" #n ")" ::: "memory")
; #define PG8_BAR __builtin_amdgcn_s_barrier()
; #define PG8_SCHED __builtin_amdgcn_sched_barrier(0)
; template <class Epi, class Sched, bool ALIGN_EPI = false, bool SP2 = false>
; __device__ __forceinline__ void gemm_phase(PG8_LAS unsigned char* lds, const Gemm g, const Sched& S, const Epi& E) {
;     ...
;             PG8_LDB(B0, 0, 0); PG8_LDB(B1, 0, 1); PG8_SCHED; PG8_LDA(At, 0, 0); PG8_STAGE(PG8_SA(1, 1), a1 + hstep, voffA);
;             PG8_WAIT_V(8); PG8_WAIT_L(0); PG8_BAR; PG8_MMA(0, 0, At, B0); PG8_MMA(0, 1, At, B1); PG8_BAR; PG8_SCHED;
;             PG8_LDA(At, 0, 1); PG8_STAGE(PG8_SB(0, 0), b2, voffB); PG8_STAGE(PG8_SB(0, 1), b2 + hstep, voffB); PG8_STAGE(PG8_SA(0, 0), a2, voffA);
;             PG8_WAIT_V(8); PG8_WAIT_L(0); PG8_BAR; PG8_MMA(1, 0, At, B0); PG8_MMA(1, 1, At, B1); PG8_BAR; PG8_SCHED;
.LBB0_730:
	ds_read_b128 v[128:131], v167
	ds_read_b128 v[132:135], v167 offset:1024
	ds_read_b128 v[136:139], v167 offset:2048
	ds_read_b128 v[140:143], v167 offset:3072
	ds_read_b128 v[158:161], v168
	ds_read_b128 v[162:165], v168 offset:1024
	ds_read_b128 v[174:177], v168 offset:2048
	ds_read_b128 v[178:181], v168 offset:3072
	s_add_u32 s60, s76, 0xfff50080
	s_addc_u32 s61, s77, -1
	s_cmp_eq_u32 s59, 40
	s_cselect_b32 s81, s73, s61
	s_cselect_b32 s80, s72, s60
	s_cselect_b32 s79, s75, s58
	s_cselect_b32 s78, s74, s57
	s_mov_b32 m0, s82
	s_nop 0
	global_load_lds_dwordx4 v[232:233], off
	s_mov_b32 m0, s83
	s_nop 0
	global_load_lds_dwordx4 v[234:235], off
	s_mov_b32 m0, s84
	v_lshl_add_u64 v[198:199], s[76:77], 0, v[154:155]
	ds_read_b128 v[182:185], v169
	ds_read_b128 v[186:189], v169 offset:1024
	ds_read_b128 v[190:193], v169 offset:2048
	ds_read_b128 v[194:197], v169 offset:3072
	ds_read_b128 v[206:209], v169 offset:4096
	ds_read_b128 v[210:213], v169 offset:5120
	ds_read_b128 v[214:217], v169 offset:6144
	ds_read_b128 v[218:221], v169 offset:7168
	global_load_lds_dwordx4 v[198:199], off
	v_lshl_add_u64 v[198:199], s[76:77], 0, v[156:157]
	s_mov_b32 m0, s85
	s_nop 0
	global_load_lds_dwordx4 v[198:199], off
	s_waitcnt vmcnt(8)
	s_waitcnt lgkmcnt(0)
	s_barrier
	s_setprio 1
	s_waitcnt lgkmcnt(0)
	v_mfma_f32_16x16x32_bf16 v[124:127], v[128:131], v[182:185], v[124:127]
	v_mfma_f32_16x16x32_bf16 v[120:123], v[136:139], v[182:185], v[120:123]
	v_mfma_f32_16x16x32_bf16 v[108:111], v[128:131], v[190:193], v[108:111]
	v_mfma_f32_16x16x32_bf16 v[104:107], v[136:139], v[190:193], v[104:107]
	v_mfma_f32_16x16x32_bf16 v[92:95], v[128:131], v[206:209], v[92:95]
	v_mfma_f32_16x16x32_bf16 v[88:91], v[136:139], v[206:209], v[88:91]
	v_mfma_f32_16x16x32_bf16 v[76:79], v[128:131], v[214:217], v[76:79]
	v_mfma_f32_16x16x32_bf16 v[72:75], v[136:139], v[214:217], v[72:75]
	v_mfma_f32_16x16x32_bf16 v[124:127], v[132:135], v[186:189], v[124:127]
	v_mfma_f32_16x16x32_bf16 v[120:123], v[140:143], v[186:189], v[120:123]
	v_mfma_f32_16x16x32_bf16 v[108:111], v[132:135], v[194:197], v[108:111]
	v_mfma_f32_16x16x32_bf16 v[104:107], v[140:143], v[194:197], v[104:107]
	v_mfma_f32_16x16x32_bf16 v[92:95], v[132:135], v[210:213], v[92:95]
	v_mfma_f32_16x16x32_bf16 v[88:91], v[140:143], v[210:213], v[88:91]
	v_mfma_f32_16x16x32_bf16 v[76:79], v[132:135], v[218:221], v[76:79]
	v_mfma_f32_16x16x32_bf16 v[72:75], v[140:143], v[218:221], v[72:75]
	s_setprio 0
	s_setprio 1
	v_mfma_f32_16x16x32_bf16 v[116:119], v[158:161], v[182:185], v[116:119]
	v_mfma_f32_16x16x32_bf16 v[112:115], v[174:177], v[182:185], v[112:115]
	v_mfma_f32_16x16x32_bf16 v[100:103], v[158:161], v[190:193], v[100:103]
	v_mfma_f32_16x16x32_bf16 v[96:99], v[174:177], v[190:193], v[96:99]
	v_mfma_f32_16x16x32_bf16 v[84:87], v[158:161], v[206:209], v[84:87]
	v_mfma_f32_16x16x32_bf16 v[80:83], v[174:177], v[206:209], v[80:83]
	v_mfma_f32_16x16x32_bf16 v[68:71], v[158:161], v[214:217], v[68:71]
	v_mfma_f32_16x16x32_bf16 v[64:67], v[174:177], v[214:217], v[64:67]
	v_mfma_f32_16x16x32_bf16 v[116:119], v[162:165], v[186:189], v[116:119]
	v_mfma_f32_16x16x32_bf16 v[112:115], v[178:181], v[186:189], v[112:115]
	v_mfma_f32_16x16x32_bf16 v[100:103], v[162:165], v[194:197], v[100:103]
	v_mfma_f32_16x16x32_bf16 v[96:99], v[178:181], v[194:197], v[96:99]
	v_mfma_f32_16x16x32_bf16 v[84:87], v[162:165], v[210:213], v[84:87]
	v_mfma_f32_16x16x32_bf16 v[80:83], v[178:181], v[210:213], v[80:83]
	v_mfma_f32_16x16x32_bf16 v[68:71], v[162:165], v[218:221], v[68:71]
	v_mfma_f32_16x16x32_bf16 v[64:67], v[178:181], v[218:221], v[64:67]
	s_setprio 0
	s_barrier
	s_mov_b32 m0, s86
	v_lshl_add_u64 v[198:199], s[78:79], 0, v[148:149]
	s_add_u32 vcc_lo, s78, 0xb0000
	ds_read_b128 v[182:185], v169 offset:16384
	ds_read_b128 v[186:189], v169 offset:17408
	ds_read_b128 v[190:193], v169 offset:18432
	ds_read_b128 v[194:197], v169 offset:19456
	ds_read_b128 v[206:209], v169 offset:20480
	ds_read_b128 v[210:213], v169 offset:21504
	ds_read_b128 v[214:217], v169 offset:22528
	ds_read_b128 v[218:221], v169 offset:23552
	global_load_lds_dwordx4 v[198:199], off
	v_lshl_add_u64 v[222:223], s[78:79], 0, v[152:153]
	s_mov_b32 m0, s87
	s_addc_u32 vcc_hi, s79, 0
	global_load_lds_dwordx4 v[222:223], off
	v_lshl_add_u64 v[224:225], vcc, 0, v[148:149]
	s_mov_b32 m0, s88
	v_lshl_add_u64 v[226:227], s[80:81], 0, v[150:151]
	global_load_lds_dwordx4 v[224:225], off
	v_lshl_add_u64 v[224:225], vcc, 0, v[152:153]
	s_mov_b32 m0, s89
	s_nop 0
	global_load_lds_dwordx4 v[224:225], off
	v_lshl_add_u64 v[224:225], s[80:81], 0, v[146:147]
	v_mov_b32_e32 v236, v224
	v_mov_b32_e32 v237, v225
	v_mov_b32_e32 v238, v226
	v_mov_b32_e32 v239, v227
	s_waitcnt vmcnt(6)
	s_waitcnt lgkmcnt(0)
	s_barrier
; #define PG8_STAGE(bufoff, gbase, voff) do { _Pragma("unroll") for (int _i = 0; _i < 2; ++_i) \
;         __builtin_amdgcn_global_load_lds((const unsigned*)((const char*)(gbase) + (voff)[_i]), (PG8_LAS unsigned*)(lds + (bufoff) + ldsw + _i * 8192), 16, 0, 0); } while (0)
; #define PG8_LDA(dst, b, h) do { _Pragma("unroll") for (int m = 0; m < 4; ++m) _Pragma("unroll") for (int k = 0; k < 2; ++k) dst[m][k] = *(const PG8_LAS bf16x8*)(lds + PG8_SA(b, h) + aoff + m * 2048 + k * 1024); } while (0)
; #define PG8_LDB(dst, b, h) do { _Pragma("unroll") for (int n = 0; n < 2; ++n) _Pragma("unroll") for (int k = 0; k < 2; ++k) dst[n][k] = *(const PG8_LAS bf16x8*)(lds + PG8_SB(b, h) + boff + n * 2048 + k * 1024); } while (0)
; #define PG8_MMA(ai, bj, At, Bt) do { __builtin_amdgcn_s_setprio(1); _Pragma("unroll") for (int m = 0; m < 4; ++m) _Pragma("unroll") for (int n = 0; n < 2; ++n) _Pragma("unroll") for (int k = 0; k < 2; ++k) \
;         acc[ai][bj][m][n] = __builtin_amdgcn_mfma_f32_16x16x32_bf16(Bt[n][k], At[m][k], acc[ai][bj][m][n], 0, 0, 0); __builtin_amdgcn_s_setprio(0); } while (0)
; #define PG8_WAIT_V(n) asm volatile("s_waitcnt vmcnt(" #n ")" ::: "memory")
; #define PG8_WAIT_L(n) asm volatile("s_waitcnt lgkmcnt(" #n ")" ::: "memory")
; #define PG8_BAR __builtin_amdgcn_s_barrier()
; #define PG8_SCHED __builtin_amdgcn_sched_barrier(0)
; template <class Epi, class Sched, bool ALIGN_EPI = false, bool SP2 = false>
; __device__ __forceinline__ void gemm_phase(PG8_LAS unsigned char* lds, const Gemm g, const Sched& S, const Epi& E) {
;     ...
;             PG8_WAIT_V(8); PG8_WAIT_L(0); PG8_BAR; PG8_MMA(1, 0, At, B0); PG8_MMA(1, 1, At, B1); PG8_BAR; PG8_SCHED;
;             PG8_LDB(B0, 1, 0); PG8_LDB(B1, 1, 1); PG8_SCHED; PG8_LDA(At, 1, 0); PG8_STAGE(PG8_SA(0, 1), a2 + hstep, voffA);
;             PG8_WAIT_V(8); PG8_WAIT_L(0); PG8_BAR; PG8_MMA(0, 0, At, B0); PG8_MMA(0, 1, At, B1); PG8_BAR; PG8_SCHED;
	s_setprio 1
	s_waitcnt lgkmcnt(0)
	v_mfma_f32_16x16x32_bf16 v[60:63], v[128:131], v[182:185], v[60:63]
	v_mfma_f32_16x16x32_bf16 v[56:59], v[136:139], v[182:185], v[56:59]
	v_mfma_f32_16x16x32_bf16 v[44:47], v[128:131], v[190:193], v[44:47]
	v_mfma_f32_16x16x32_bf16 v[40:43], v[136:139], v[190:193], v[40:43]
	v_mfma_f32_16x16x32_bf16 v[32:35], v[128:131], v[206:209], v[32:35]
	v_mfma_f32_16x16x32_bf16 v[24:27], v[136:139], v[206:209], v[24:27]
	v_mfma_f32_16x16x32_bf16 v[16:19], v[128:131], v[214:217], v[16:19]
	v_mfma_f32_16x16x32_bf16 v[8:11], v[136:139], v[214:217], v[8:11]
	v_mfma_f32_16x16x32_bf16 v[60:63], v[132:135], v[186:189], v[60:63]
	v_mfma_f32_16x16x32_bf16 v[56:59], v[140:143], v[186:189], v[56:59]
	v_mfma_f32_16x16x32_bf16 v[44:47], v[132:135], v[194:197], v[44:47]
	v_mfma_f32_16x16x32_bf16 v[40:43], v[140:143], v[194:197], v[40:43]
	v_mfma_f32_16x16x32_bf16 v[32:35], v[132:135], v[210:213], v[32:35]
	v_mfma_f32_16x16x32_bf16 v[24:27], v[140:143], v[210:213], v[24:27]
	v_mfma_f32_16x16x32_bf16 v[16:19], v[132:135], v[218:221], v[16:19]
	v_mfma_f32_16x16x32_bf16 v[8:11], v[140:143], v[218:221], v[8:11]
	s_setprio 0
	s_setprio 1
	v_mfma_f32_16x16x32_bf16 v[52:55], v[158:161], v[182:185], v[52:55]
	v_mfma_f32_16x16x32_bf16 v[48:51], v[174:177], v[182:185], v[48:51]
	v_mfma_f32_16x16x32_bf16 v[36:39], v[158:161], v[190:193], v[36:39]
	v_mfma_f32_16x16x32_bf16 v[28:31], v[174:177], v[190:193], v[28:31]
	v_mfma_f32_16x16x32_bf16 v[20:23], v[158:161], v[206:209], v[20:23]
	v_mfma_f32_16x16x32_bf16 v[12:15], v[174:177], v[206:209], v[12:15]
	v_mfma_f32_16x16x32_bf16 v[4:7], v[158:161], v[214:217], v[4:7]
	v_mfma_f32_16x16x32_bf16 v[0:3], v[174:177], v[214:217], v[0:3]
	v_mfma_f32_16x16x32_bf16 v[52:55], v[162:165], v[186:189], v[52:55]
	v_mfma_f32_16x16x32_bf16 v[48:51], v[178:181], v[186:189], v[48:51]
	v_mfma_f32_16x16x32_bf16 v[36:39], v[162:165], v[194:197], v[36:39]
	v_mfma_f32_16x16x32_bf16 v[28:31], v[178:181], v[194:197], v[28:31]
	v_mfma_f32_16x16x32_bf16 v[20:23], v[162:165], v[210:213], v[20:23]
	v_mfma_f32_16x16x32_bf16 v[12:15], v[178:181], v[210:213], v[12:15]
	v_mfma_f32_16x16x32_bf16 v[4:7], v[162:165], v[218:221], v[4:7]
	v_mfma_f32_16x16x32_bf16 v[0:3], v[178:181], v[218:221], v[0:3]
	s_setprio 0
	s_barrier
	ds_read_b128 v[128:131], v171
	ds_read_b128 v[132:135], v171 offset:1024
	ds_read_b128 v[136:139], v171 offset:2048
	ds_read_b128 v[140:143], v171 offset:3072
	ds_read_b128 v[158:161], v172
	ds_read_b128 v[162:165], v172 offset:1024
	ds_read_b128 v[174:177], v172 offset:2048
	ds_read_b128 v[178:181], v172 offset:3072
	s_add_u32 s80, s80, 0xb0000
	s_addc_u32 s81, s81, 0
	s_mov_b32 m0, s29
	s_nop 0
	global_load_lds_dwordx4 v[236:237], off
	s_mov_b32 m0, s30
	s_nop 0
	global_load_lds_dwordx4 v[238:239], off
	s_mov_b32 m0, s31
	v_lshl_add_u64 v[228:229], s[80:81], 0, v[146:147]
	ds_read_b128 v[182:185], v169 offset:32768
	ds_read_b128 v[186:189], v169 offset:33792
	ds_read_b128 v[190:193], v169 offset:34816
	ds_read_b128 v[194:197], v169 offset:35840
	ds_read_b128 v[206:209], v169 offset:36864
	ds_read_b128 v[210:213], v169 offset:37888
	ds_read_b128 v[214:217], v169 offset:38912
	ds_read_b128 v[218:221], v169 offset:39936
	global_load_lds_dwordx4 v[228:229], off
	v_lshl_add_u64 v[228:229], s[80:81], 0, v[150:151]
	s_mov_b32 m0, s37
	s_nop 0
	global_load_lds_dwordx4 v[228:229], off
	s_waitcnt vmcnt(8)
	s_waitcnt lgkmcnt(0)
	s_barrier
	s_setprio 1
	s_waitcnt lgkmcnt(0)
	v_mfma_f32_16x16x32_bf16 v[124:127], v[128:131], v[182:185], v[124:127]
	v_mfma_f32_16x16x32_bf16 v[120:123], v[136:139], v[182:185], v[120:123]
	v_mfma_f32_16x16x32_bf16 v[108:111], v[128:131], v[190:193], v[108:111]
	v_mfma_f32_16x16x32_bf16 v[104:107], v[136:139], v[190:193], v[104:107]
	v_mfma_f32_16x16x32_bf16 v[92:95], v[128:131], v[206:209], v[92:95]
	v_mfma_f32_16x16x32_bf16 v[88:91], v[136:139], v[206:209], v[88:91]
	v_mfma_f32_16x16x32_bf16 v[76:79], v[128:131], v[214:217], v[76:79]
	v_mfma_f32_16x16x32_bf16 v[72:75], v[136:139], v[214:217], v[72:75]
	v_mfma_f32_16x16x32_bf16 v[124:127], v[132:135], v[186:189], v[124:127]
	v_mfma_f32_16x16x32_bf16 v[120:123], v[140:143], v[186:189], v[120:123]
	v_mfma_f32_16x16x32_bf16 v[108:111], v[132:135], v[194:197], v[108:111]
	v_mfma_f32_16x16x32_bf16 v[104:107], v[140:143], v[194:197], v[104:107]
	v_mfma_f32_16x16x32_bf16 v[92:95], v[132:135], v[210:213], v[92:95]
	v_mfma_f32_16x16x32_bf16 v[88:91], v[140:143], v[210:213], v[88:91]
	v_mfma_f32_16x16x32_bf16 v[76:79], v[132:135], v[218:221], v[76:79]
	v_mfma_f32_16x16x32_bf16 v[72:75], v[140:143], v[218:221], v[72:75]
	s_setprio 0
	s_setprio 1
	v_mfma_f32_16x16x32_bf16 v[116:119], v[158:161], v[182:185], v[116:119]
	v_mfma_f32_16x16x32_bf16 v[112:115], v[174:177], v[182:185], v[112:115]
	v_mfma_f32_16x16x32_bf16 v[100:103], v[158:161], v[190:193], v[100:103]
	v_mfma_f32_16x16x32_bf16 v[96:99], v[174:177], v[190:193], v[96:99]
	v_mfma_f32_16x16x32_bf16 v[84:87], v[158:161], v[206:209], v[84:87]
	v_mfma_f32_16x16x32_bf16 v[80:83], v[174:177], v[206:209], v[80:83]
	v_mfma_f32_16x16x32_bf16 v[68:71], v[158:161], v[214:217], v[68:71]
	v_mfma_f32_16x16x32_bf16 v[64:67], v[174:177], v[214:217], v[64:67]
	v_mfma_f32_16x16x32_bf16 v[116:119], v[162:165], v[186:189], v[116:119]
	v_mfma_f32_16x16x32_bf16 v[112:115], v[178:181], v[186:189], v[112:115]
	v_mfma_f32_16x16x32_bf16 v[100:103], v[162:165], v[194:197], v[100:103]
	v_mfma_f32_16x16x32_bf16 v[96:99], v[178:181], v[194:197], v[96:99]
	v_mfma_f32_16x16x32_bf16 v[84:87], v[162:165], v[210:213], v[84:87]
	v_mfma_f32_16x16x32_bf16 v[80:83], v[178:181], v[210:213], v[80:83]
	v_mfma_f32_16x16x32_bf16 v[68:71], v[162:165], v[218:221], v[68:71]
	v_mfma_f32_16x16x32_bf16 v[64:67], v[178:181], v[218:221], v[64:67]
	s_setprio 0
	s_barrier
; #define PG8_STAGE(bufoff, gbase, voff) do { _Pragma("unroll") for (int _i = 0; _i < 2; ++_i) \
;         __builtin_amdgcn_global_load_lds((const unsigned*)((const char*)(gbase) + (voff)[_i]), (PG8_LAS unsigned*)(lds + (bufoff) + ldsw + _i * 8192), 16, 0, 0); } while (0)
; #define PG8_LDA(dst, b, h) do { _Pragma("unroll") for (int m = 0; m < 4; ++m) _Pragma("unroll") for (int k = 0; k < 2; ++k) dst[m][k] = *(const PG8_LAS bf16x8*)(lds + PG8_SA(b, h) + aoff + m * 2048 + k * 1024); } while (0)
; #define PG8_MMA(ai, bj, At, Bt) do { __builtin_amdgcn_s_setprio(1); _Pragma("unroll") for (int m = 0; m < 4; ++m) _Pragma("unroll") for (int n = 0; n < 2; ++n) _Pragma("unroll") for (int k = 0; k < 2; ++k) \
;         acc[ai][bj][m][n] = __builtin_amdgcn_mfma_f32_16x16x32_bf16(Bt[n][k], At[m][k], acc[ai][bj][m][n], 0, 0, 0); __builtin_amdgcn_s_setprio(0); } while (0)
; #define PG8_WAIT_V(n) asm volatile("s_waitcnt vmcnt(" #n ")" ::: "memory")
; #define PG8_WAIT_L(n) asm volatile("s_waitcnt lgkmcnt(" #n ")" ::: "memory")
; #define PG8_BAR __builtin_amdgcn_s_barrier()
; #define PG8_SCHED __builtin_amdgcn_sched_barrier(0)
; template <class Epi, class Sched, bool ALIGN_EPI = false, bool SP2 = false>
; __device__ __forceinline__ void gemm_phase(PG8_LAS unsigned char* lds, const Gemm g, const Sched& S, const Epi& E) {
;     ...
;         for (int t = 0; t < nt; t += 2) {
;             const bool last = (t == nt - 2);
;             const char* a1 = cA + (size_t)(t + 1) * kstep;
;             const char* a2 = last ? nA : cA + (size_t)(t + 2) * kstep; const char* b2 = last ? nB : cB + (size_t)(t + 2) * kstep;
;     ...
;             PG8_LDA(At, 1, 1); PG8_STAGE(PG8_SB(1, 0), b3, voffB); PG8_STAGE(PG8_SB(1, 1), b3 + hstep, voffB); PG8_STAGE(PG8_SA(1, 0), a3, voffA);
;             PG8_WAIT_V(8); PG8_WAIT_L(0); PG8_BAR; PG8_MMA(1, 0, At, B0); PG8_MMA(1, 1, At, B1); PG8_BAR; PG8_SCHED;
;     ...
;         if constexpr (ALIGN_EPI) { if (wr == 0) PG8_BAR; }
	s_add_i32 s60, s90, s28
	v_lshl_add_u64 v[198:199], v[198:199], 0, s[68:69]
	s_mov_b32 m0, s60
	ds_read_b128 v[182:185], v169 offset:49152
	ds_read_b128 v[186:189], v169 offset:50176
	ds_read_b128 v[190:193], v169 offset:51200
	ds_read_b128 v[194:197], v169 offset:52224
	ds_read_b128 v[206:209], v169 offset:53248
	ds_read_b128 v[210:213], v169 offset:54272
	ds_read_b128 v[214:217], v169 offset:55296
	ds_read_b128 v[218:221], v169 offset:56320
	global_load_lds_dwordx4 v[198:199], off
	s_add_i32 m0, s60, 0x2000
	s_add_u32 s78, s78, 0xb0080
	v_lshl_add_u64 v[198:199], v[222:223], 0, s[68:69]
	s_addc_u32 s79, s79, 0
	s_add_i32 s60, s91, s28
	global_load_lds_dwordx4 v[198:199], off
	v_lshl_add_u64 v[198:199], s[78:79], 0, v[148:149]
	s_mov_b32 m0, s60
	s_nop 0
	global_load_lds_dwordx4 v[198:199], off
	v_lshl_add_u64 v[198:199], s[78:79], 0, v[152:153]
	s_add_i32 m0, s60, 0x2000
	s_nop 0
	global_load_lds_dwordx4 v[198:199], off
	v_lshl_add_u64 v[198:199], v[224:225], 0, s[68:69]
	v_mov_b32_e32 v232, v198
	v_mov_b32_e32 v233, v199
	v_lshl_add_u64 v[198:199], v[226:227], 0, s[68:69]
	v_mov_b32_e32 v234, v198
	v_mov_b32_e32 v235, v199
	s_waitcnt vmcnt(6)
	s_waitcnt lgkmcnt(0)
	s_barrier
	s_setprio 1
	s_waitcnt lgkmcnt(0)
	v_mfma_f32_16x16x32_bf16 v[60:63], v[128:131], v[182:185], v[60:63]
	v_mfma_f32_16x16x32_bf16 v[56:59], v[136:139], v[182:185], v[56:59]
	v_mfma_f32_16x16x32_bf16 v[44:47], v[128:131], v[190:193], v[44:47]
	v_mfma_f32_16x16x32_bf16 v[40:43], v[136:139], v[190:193], v[40:43]
	v_mfma_f32_16x16x32_bf16 v[32:35], v[128:131], v[206:209], v[32:35]
	v_mfma_f32_16x16x32_bf16 v[24:27], v[136:139], v[206:209], v[24:27]
	v_mfma_f32_16x16x32_bf16 v[16:19], v[128:131], v[214:217], v[16:19]
	v_mfma_f32_16x16x32_bf16 v[8:11], v[136:139], v[214:217], v[8:11]
	v_mfma_f32_16x16x32_bf16 v[60:63], v[132:135], v[186:189], v[60:63]
	v_mfma_f32_16x16x32_bf16 v[56:59], v[140:143], v[186:189], v[56:59]
	v_mfma_f32_16x16x32_bf16 v[44:47], v[132:135], v[194:197], v[44:47]
	v_mfma_f32_16x16x32_bf16 v[40:43], v[140:143], v[194:197], v[40:43]
	v_mfma_f32_16x16x32_bf16 v[32:35], v[132:135], v[210:213], v[32:35]
	v_mfma_f32_16x16x32_bf16 v[24:27], v[140:143], v[210:213], v[24:27]
	v_mfma_f32_16x16x32_bf16 v[16:19], v[132:135], v[218:221], v[16:19]
	v_mfma_f32_16x16x32_bf16 v[8:11], v[140:143], v[218:221], v[8:11]
	s_setprio 0
	s_setprio 1
	v_mfma_f32_16x16x32_bf16 v[52:55], v[158:161], v[182:185], v[52:55]
	v_mfma_f32_16x16x32_bf16 v[48:51], v[174:177], v[182:185], v[48:51]
	v_mfma_f32_16x16x32_bf16 v[36:39], v[158:161], v[190:193], v[36:39]
	v_mfma_f32_16x16x32_bf16 v[28:31], v[174:177], v[190:193], v[28:31]
	v_mfma_f32_16x16x32_bf16 v[20:23], v[158:161], v[206:209], v[20:23]
	v_mfma_f32_16x16x32_bf16 v[12:15], v[174:177], v[206:209], v[12:15]
	v_mfma_f32_16x16x32_bf16 v[4:7], v[158:161], v[214:217], v[4:7]
	v_mfma_f32_16x16x32_bf16 v[0:3], v[174:177], v[214:217], v[0:3]
	v_mfma_f32_16x16x32_bf16 v[52:55], v[162:165], v[186:189], v[52:55]
	v_mfma_f32_16x16x32_bf16 v[48:51], v[178:181], v[186:189], v[48:51]
	v_mfma_f32_16x16x32_bf16 v[36:39], v[162:165], v[194:197], v[36:39]
	v_mfma_f32_16x16x32_bf16 v[28:31], v[178:181], v[194:197], v[28:31]
	v_mfma_f32_16x16x32_bf16 v[20:23], v[162:165], v[210:213], v[20:23]
	v_mfma_f32_16x16x32_bf16 v[12:15], v[178:181], v[210:213], v[12:15]
	v_mfma_f32_16x16x32_bf16 v[4:7], v[162:165], v[218:221], v[4:7]
	v_mfma_f32_16x16x32_bf16 v[0:3], v[178:181], v[218:221], v[0:3]
	s_setprio 0
	s_barrier
	s_add_i32 s59, s59, 2
	s_add_u32 s76, s76, 0x100
	s_addc_u32 s77, s77, 0
	s_add_u32 s57, s57, 0x100
	s_addc_u32 s58, s58, 0
	s_cmp_gt_u32 s59, 41
	s_cbranch_scc0 .LBB0_730
	s_and_b64 vcc, exec, s[70:71]
	s_cbranch_vccz .LBB0_733
	s_barrier

; #define PG8_STAGE(bufoff, gbase, voff) do { _Pragma("unroll") for (int _i = 0; _i < 2; ++_i) \
;         __builtin_amdgcn_global_load_lds((const unsigned*)((const char*)(gbase) + (voff)[_i]), (PG8_LAS unsigned*)(lds + (bufoff) + ldsw + _i * 8192), 16, 0, 0); } while (0)
; #define PG8_WAIT_V(n) asm volatile("s_waitcnt vmcnt(" #n ")" ::: "memory")
; #define PG8_BAR __builtin_amdgcn_s_barrier()
; template <class Epi, class Sched, bool ALIGN_EPI = false, bool SP2 = false>
; __device__ __forceinline__ void gemm_phase(PG8_LAS unsigned char* lds, const Gemm g, const Sched& S, const Epi& E) {
;     const int tid = threadIdx.x, wid = __builtin_amdgcn_readfirstlane(tid >> 6), lane = tid & 63, wr = wid >> 2, wc = wid & 3, fr = lane & 15, fq = lane >> 4;
;     const int K = g.K, nt = K / BK;
;     unsigned voffA[2], voffB[2];
; #pragma unroll
;     for (int i = 0; i < 2; ++i) { int R, C; stage_rc(tid * 16 + i * 8192, R, C); const int Rb = Epi::PERM ? ((R & ~31) + perm32(R & 31)) : R;
;         voffA[i] = (unsigned)(R * K + C) * 2u; voffB[i] = (unsigned)(Rb * K + C) * 2u; }
;     const size_t kstep = (size_t)(BK * 2);
;     const size_t hstep = (size_t)HALF * K * 2;
;     const size_t tstep = 2 * hstep;
;     const unsigned ldsw = (unsigned)wid * 1024u;
;     const int aoff = lds_byte(wr * 64 + fr, fq * 8), boff = lds_byte(wc * 32 + fr, fq * 8);
;     ...
;         PG8_STAGE(PG8_SB(0, 0), cB, voffB); PG8_STAGE(PG8_SB(0, 1), cB + hstep, voffB); PG8_STAGE(PG8_SA(0, 0), cA, voffA); PG8_STAGE(PG8_SA(0, 1), cA + hstep, voffA);
;         if (wr == 1) PG8_BAR;
;         PG8_WAIT_V(2); PG8_BAR;
;         PG8_STAGE(PG8_SB(1, 0), cB + kstep, voffB); PG8_STAGE(PG8_SA(1, 0), cA + kstep, voffA); PG8_STAGE(PG8_SB(1, 1), cB + hstep + kstep, voffB);
;         PG8_WAIT_V(6); PG8_BAR;
.LBB0_802:
	s_add_u32 s64, s26, 0xc0000
	s_addc_u32 s65, s27, 0
	s_lshl_b32 s31, s31, 5
	s_mov_b64 s[66:67], 0x80
	s_and_b32 s57, s31, 0x60
	s_add_i32 m0, s20, 0x18000
	v_lshl_add_u64 v[6:7], v[6:7], 0, s[66:67]
	s_lshl_b32 s5, s56, 13
	s_lshl_b32 s60, s57, 7
	s_waitcnt vmcnt(2)
	s_barrier
	global_load_lds_dwordx4 v[6:7], off
	v_lshl_add_u64 v[4:5], v[4:5], 0, s[66:67]
	s_add_i32 m0, s20, 0x1a000
	s_add_i32 s31, s20, 0x8000
	s_add_i32 s37, s20, 0xa000
	global_load_lds_dwordx4 v[4:5], off
	v_lshl_add_u64 v[0:1], v[0:1], 0, s[66:67]
	s_mov_b32 m0, s31
	s_add_u32 s58, s82, 0x40080
	global_load_lds_dwordx4 v[0:1], off
	v_mov_b32_e32 v232, v0
	v_mov_b32_e32 v233, v1
	v_lshl_add_u64 v[0:1], v[2:3], 0, s[66:67]
	s_mov_b32 m0, s37
	s_addc_u32 s59, s83, 0
	global_load_lds_dwordx4 v[0:1], off
	v_mov_b32_e32 v234, v0
	v_mov_b32_e32 v235, v1
	s_add_i32 m0, s20, 0x1c000
	v_lshl_add_u64 v[0:1], s[58:59], 0, v[132:133]
	global_load_lds_dwordx4 v[0:1], off
	v_lshl_add_u64 v[0:1], s[58:59], 0, v[128:129]
	s_add_i32 m0, s20, 0x1e000
	v_lshlrev_b32_e32 v2, 2, v201
	global_load_lds_dwordx4 v[0:1], off
	v_and_b32_e32 v0, 15, v201
	v_lshlrev_b32_e32 v1, 1, v11
	v_lshl_or_b32 v145, s56, 6, v0
	v_lshl_or_b32 v0, v0, 6, v1
	v_and_b32_e32 v2, 32, v2
	v_bitop3_b32 v0, v0, s5, v2 bitop3:0xde
	v_lshlrev_b32_e32 v3, 6, v201
	s_movk_i32 s5, 0x3c0
	v_and_or_b32 v1, v3, s5, v1
	v_bitop3_b32 v188, s60, v1, v2 bitop3:0xf6
	v_lshlrev_b32_e32 v1, 8, v201
	v_and_b32_e32 v1, 0x38000, v1
	v_lshlrev_b32_e32 v2, 11, v12
	v_or3_b32 v1, v9, v1, v2
	v_add_u32_e32 v136, v1, v10
	v_lshlrev_b32_e32 v1, 4, v8
	s_waitcnt vmcnt(6)
	s_cmpk_lt_u32 s39, 0x100
	v_and_b32_e32 v1, 0x78000, v1
	s_sext_i32_i8 s86, s68
	s_cselect_b64 s[68:69], -1, 0
	v_or3_b32 v1, v9, v1, v2
	s_add_i32 s39, 0, 0x10000
	s_add_i32 s56, 0, 0x14000
	v_or_b32_e32 v189, s57, v11
	v_mov_b32_e32 v137, v133
	v_add_u32_e32 v138, v1, v10
	v_mov_b32_e32 v139, v133
	v_add_u32_e32 v190, s39, v188
	v_add_u32_e32 v191, s56, v188
	v_add_u32_e32 v192, 0, v0
	v_mov_b32_e32 v193, 0x358637bd
	s_movk_i32 s57, 0x1600
	s_barrier
	s_branch .LBB0_805

; #define PG8_STAGE(bufoff, gbase, voff) do { _Pragma("unroll") for (int _i = 0; _i < 2; ++_i) \
;         __builtin_amdgcn_global_load_lds((const unsigned*)((const char*)(gbase) + (voff)[_i]), (PG8_LAS unsigned*)(lds + (bufoff) + ldsw + _i * 8192), 16, 0, 0); } while (0)
; #define PG8_WAIT_V(n) asm volatile("s_waitcnt vmcnt(" #n ")" ::: "memory")
; #define PG8_BAR __builtin_amdgcn_s_barrier()
; template <class Epi, class Sched, bool ALIGN_EPI = false, bool SP2 = false>
; __device__ __forceinline__ void gemm_phase(PG8_LAS unsigned char* lds, const Gemm g, const Sched& S, const Epi& E) {
;     ...
;     const unsigned ldsw = (unsigned)wid * 1024u;
;     const int aoff = lds_byte(wr * 64 + fr, fq * 8), boff = lds_byte(wc * 32 + fr, fq * 8);
;     ...
;     const char* cA = (const char*)g.A + (size_t)cur.pm * tstep; const char* cB = (const char*)g.Bt + (size_t)cur.pn * tstep;
;     S.a_ready(cur);
;     if constexpr (SP2) {
;         PG8_STAGE(PG8_SB(0, 0), cB, voffB); PG8_STAGE(PG8_SB(0, 1), cB + hstep, voffB); PG8_STAGE(PG8_SA(0, 0), cA, voffA); PG8_STAGE(PG8_SA(0, 1), cA + hstep, voffA);
;         if (wr == 1) PG8_BAR;
;         PG8_WAIT_V(2); PG8_BAR;
;         PG8_STAGE(PG8_SB(1, 0), cB + kstep, voffB); PG8_STAGE(PG8_SA(1, 0), cA + kstep, voffA); PG8_STAGE(PG8_SB(1, 1), cB + hstep + kstep, voffB);
;         PG8_WAIT_V(6); PG8_BAR;
.LBB0_868:
	s_add_u32 s66, s26, 0x100000
	s_addc_u32 s67, s27, 0
	s_lshl_b32 s4, s4, 5
	s_mov_b64 s[68:69], 0x80
	s_and_b32 s7, s4, 0x60
	s_add_i32 m0, s29, 0x18000
	v_lshl_add_u64 v[6:7], v[6:7], 0, s[68:69]
	s_lshl_b32 s6, s3, 13
	s_lshl_b32 s57, s7, 7
	s_waitcnt vmcnt(2)
	s_barrier
	global_load_lds_dwordx4 v[6:7], off
	v_lshl_add_u64 v[4:5], v[4:5], 0, s[68:69]
	s_add_i32 m0, s29, 0x1a000
	s_add_i32 s82, s29, 0x8000
	s_add_i32 s83, s29, 0xa000
	global_load_lds_dwordx4 v[4:5], off
	v_lshl_add_u64 v[0:1], v[0:1], 0, s[68:69]
	s_mov_b32 m0, s82
	s_add_u32 s4, s78, 0xb0080
	global_load_lds_dwordx4 v[0:1], off
	v_mov_b32_e32 v232, v0
	v_mov_b32_e32 v233, v1
	v_lshl_add_u64 v[0:1], v[2:3], 0, s[68:69]
	s_mov_b32 m0, s83
	s_addc_u32 s5, s79, 0
	global_load_lds_dwordx4 v[0:1], off
	v_mov_b32_e32 v234, v0
	v_mov_b32_e32 v235, v1
	s_add_i32 m0, s29, 0x1c000
	v_lshl_add_u64 v[0:1], s[4:5], 0, v[148:149]
	global_load_lds_dwordx4 v[0:1], off
	v_lshl_add_u64 v[0:1], s[4:5], 0, v[152:153]
	s_add_i32 m0, s29, 0x1e000
	v_lshlrev_b32_e32 v3, 2, v201
	global_load_lds_dwordx4 v[0:1], off
	v_bfe_u32 v0, v201, 4, 2
	v_and_b32_e32 v1, 15, v201
	v_lshl_or_b32 v145, s3, 6, v1
	v_lshlrev_b32_e32 v2, 4, v0
	v_lshlrev_b32_e32 v4, 6, v201
	s_movk_i32 s3, 0x3c0
	v_lshl_or_b32 v1, v1, 6, v2
	v_and_b32_e32 v3, 32, v3
	v_and_or_b32 v2, v4, s3, v2
	s_cmpk_lt_u32 s2, 0x100
	v_cmp_eq_u32_e64 s[4:5], 0, v0
	v_lshl_or_b32 v166, v0, 3, s7
	v_add_u16_e32 v0, v8, v9
	v_bitop3_b32 v2, s57, v2, v3 bitop3:0xf6
	s_waitcnt vmcnt(6)
	s_cselect_b64 s[70:71], -1, 0
	v_lshrrev_b16_e32 v0, 1, v0
	s_add_i32 s86, 0, 0x10000
	s_add_i32 s88, 0, 0x14000
	v_bitop3_b32 v1, v1, s6, v3 bitop3:0xde
	v_add_lshl_u32 v154, v10, v0, 1
	v_add_lshl_u32 v156, v11, v0, 1
	v_add_u32_e32 v167, s86, v2
	v_add_u32_e32 v168, s88, v2
	v_mbcnt_lo_u32_b32 v0, -1, 0
	s_add_i32 s86, s86, s28
	s_add_i32 s88, s88, s28
	s_add_i32 s90, 0, 0x18000
	s_add_i32 s91, 0, 0x1c000
	v_mov_b32_e32 v155, v149
	v_mov_b32_e32 v157, v149
	v_add_u32_e32 v169, 0, v1
	v_mbcnt_hi_u32_b32 v170, -1, v0
	s_add_i32 s84, s29, 0xc000
	s_add_i32 s85, s29, 0xe000
	s_add_i32 s87, s86, 0x2000
	s_add_i32 s89, s88, 0x2000
	v_add_u32_e32 v171, s90, v2
	v_add_u32_e32 v172, s91, v2
	s_barrier
	s_branch .LBB0_871

; #define PG8_STAGE(bufoff, gbase, voff) do { _Pragma("unroll") for (int _i = 0; _i < 2; ++_i) \
;         __builtin_amdgcn_global_load_lds((const unsigned*)((const char*)(gbase) + (voff)[_i]), (PG8_LAS unsigned*)(lds + (bufoff) + ldsw + _i * 8192), 16, 0, 0); } while (0)
; #define PG8_WAIT_V(n) asm volatile("s_waitcnt vmcnt(" #n ")" ::: "memory")
; #define PG8_BAR __builtin_amdgcn_s_barrier()
; template <class Epi, class Sched, bool ALIGN_EPI = false, bool SP2 = false>
; __device__ __forceinline__ void gemm_phase(PG8_LAS unsigned char* lds, const Gemm g, const Sched& S, const Epi& E) {
;     ...
;     const unsigned ldsw = (unsigned)wid * 1024u;
;     const int aoff = lds_byte(wr * 64 + fr, fq * 8), boff = lds_byte(wc * 32 + fr, fq * 8);
;     ...
;     const char* cA = (const char*)g.A + (size_t)cur.pm * tstep; const char* cB = (const char*)g.Bt + (size_t)cur.pn * tstep;
;     S.a_ready(cur);
;     if constexpr (SP2) {
;         PG8_STAGE(PG8_SB(0, 0), cB, voffB); PG8_STAGE(PG8_SB(0, 1), cB + hstep, voffB); PG8_STAGE(PG8_SA(0, 0), cA, voffA); PG8_STAGE(PG8_SA(0, 1), cA + hstep, voffA);
;         if (wr == 1) PG8_BAR;
;         PG8_WAIT_V(2); PG8_BAR;
;         PG8_STAGE(PG8_SB(1, 0), cB + kstep, voffB); PG8_STAGE(PG8_SA(1, 0), cA + kstep, voffA); PG8_STAGE(PG8_SB(1, 1), cB + hstep + kstep, voffB);
;         PG8_WAIT_V(6); PG8_BAR;
.LBB0_952:
	s_add_u32 s68, s26, 0x200000
	s_addc_u32 s69, s27, 0
	s_lshl_b32 s5, s5, 5
	s_mov_b64 s[70:71], 0x80
	s_and_b32 s58, s5, 0x60
	s_add_i32 m0, s20, 0x18000
	v_lshl_add_u64 v[6:7], v[6:7], 0, s[70:71]
	s_lshl_b32 s7, s4, 13
	s_lshl_b32 s5, s58, 7
	s_waitcnt vmcnt(2)
	s_barrier
	global_load_lds_dwordx4 v[6:7], off
	v_lshl_add_u64 v[4:5], v[4:5], 0, s[70:71]
	s_add_i32 m0, s20, 0x1a000
	s_add_i32 s31, s20, 0x8000
	s_add_i32 s37, s20, 0xa000
	global_load_lds_dwordx4 v[4:5], off
	v_lshl_add_u64 v[0:1], v[0:1], 0, s[70:71]
	s_mov_b32 m0, s31
	s_add_u32 s56, s88, 0x40080
	global_load_lds_dwordx4 v[0:1], off
	v_mov_b32_e32 v232, v0
	v_mov_b32_e32 v233, v1
	v_lshl_add_u64 v[0:1], v[2:3], 0, s[70:71]
	s_mov_b32 m0, s37
	s_addc_u32 s57, s89, 0
	global_load_lds_dwordx4 v[0:1], off
	v_mov_b32_e32 v234, v0
	v_mov_b32_e32 v235, v1
	s_add_i32 m0, s20, 0x1c000
	v_lshl_add_u64 v[0:1], s[56:57], 0, v[130:131]
	global_load_lds_dwordx4 v[0:1], off
	v_lshl_add_u64 v[0:1], s[56:57], 0, v[134:135]
	s_add_i32 m0, s20, 0x1e000
	v_lshlrev_b32_e32 v3, 2, v160
	global_load_lds_dwordx4 v[0:1], off
	v_bfe_u32 v0, v201, 4, 2
	v_lshlrev_b32_e32 v1, 4, v0
	v_lshl_or_b32 v2, v160, 6, v1
	v_and_b32_e32 v3, 32, v3
	v_lshl_or_b32 v145, s4, 6, v160
	v_bitop3_b32 v2, v2, s7, v3 bitop3:0xde
	v_lshlrev_b32_e32 v3, 6, v201
	s_movk_i32 s4, 0x3c0
	v_and_or_b32 v1, v3, s4, v1
	v_lshlrev_b32_e32 v3, 2, v201
	v_and_b32_e32 v3, 32, v3
	v_bitop3_b32 v161, s5, v1, v3 bitop3:0xf6
	v_cmp_eq_u32_e64 s[4:5], 0, v0
	v_lshl_or_b32 v162, v0, 3, s58
	v_lshlrev_b32_e32 v0, 8, v201
	v_and_b32_e32 v0, 0x38000, v0
	v_lshlrev_b32_e32 v1, 11, v10
	v_or3_b32 v0, v8, v0, v1
	v_add_u32_e32 v136, v0, v9
	v_lshlrev_b32_e32 v0, 4, v11
	v_and_b32_e32 v0, 0x78000, v0
	s_waitcnt vmcnt(6)
	s_cmpk_lt_u32 s39, 0x100
	v_or3_b32 v0, v8, v0, v1
	s_cselect_b64 s[72:73], -1, 0
	v_add_u32_e32 v138, v0, v9
	s_add_i32 s39, 0, 0x10000
	s_add_i32 s56, 0, 0x14000
	v_mbcnt_lo_u32_b32 v0, -1, 0
	v_mov_b32_e32 v137, v131
	v_mov_b32_e32 v139, v131
	v_add_u32_e32 v163, s39, v161
	v_add_u32_e32 v164, s56, v161
	v_add_u32_e32 v165, 0, v2
	v_mov_b32_e32 v166, 0x358637bd
	s_movk_i32 s57, 0x1600
	v_mbcnt_hi_u32_b32 v167, -1, v0
	s_barrier
	s_branch .LBB0_955

; #define PG8_STAGE(bufoff, gbase, voff) do { _Pragma("unroll") for (int _i = 0; _i < 2; ++_i) \
;         __builtin_amdgcn_global_load_lds((const unsigned*)((const char*)(gbase) + (voff)[_i]), (PG8_LAS unsigned*)(lds + (bufoff) + ldsw + _i * 8192), 16, 0, 0); } while (0)
; #define PG8_LDA(dst, b, h) do { _Pragma("unroll") for (int m = 0; m < 4; ++m) _Pragma("unroll") for (int k = 0; k < 2; ++k) dst[m][k] = *(const PG8_LAS bf16x8*)(lds + PG8_SA(b, h) + aoff + m * 2048 + k * 1024); } while (0)
; #define PG8_LDB(dst, b, h) do { _Pragma("unroll") for (int n = 0; n < 2; ++n) _Pragma("unroll") for (int k = 0; k < 2; ++k) dst[n][k] = *(const PG8_LAS bf16x8*)(lds + PG8_SB(b, h) + boff + n * 2048 + k * 1024); } while (0)
; #define PG8_MMA(ai, bj, At, Bt) do { __builtin_amdgcn_s_setprio(1); _Pragma("unroll") for (int m = 0; m < 4; ++m) _Pragma("unroll") for (int n = 0; n < 2; ++n) _Pragma("unroll") for (int k = 0; k < 2; ++k) \
;         acc[ai][bj][m][n] = __builtin_amdgcn_mfma_f32_16x16x32_bf16(Bt[n][k], At[m][k], acc[ai][bj][m][n], 0, 0, 0); __builtin_amdgcn_s_setprio(0); } while (0)
; #define PG8_WAIT_V(n) asm volatile("s_waitcnt vmcnt(" #n ")" ::: "memory")
; #define PG8_BAR __builtin_amdgcn_s_barrier()
; template <class Epi, class Sched, bool ALIGN_EPI = false, bool SP2 = false>
; __device__ __forceinline__ void gemm_phase(PG8_LAS unsigned char* lds, const Gemm g, const Sched& S, const Epi& E) {
;     ...
;         for (int t = 0; t < nt; t += 2) {
;             const bool last = (t == nt - 2);
;             const char* a1 = cA + (size_t)(t + 1) * kstep;
;             const char* a2 = last ? nA : cA + (size_t)(t + 2) * kstep; const char* b2 = last ? nB : cB + (size_t)(t + 2) * kstep;
;             const char* a3 = a2 + kstep; const char* b3 = b2 + kstep;
;             if (last && has_next) S.a_ready(nxt);
;             if constexpr (SP2) {
;             PG8_LDB(B0, 0, 0); PG8_LDB(B1, 0, 1); PG8_SCHED; PG8_LDA(At, 0, 0); PG8_STAGE(PG8_SA(1, 1), a1 + hstep, voffA);
;             PG8_WAIT_V(8); PG8_WAIT_L(0); PG8_BAR; PG8_MMA(0, 0, At, B0); PG8_MMA(0, 1, At, B1); PG8_BAR; PG8_SCHED;
;             PG8_LDA(At, 0, 1); PG8_STAGE(PG8_SB(0, 0), b2, voffB); PG8_STAGE(PG8_SB(0, 1), b2 + hstep, voffB); PG8_STAGE(PG8_SA(0, 0), a2, voffA);
;             PG8_WAIT_V(8); PG8_WAIT_L(0); PG8_BAR; PG8_MMA(1, 0, At, B0); PG8_MMA(1, 1, At, B1); PG8_BAR; PG8_SCHED;
.LBB0_958:
	ds_read_b128 v[140:143], v163
	ds_read_b128 v[146:149], v163 offset:1024
	ds_read_b128 v[150:153], v163 offset:2048
	ds_read_b128 v[154:157], v163 offset:3072
	ds_read_b128 v[168:171], v164
	ds_read_b128 v[172:175], v164 offset:1024
	ds_read_b128 v[176:179], v164 offset:2048
	ds_read_b128 v[180:183], v164 offset:3072
	s_add_u32 s59, s86, 0xfffc0080
	s_addc_u32 s60, s87, -1
	s_cmp_eq_u32 s58, 12
	s_cselect_b32 s91, s7, s60
	s_cselect_b32 s90, s75, s59
	s_cselect_b32 s89, s77, vcc_hi
	s_cselect_b32 s88, s85, vcc_lo
	v_lshl_add_u64 v[158:159], s[86:87], 0, v[136:137]
	s_mov_b32 m0, s31
	s_nop 0
	global_load_lds_dwordx4 v[232:233], off
	s_mov_b32 m0, s37
	s_nop 0
	global_load_lds_dwordx4 v[234:235], off
	s_add_i32 m0, s20, 0xc000
	ds_read_b128 v[184:187], v165
	ds_read_b128 v[188:191], v165 offset:1024
	ds_read_b128 v[192:195], v165 offset:2048
	ds_read_b128 v[196:199], v165 offset:3072
	ds_read_b128 v[206:209], v165 offset:4096
	ds_read_b128 v[210:213], v165 offset:5120
	ds_read_b128 v[214:217], v165 offset:6144
	ds_read_b128 v[218:221], v165 offset:7168
	global_load_lds_dwordx4 v[158:159], off
	v_lshl_add_u64 v[158:159], s[86:87], 0, v[138:139]
	s_add_i32 m0, s20, 0xe000
	s_nop 0
	global_load_lds_dwordx4 v[158:159], off
	s_waitcnt vmcnt(8)
	s_waitcnt lgkmcnt(0)
	s_barrier
	s_setprio 1
	s_waitcnt lgkmcnt(0)
	v_mfma_f32_16x16x32_bf16 v[124:127], v[140:143], v[184:187], v[124:127]
	v_mfma_f32_16x16x32_bf16 v[120:123], v[150:153], v[184:187], v[120:123]
	v_mfma_f32_16x16x32_bf16 v[108:111], v[140:143], v[192:195], v[108:111]
	v_mfma_f32_16x16x32_bf16 v[104:107], v[150:153], v[192:195], v[104:107]
	v_mfma_f32_16x16x32_bf16 v[92:95], v[140:143], v[206:209], v[92:95]
	v_mfma_f32_16x16x32_bf16 v[88:91], v[150:153], v[206:209], v[88:91]
	v_mfma_f32_16x16x32_bf16 v[76:79], v[140:143], v[214:217], v[76:79]
	v_mfma_f32_16x16x32_bf16 v[72:75], v[150:153], v[214:217], v[72:75]
	v_mfma_f32_16x16x32_bf16 v[124:127], v[146:149], v[188:191], v[124:127]
	v_mfma_f32_16x16x32_bf16 v[120:123], v[154:157], v[188:191], v[120:123]
	v_mfma_f32_16x16x32_bf16 v[108:111], v[146:149], v[196:199], v[108:111]
	v_mfma_f32_16x16x32_bf16 v[104:107], v[154:157], v[196:199], v[104:107]
	v_mfma_f32_16x16x32_bf16 v[92:95], v[146:149], v[210:213], v[92:95]
	v_mfma_f32_16x16x32_bf16 v[88:91], v[154:157], v[210:213], v[88:91]
	v_mfma_f32_16x16x32_bf16 v[76:79], v[146:149], v[218:221], v[76:79]
	v_mfma_f32_16x16x32_bf16 v[72:75], v[154:157], v[218:221], v[72:75]
	s_setprio 0
	s_setprio 1
	v_mfma_f32_16x16x32_bf16 v[116:119], v[168:171], v[184:187], v[116:119]
	v_mfma_f32_16x16x32_bf16 v[112:115], v[176:179], v[184:187], v[112:115]
	v_mfma_f32_16x16x32_bf16 v[100:103], v[168:171], v[192:195], v[100:103]
	v_mfma_f32_16x16x32_bf16 v[96:99], v[176:179], v[192:195], v[96:99]
	v_mfma_f32_16x16x32_bf16 v[84:87], v[168:171], v[206:209], v[84:87]
	v_mfma_f32_16x16x32_bf16 v[80:83], v[176:179], v[206:209], v[80:83]
	v_mfma_f32_16x16x32_bf16 v[68:71], v[168:171], v[214:217], v[68:71]
	v_mfma_f32_16x16x32_bf16 v[64:67], v[176:179], v[214:217], v[64:67]
	v_mfma_f32_16x16x32_bf16 v[116:119], v[172:175], v[188:191], v[116:119]
	v_mfma_f32_16x16x32_bf16 v[112:115], v[180:183], v[188:191], v[112:115]
	v_mfma_f32_16x16x32_bf16 v[100:103], v[172:175], v[196:199], v[100:103]
	v_mfma_f32_16x16x32_bf16 v[96:99], v[180:183], v[196:199], v[96:99]
	v_mfma_f32_16x16x32_bf16 v[84:87], v[172:175], v[210:213], v[84:87]
	v_mfma_f32_16x16x32_bf16 v[80:83], v[180:183], v[210:213], v[80:83]
	v_mfma_f32_16x16x32_bf16 v[68:71], v[172:175], v[218:221], v[68:71]
	v_mfma_f32_16x16x32_bf16 v[64:67], v[180:183], v[218:221], v[64:67]
	s_setprio 0
	s_barrier
	s_add_i32 s59, s39, s11
	v_lshl_add_u64 v[158:159], s[88:89], 0, v[130:131]
	s_mov_b32 m0, s59
	ds_read_b128 v[184:187], v165 offset:16384
	ds_read_b128 v[188:191], v165 offset:17408
	ds_read_b128 v[192:195], v165 offset:18432
	ds_read_b128 v[196:199], v165 offset:19456
	ds_read_b128 v[206:209], v165 offset:20480
	ds_read_b128 v[210:213], v165 offset:21504
	ds_read_b128 v[214:217], v165 offset:22528
	ds_read_b128 v[218:221], v165 offset:23552
	global_load_lds_dwordx4 v[158:159], off
	s_add_i32 m0, s59, 0x2000
	s_add_u32 s60, s88, 0x40000
	v_lshl_add_u64 v[222:223], s[88:89], 0, v[134:135]
	s_addc_u32 s61, s89, 0
	s_add_i32 s59, s56, s11
	global_load_lds_dwordx4 v[222:223], off
	v_lshl_add_u64 v[224:225], s[60:61], 0, v[130:131]
	s_mov_b32 m0, s59
	v_lshl_add_u64 v[226:227], s[90:91], 0, v[132:133]
	global_load_lds_dwordx4 v[224:225], off
	v_lshl_add_u64 v[224:225], s[60:61], 0, v[134:135]
	s_add_i32 m0, s59, 0x2000
	s_nop 0
	global_load_lds_dwordx4 v[224:225], off
	v_lshl_add_u64 v[224:225], s[90:91], 0, v[128:129]
	v_mov_b32_e32 v236, v224
	v_mov_b32_e32 v237, v225
	v_mov_b32_e32 v238, v226
	v_mov_b32_e32 v239, v227
	s_waitcnt vmcnt(6)
	s_waitcnt lgkmcnt(0)
	s_barrier
; #define PG8_STAGE(bufoff, gbase, voff) do { _Pragma("unroll") for (int _i = 0; _i < 2; ++_i) \
;         __builtin_amdgcn_global_load_lds((const unsigned*)((const char*)(gbase) + (voff)[_i]), (PG8_LAS unsigned*)(lds + (bufoff) + ldsw + _i * 8192), 16, 0, 0); } while (0)
; #define PG8_LDA(dst, b, h) do { _Pragma("unroll") for (int m = 0; m < 4; ++m) _Pragma("unroll") for (int k = 0; k < 2; ++k) dst[m][k] = *(const PG8_LAS bf16x8*)(lds + PG8_SA(b, h) + aoff + m * 2048 + k * 1024); } while (0)
; #define PG8_LDB(dst, b, h) do { _Pragma("unroll") for (int n = 0; n < 2; ++n) _Pragma("unroll") for (int k = 0; k < 2; ++k) dst[n][k] = *(const PG8_LAS bf16x8*)(lds + PG8_SB(b, h) + boff + n * 2048 + k * 1024); } while (0)
; #define PG8_MMA(ai, bj, At, Bt) do { __builtin_amdgcn_s_setprio(1); _Pragma("unroll") for (int m = 0; m < 4; ++m) _Pragma("unroll") for (int n = 0; n < 2; ++n) _Pragma("unroll") for (int k = 0; k < 2; ++k) \
;         acc[ai][bj][m][n] = __builtin_amdgcn_mfma_f32_16x16x32_bf16(Bt[n][k], At[m][k], acc[ai][bj][m][n], 0, 0, 0); __builtin_amdgcn_s_setprio(0); } while (0)
; #define PG8_WAIT_V(n) asm volatile("s_waitcnt vmcnt(" #n ")" ::: "memory")
; #define PG8_WAIT_L(n) asm volatile("s_waitcnt lgkmcnt(" #n ")" ::: "memory")
; #define PG8_BAR __builtin_amdgcn_s_barrier()
; #define PG8_SCHED __builtin_amdgcn_sched_barrier(0)
; template <class Epi, class Sched, bool ALIGN_EPI = false, bool SP2 = false>
; __device__ __forceinline__ void gemm_phase(PG8_LAS unsigned char* lds, const Gemm g, const Sched& S, const Epi& E) {
;     ...
;             PG8_WAIT_V(8); PG8_WAIT_L(0); PG8_BAR; PG8_MMA(1, 0, At, B0); PG8_MMA(1, 1, At, B1); PG8_BAR; PG8_SCHED;
;             PG8_LDB(B0, 1, 0); PG8_LDB(B1, 1, 1); PG8_SCHED; PG8_LDA(At, 1, 0); PG8_STAGE(PG8_SA(0, 1), a2 + hstep, voffA);
;             PG8_WAIT_V(8); PG8_WAIT_L(0); PG8_BAR; PG8_MMA(0, 0, At, B0); PG8_MMA(0, 1, At, B1); PG8_BAR; PG8_SCHED;
	s_setprio 1
	s_waitcnt lgkmcnt(0)
	v_mfma_f32_16x16x32_bf16 v[60:63], v[140:143], v[184:187], v[60:63]
	v_mfma_f32_16x16x32_bf16 v[56:59], v[150:153], v[184:187], v[56:59]
	v_mfma_f32_16x16x32_bf16 v[44:47], v[140:143], v[192:195], v[44:47]
	v_mfma_f32_16x16x32_bf16 v[40:43], v[150:153], v[192:195], v[40:43]
	v_mfma_f32_16x16x32_bf16 v[28:31], v[140:143], v[206:209], v[28:31]
	v_mfma_f32_16x16x32_bf16 v[24:27], v[150:153], v[206:209], v[24:27]
	v_mfma_f32_16x16x32_bf16 v[12:15], v[140:143], v[214:217], v[12:15]
	v_mfma_f32_16x16x32_bf16 v[8:11], v[150:153], v[214:217], v[8:11]
	v_mfma_f32_16x16x32_bf16 v[60:63], v[146:149], v[188:191], v[60:63]
	v_mfma_f32_16x16x32_bf16 v[56:59], v[154:157], v[188:191], v[56:59]
	v_mfma_f32_16x16x32_bf16 v[44:47], v[146:149], v[196:199], v[44:47]
	v_mfma_f32_16x16x32_bf16 v[40:43], v[154:157], v[196:199], v[40:43]
	v_mfma_f32_16x16x32_bf16 v[28:31], v[146:149], v[210:213], v[28:31]
	v_mfma_f32_16x16x32_bf16 v[24:27], v[154:157], v[210:213], v[24:27]
	v_mfma_f32_16x16x32_bf16 v[12:15], v[146:149], v[218:221], v[12:15]
	v_mfma_f32_16x16x32_bf16 v[8:11], v[154:157], v[218:221], v[8:11]
	s_setprio 0
	s_setprio 1
	v_mfma_f32_16x16x32_bf16 v[52:55], v[168:171], v[184:187], v[52:55]
	v_mfma_f32_16x16x32_bf16 v[48:51], v[176:179], v[184:187], v[48:51]
	v_mfma_f32_16x16x32_bf16 v[36:39], v[168:171], v[192:195], v[36:39]
	v_mfma_f32_16x16x32_bf16 v[32:35], v[176:179], v[192:195], v[32:35]
	v_mfma_f32_16x16x32_bf16 v[20:23], v[168:171], v[206:209], v[20:23]
	v_mfma_f32_16x16x32_bf16 v[16:19], v[176:179], v[206:209], v[16:19]
	v_mfma_f32_16x16x32_bf16 v[4:7], v[168:171], v[214:217], v[4:7]
	v_mfma_f32_16x16x32_bf16 v[0:3], v[176:179], v[214:217], v[0:3]
	v_mfma_f32_16x16x32_bf16 v[52:55], v[172:175], v[188:191], v[52:55]
	v_mfma_f32_16x16x32_bf16 v[48:51], v[180:183], v[188:191], v[48:51]
	v_mfma_f32_16x16x32_bf16 v[36:39], v[172:175], v[196:199], v[36:39]
	v_mfma_f32_16x16x32_bf16 v[32:35], v[180:183], v[196:199], v[32:35]
	v_mfma_f32_16x16x32_bf16 v[20:23], v[172:175], v[210:213], v[20:23]
	v_mfma_f32_16x16x32_bf16 v[16:19], v[180:183], v[210:213], v[16:19]
	v_mfma_f32_16x16x32_bf16 v[4:7], v[172:175], v[218:221], v[4:7]
	v_mfma_f32_16x16x32_bf16 v[0:3], v[180:183], v[218:221], v[0:3]
	s_setprio 0
	s_barrier
	s_add_i32 s59, 0, 0x18000
	s_add_i32 s96, 0, 0x1c000
	v_add_u32_e32 v154, s59, v161
	v_add_u32_e32 v180, s96, v161
	ds_read_b128 v[140:143], v154
	ds_read_b128 v[146:149], v154 offset:1024
	ds_read_b128 v[150:153], v154 offset:2048
	ds_read_b128 v[154:157], v154 offset:3072
	ds_read_b128 v[168:171], v180
	ds_read_b128 v[172:175], v180 offset:1024
	ds_read_b128 v[176:179], v180 offset:2048
	ds_read_b128 v[180:183], v180 offset:3072
	s_add_u32 s60, s90, 0x40000
	s_addc_u32 s61, s91, 0
	s_mov_b32 m0, s20
	s_nop 0
	global_load_lds_dwordx4 v[236:237], off
	s_mov_b32 m0, s21
	s_nop 0
	global_load_lds_dwordx4 v[238:239], off
	s_mov_b32 m0, s28
	v_lshl_add_u64 v[228:229], s[60:61], 0, v[128:129]
	ds_read_b128 v[184:187], v165 offset:32768
	ds_read_b128 v[188:191], v165 offset:33792
	ds_read_b128 v[192:195], v165 offset:34816
	ds_read_b128 v[196:199], v165 offset:35840
	ds_read_b128 v[206:209], v165 offset:36864
	ds_read_b128 v[210:213], v165 offset:37888
	ds_read_b128 v[214:217], v165 offset:38912
	ds_read_b128 v[218:221], v165 offset:39936
	global_load_lds_dwordx4 v[228:229], off
	v_lshl_add_u64 v[228:229], s[60:61], 0, v[132:133]
	s_mov_b32 m0, s29
	s_nop 0
	global_load_lds_dwordx4 v[228:229], off
	s_waitcnt vmcnt(8)
	s_waitcnt lgkmcnt(0)
	s_barrier
	s_setprio 1
	s_waitcnt lgkmcnt(0)
	v_mfma_f32_16x16x32_bf16 v[124:127], v[140:143], v[184:187], v[124:127]
	v_mfma_f32_16x16x32_bf16 v[120:123], v[150:153], v[184:187], v[120:123]
	v_mfma_f32_16x16x32_bf16 v[108:111], v[140:143], v[192:195], v[108:111]
	v_mfma_f32_16x16x32_bf16 v[104:107], v[150:153], v[192:195], v[104:107]
	v_mfma_f32_16x16x32_bf16 v[92:95], v[140:143], v[206:209], v[92:95]
	v_mfma_f32_16x16x32_bf16 v[88:91], v[150:153], v[206:209], v[88:91]
	v_mfma_f32_16x16x32_bf16 v[76:79], v[140:143], v[214:217], v[76:79]
	v_mfma_f32_16x16x32_bf16 v[72:75], v[150:153], v[214:217], v[72:75]
	v_mfma_f32_16x16x32_bf16 v[124:127], v[146:149], v[188:191], v[124:127]
	v_mfma_f32_16x16x32_bf16 v[120:123], v[154:157], v[188:191], v[120:123]
	v_mfma_f32_16x16x32_bf16 v[108:111], v[146:149], v[196:199], v[108:111]
	v_mfma_f32_16x16x32_bf16 v[104:107], v[154:157], v[196:199], v[104:107]
	v_mfma_f32_16x16x32_bf16 v[92:95], v[146:149], v[210:213], v[92:95]
	v_mfma_f32_16x16x32_bf16 v[88:91], v[154:157], v[210:213], v[88:91]
	v_mfma_f32_16x16x32_bf16 v[76:79], v[146:149], v[218:221], v[76:79]
	v_mfma_f32_16x16x32_bf16 v[72:75], v[154:157], v[218:221], v[72:75]
	s_setprio 0
	s_setprio 1
	v_mfma_f32_16x16x32_bf16 v[116:119], v[168:171], v[184:187], v[116:119]
	v_mfma_f32_16x16x32_bf16 v[112:115], v[176:179], v[184:187], v[112:115]
	v_mfma_f32_16x16x32_bf16 v[100:103], v[168:171], v[192:195], v[100:103]
	v_mfma_f32_16x16x32_bf16 v[96:99], v[176:179], v[192:195], v[96:99]
	v_mfma_f32_16x16x32_bf16 v[84:87], v[168:171], v[206:209], v[84:87]
	v_mfma_f32_16x16x32_bf16 v[80:83], v[176:179], v[206:209], v[80:83]
	v_mfma_f32_16x16x32_bf16 v[68:71], v[168:171], v[214:217], v[68:71]
	v_mfma_f32_16x16x32_bf16 v[64:67], v[176:179], v[214:217], v[64:67]
	v_mfma_f32_16x16x32_bf16 v[116:119], v[172:175], v[188:191], v[116:119]
	v_mfma_f32_16x16x32_bf16 v[112:115], v[180:183], v[188:191], v[112:115]
	v_mfma_f32_16x16x32_bf16 v[100:103], v[172:175], v[196:199], v[100:103]
	v_mfma_f32_16x16x32_bf16 v[96:99], v[180:183], v[196:199], v[96:99]
	v_mfma_f32_16x16x32_bf16 v[84:87], v[172:175], v[210:213], v[84:87]
	v_mfma_f32_16x16x32_bf16 v[80:83], v[180:183], v[210:213], v[80:83]
	v_mfma_f32_16x16x32_bf16 v[68:71], v[172:175], v[218:221], v[68:71]
	v_mfma_f32_16x16x32_bf16 v[64:67], v[180:183], v[218:221], v[64:67]
	s_setprio 0
	s_barrier
; #define PG8_STAGE(bufoff, gbase, voff) do { _Pragma("unroll") for (int _i = 0; _i < 2; ++_i) \
;         __builtin_amdgcn_global_load_lds((const unsigned*)((const char*)(gbase) + (voff)[_i]), (PG8_LAS unsigned*)(lds + (bufoff) + ldsw + _i * 8192), 16, 0, 0); } while (0)
; #define PG8_LDA(dst, b, h) do { _Pragma("unroll") for (int m = 0; m < 4; ++m) _Pragma("unroll") for (int k = 0; k < 2; ++k) dst[m][k] = *(const PG8_LAS bf16x8*)(lds + PG8_SA(b, h) + aoff + m * 2048 + k * 1024); } while (0)
; #define PG8_MMA(ai, bj, At, Bt) do { __builtin_amdgcn_s_setprio(1); _Pragma("unroll") for (int m = 0; m < 4; ++m) _Pragma("unroll") for (int n = 0; n < 2; ++n) _Pragma("unroll") for (int k = 0; k < 2; ++k) \
;         acc[ai][bj][m][n] = __builtin_amdgcn_mfma_f32_16x16x32_bf16(Bt[n][k], At[m][k], acc[ai][bj][m][n], 0, 0, 0); __builtin_amdgcn_s_setprio(0); } while (0)
; #define PG8_WAIT_V(n) asm volatile("s_waitcnt vmcnt(" #n ")" ::: "memory")
; #define PG8_WAIT_L(n) asm volatile("s_waitcnt lgkmcnt(" #n ")" ::: "memory")
; #define PG8_BAR __builtin_amdgcn_s_barrier()
; #define PG8_SCHED __builtin_amdgcn_sched_barrier(0)
; template <class Epi, class Sched, bool ALIGN_EPI = false, bool SP2 = false>
; __device__ __forceinline__ void gemm_phase(PG8_LAS unsigned char* lds, const Gemm g, const Sched& S, const Epi& E) {
;     ...
;             PG8_LDA(At, 1, 1); PG8_STAGE(PG8_SB(1, 0), b3, voffB); PG8_STAGE(PG8_SB(1, 1), b3 + hstep, voffB); PG8_STAGE(PG8_SA(1, 0), a3, voffA);
;             PG8_WAIT_V(8); PG8_WAIT_L(0); PG8_BAR; PG8_MMA(1, 0, At, B0); PG8_MMA(1, 1, At, B1); PG8_BAR; PG8_SCHED;
	s_add_i32 s59, s59, s11
	v_lshl_add_u64 v[158:159], v[158:159], 0, s[70:71]
	s_mov_b32 m0, s59
	ds_read_b128 v[184:187], v165 offset:49152
	ds_read_b128 v[188:191], v165 offset:50176
	ds_read_b128 v[192:195], v165 offset:51200
	ds_read_b128 v[196:199], v165 offset:52224
	ds_read_b128 v[206:209], v165 offset:53248
	ds_read_b128 v[210:213], v165 offset:54272
	ds_read_b128 v[214:217], v165 offset:55296
	ds_read_b128 v[218:221], v165 offset:56320
	global_load_lds_dwordx4 v[158:159], off
	s_add_i32 m0, s59, 0x2000
	s_add_u32 s60, s88, 0x40080
	v_lshl_add_u64 v[158:159], v[222:223], 0, s[70:71]
	s_addc_u32 s61, s89, 0
	s_add_i32 s59, s96, s11
	global_load_lds_dwordx4 v[158:159], off
	v_lshl_add_u64 v[158:159], s[60:61], 0, v[130:131]
	s_mov_b32 m0, s59
	s_nop 0
	global_load_lds_dwordx4 v[158:159], off
	v_lshl_add_u64 v[158:159], s[60:61], 0, v[134:135]
	s_add_i32 m0, s59, 0x2000
	s_nop 0
	global_load_lds_dwordx4 v[158:159], off
	v_lshl_add_u64 v[158:159], v[224:225], 0, s[70:71]
	v_mov_b32_e32 v232, v158
	v_mov_b32_e32 v233, v159
	v_lshl_add_u64 v[158:159], v[226:227], 0, s[70:71]
	v_mov_b32_e32 v234, v158
	v_mov_b32_e32 v235, v159
	s_waitcnt vmcnt(6)
	s_waitcnt lgkmcnt(0)
	s_barrier
	s_setprio 1
	s_waitcnt lgkmcnt(0)
	v_mfma_f32_16x16x32_bf16 v[60:63], v[140:143], v[184:187], v[60:63]
	v_mfma_f32_16x16x32_bf16 v[56:59], v[150:153], v[184:187], v[56:59]
	v_mfma_f32_16x16x32_bf16 v[44:47], v[140:143], v[192:195], v[44:47]
	v_mfma_f32_16x16x32_bf16 v[40:43], v[150:153], v[192:195], v[40:43]
	v_mfma_f32_16x16x32_bf16 v[28:31], v[140:143], v[206:209], v[28:31]
	v_mfma_f32_16x16x32_bf16 v[24:27], v[150:153], v[206:209], v[24:27]
	v_mfma_f32_16x16x32_bf16 v[12:15], v[140:143], v[214:217], v[12:15]
	v_mfma_f32_16x16x32_bf16 v[8:11], v[150:153], v[214:217], v[8:11]
	v_mfma_f32_16x16x32_bf16 v[60:63], v[146:149], v[188:191], v[60:63]
	v_mfma_f32_16x16x32_bf16 v[56:59], v[154:157], v[188:191], v[56:59]
	v_mfma_f32_16x16x32_bf16 v[44:47], v[146:149], v[196:199], v[44:47]
	v_mfma_f32_16x16x32_bf16 v[40:43], v[154:157], v[196:199], v[40:43]
	v_mfma_f32_16x16x32_bf16 v[28:31], v[146:149], v[210:213], v[28:31]
	v_mfma_f32_16x16x32_bf16 v[24:27], v[154:157], v[210:213], v[24:27]
	v_mfma_f32_16x16x32_bf16 v[12:15], v[146:149], v[218:221], v[12:15]
	v_mfma_f32_16x16x32_bf16 v[8:11], v[154:157], v[218:221], v[8:11]
	s_setprio 0
	s_setprio 1
	v_mfma_f32_16x16x32_bf16 v[52:55], v[168:171], v[184:187], v[52:55]
	v_mfma_f32_16x16x32_bf16 v[48:51], v[176:179], v[184:187], v[48:51]
	v_mfma_f32_16x16x32_bf16 v[36:39], v[168:171], v[192:195], v[36:39]
	v_mfma_f32_16x16x32_bf16 v[32:35], v[176:179], v[192:195], v[32:35]
	v_mfma_f32_16x16x32_bf16 v[20:23], v[168:171], v[206:209], v[20:23]
	v_mfma_f32_16x16x32_bf16 v[16:19], v[176:179], v[206:209], v[16:19]
	v_mfma_f32_16x16x32_bf16 v[4:7], v[168:171], v[214:217], v[4:7]
	v_mfma_f32_16x16x32_bf16 v[0:3], v[176:179], v[214:217], v[0:3]
	v_mfma_f32_16x16x32_bf16 v[52:55], v[172:175], v[188:191], v[52:55]
	v_mfma_f32_16x16x32_bf16 v[48:51], v[180:183], v[188:191], v[48:51]
	v_mfma_f32_16x16x32_bf16 v[36:39], v[172:175], v[196:199], v[36:39]
	v_mfma_f32_16x16x32_bf16 v[32:35], v[180:183], v[196:199], v[32:35]
	v_mfma_f32_16x16x32_bf16 v[20:23], v[172:175], v[210:213], v[20:23]
	v_mfma_f32_16x16x32_bf16 v[16:19], v[180:183], v[210:213], v[16:19]
	v_mfma_f32_16x16x32_bf16 v[4:7], v[172:175], v[218:221], v[4:7]
	v_mfma_f32_16x16x32_bf16 v[0:3], v[180:183], v[218:221], v[0:3]
	s_setprio 0
	s_barrier
	s_add_i32 s58, s58, 2
	s_add_u32 s86, s86, 0x100
	s_addc_u32 s87, s87, 0
	s_add_u32 vcc_lo, vcc_lo, 0x100
	s_addc_u32 vcc_hi, vcc_hi, 0
	s_cmp_gt_u32 s58, 13
	s_cbranch_scc0 .LBB0_958
	s_and_b64 vcc, exec, s[72:73]
	s_cbranch_vccz .LBB0_961
	s_barrier

; #define PG8_STAGE(bufoff, gbase, voff) do { _Pragma("unroll") for (int _i = 0; _i < 2; ++_i) \
;         __builtin_amdgcn_global_load_lds((const unsigned*)((const char*)(gbase) + (voff)[_i]), (PG8_LAS unsigned*)(lds + (bufoff) + ldsw + _i * 8192), 16, 0, 0); } while (0)
; #define PG8_WAIT_V(n) asm volatile("s_waitcnt vmcnt(" #n ")" ::: "memory")
; #define PG8_BAR __builtin_amdgcn_s_barrier()
; template <class Epi, class Sched, bool ALIGN_EPI = false, bool SP2 = false>
; __device__ __forceinline__ void gemm_phase(PG8_LAS unsigned char* lds, const Gemm g, const Sched& S, const Epi& E) {
;     ...
;     const unsigned ldsw = (unsigned)wid * 1024u;
;     const int aoff = lds_byte(wr * 64 + fr, fq * 8), boff = lds_byte(wc * 32 + fr, fq * 8);
;     ...
;     const char* cA = (const char*)g.A + (size_t)cur.pm * tstep; const char* cB = (const char*)g.Bt + (size_t)cur.pn * tstep;
;     S.a_ready(cur);
;     if constexpr (SP2) {
;         PG8_STAGE(PG8_SB(0, 0), cB, voffB); PG8_STAGE(PG8_SB(0, 1), cB + hstep, voffB); PG8_STAGE(PG8_SA(0, 0), cA, voffA); PG8_STAGE(PG8_SA(0, 1), cA + hstep, voffA);
;         if (wr == 1) PG8_BAR;
;         PG8_WAIT_V(2); PG8_BAR;
;         PG8_STAGE(PG8_SB(1, 0), cB + kstep, voffB); PG8_STAGE(PG8_SA(1, 0), cA + kstep, voffA); PG8_STAGE(PG8_SB(1, 1), cB + hstep + kstep, voffB);
;         PG8_WAIT_V(6); PG8_BAR;
.LBB0_1209:
	s_add_u32 s6, s26, 0x140000
	s_addc_u32 s7, s27, 0
	s_lshl_b32 s3, s3, 5
	s_mov_b64 s[12:13], 0x80
	s_and_b32 s18, s3, 0x60
	s_add_i32 m0, s28, 0x18000
	v_lshl_add_u64 v[6:7], v[6:7], 0, s[12:13]
	s_lshl_b32 s15, s2, 13
	s_lshl_b32 s3, s18, 7
	s_waitcnt vmcnt(2)
	s_barrier
	global_load_lds_dwordx4 v[6:7], off
	v_lshl_add_u64 v[4:5], v[4:5], 0, s[12:13]
	s_add_i32 m0, s28, 0x1a000
	s_add_i32 s57, s28, 0x8000
	s_add_i32 s64, s28, 0xa000
	global_load_lds_dwordx4 v[4:5], off
	v_lshl_add_u64 v[0:1], v[0:1], 0, s[12:13]
	s_mov_b32 m0, s57
	s_add_u32 s16, s60, 0x40080
	global_load_lds_dwordx4 v[0:1], off
	v_mov_b32_e32 v232, v0
	v_mov_b32_e32 v233, v1
	v_lshl_add_u64 v[0:1], v[2:3], 0, s[12:13]
	s_mov_b32 m0, s64
	s_addc_u32 s17, s61, 0
	global_load_lds_dwordx4 v[0:1], off
	v_mov_b32_e32 v234, v0
	v_mov_b32_e32 v235, v1
	s_add_i32 m0, s28, 0x1c000
	v_lshl_add_u64 v[0:1], s[16:17], 0, v[130:131]
	global_load_lds_dwordx4 v[0:1], off
	v_lshl_add_u64 v[0:1], s[16:17], 0, v[134:135]
	s_add_i32 m0, s28, 0x1e000
	v_lshlrev_b32_e32 v3, 2, v201
	global_load_lds_dwordx4 v[0:1], off
	v_bfe_u32 v0, v201, 4, 2
	v_and_b32_e32 v1, 15, v201
	v_lshl_or_b32 v146, s2, 6, v1
	v_lshlrev_b32_e32 v2, 4, v0
	v_lshlrev_b32_e32 v4, 6, v201
	s_movk_i32 s2, 0x3c0
	v_lshl_or_b32 v1, v1, 6, v2
	v_and_b32_e32 v3, 32, v3
	v_and_or_b32 v2, v4, s2, v2
	v_bitop3_b32 v147, s3, v2, v3 bitop3:0xf6
	v_cmp_eq_u32_e64 s[2:3], 0, v0
	v_lshl_or_b32 v148, v0, 3, s18
	v_lshlrev_b32_e32 v0, 8, v201
	v_and_b32_e32 v0, 0x38000, v0
	v_lshlrev_b32_e32 v2, 11, v10
	v_or3_b32 v0, v8, v0, v2
	v_add_u32_e32 v136, v0, v9
	v_lshlrev_b32_e32 v0, 4, v11
	v_and_b32_e32 v0, 0x78000, v0
	s_waitcnt vmcnt(6)
	s_cmpk_lt_u32 s14, 0x100
	v_or3_b32 v0, v8, v0, v2
	v_bitop3_b32 v1, v1, s15, v3 bitop3:0xde
	s_cselect_b64 s[14:15], -1, 0
	v_add_u32_e32 v138, v0, v9
	s_add_i32 s66, 0, 0x10000
	s_add_i32 s67, 0, 0x14000
	v_mbcnt_lo_u32_b32 v0, -1, 0
	s_mov_b32 s65, 0x18000
	v_mov_b32_e32 v137, v131
	v_mov_b32_e32 v139, v131
	v_add_u32_e32 v149, s66, v147
	v_add_u32_e32 v150, s67, v147
	v_add_u32_e32 v151, 0, v1
	s_mov_b32 s68, 0x40000
	s_mov_b32 s69, 0x48000
	s_mov_b32 s70, 0x50000
	s_mov_b32 s71, 0x58000
	v_mbcnt_hi_u32_b32 v152, -1, v0
	s_barrier
	s_branch .LBB0_1212

; #define PG8_STAGE(bufoff, gbase, voff) do { _Pragma("unroll") for (int _i = 0; _i < 2; ++_i) \
;         __builtin_amdgcn_global_load_lds((const unsigned*)((const char*)(gbase) + (voff)[_i]), (PG8_LAS unsigned*)(lds + (bufoff) + ldsw + _i * 8192), 16, 0, 0); } while (0)
; #define PG8_LDA(dst, b, h) do { _Pragma("unroll") for (int m = 0; m < 4; ++m) _Pragma("unroll") for (int k = 0; k < 2; ++k) dst[m][k] = *(const PG8_LAS bf16x8*)(lds + PG8_SA(b, h) + aoff + m * 2048 + k * 1024); } while (0)
; #define PG8_LDB(dst, b, h) do { _Pragma("unroll") for (int n = 0; n < 2; ++n) _Pragma("unroll") for (int k = 0; k < 2; ++k) dst[n][k] = *(const PG8_LAS bf16x8*)(lds + PG8_SB(b, h) + boff + n * 2048 + k * 1024); } while (0)
; #define PG8_MMA(ai, bj, At, Bt) do { __builtin_amdgcn_s_setprio(1); _Pragma("unroll") for (int m = 0; m < 4; ++m) _Pragma("unroll") for (int n = 0; n < 2; ++n) _Pragma("unroll") for (int k = 0; k < 2; ++k) \
;         acc[ai][bj][m][n] = __builtin_amdgcn_mfma_f32_16x16x32_bf16(Bt[n][k], At[m][k], acc[ai][bj][m][n], 0, 0, 0); __builtin_amdgcn_s_setprio(0); } while (0)
; #define PG8_WAIT_V(n) asm volatile("s_waitcnt vmcnt(" #n ")" ::: "memory")
; #define PG8_BAR __builtin_amdgcn_s_barrier()
; template <class Epi, class Sched, bool ALIGN_EPI = false, bool SP2 = false>
; __device__ __forceinline__ void gemm_phase(PG8_LAS unsigned char* lds, const Gemm g, const Sched& S, const Epi& E) {
;     ...
;         for (int t = 0; t < nt; t += 2) {
;             const bool last = (t == nt - 2);
;             const char* a1 = cA + (size_t)(t + 1) * kstep;
;             const char* a2 = last ? nA : cA + (size_t)(t + 2) * kstep; const char* b2 = last ? nB : cB + (size_t)(t + 2) * kstep;
;             const char* a3 = a2 + kstep; const char* b3 = b2 + kstep;
;             if (last && has_next) S.a_ready(nxt);
;             if constexpr (SP2) {
;             PG8_LDB(B0, 0, 0); PG8_LDB(B1, 0, 1); PG8_SCHED; PG8_LDA(At, 0, 0); PG8_STAGE(PG8_SA(1, 1), a1 + hstep, voffA);
;             PG8_WAIT_V(8); PG8_WAIT_L(0); PG8_BAR; PG8_MMA(0, 0, At, B0); PG8_MMA(0, 1, At, B1); PG8_BAR; PG8_SCHED;
;             PG8_LDA(At, 0, 1); PG8_STAGE(PG8_SB(0, 0), b2, voffB); PG8_STAGE(PG8_SB(0, 1), b2 + hstep, voffB); PG8_STAGE(PG8_SA(0, 0), a2, voffA);
;             PG8_WAIT_V(8); PG8_WAIT_L(0); PG8_BAR; PG8_MMA(1, 0, At, B0); PG8_MMA(1, 1, At, B1); PG8_BAR; PG8_SCHED;
.LBB0_1215:
	ds_read_b128 v[140:143], v149
	ds_read_b128 v[154:157], v149 offset:1024
	ds_read_b128 v[158:161], v149 offset:2048
	ds_read_b128 v[162:165], v149 offset:3072
	ds_read_b128 v[166:169], v150
	ds_read_b128 v[170:173], v150 offset:1024
	ds_read_b128 v[174:177], v150 offset:2048
	ds_read_b128 v[178:181], v150 offset:3072
	s_add_u32 s60, s58, 0xfffc0080
	s_addc_u32 s61, s59, -1
	s_cmp_eq_u32 s75, 12
	s_cselect_b32 s63, s17, s61
	s_cselect_b32 s62, s51, s60
	s_cselect_b32 s61, s19, s74
	s_cselect_b32 s60, s72, s73
	v_lshl_add_u64 v[144:145], s[58:59], 0, v[136:137]
	s_mov_b32 m0, s57
	s_nop 0
	global_load_lds_dwordx4 v[232:233], off
	s_mov_b32 m0, s64
	s_nop 0
	global_load_lds_dwordx4 v[234:235], off
	s_add_i32 m0, s28, 0xc000
	ds_read_b128 v[182:185], v151
	ds_read_b128 v[186:189], v151 offset:1024
	ds_read_b128 v[190:193], v151 offset:2048
	ds_read_b128 v[194:197], v151 offset:3072
	ds_read_b128 v[202:205], v151 offset:4096
	ds_read_b128 v[206:209], v151 offset:5120
	ds_read_b128 v[210:213], v151 offset:6144
	ds_read_b128 v[214:217], v151 offset:7168
	global_load_lds_dwordx4 v[144:145], off
	v_lshl_add_u64 v[144:145], s[58:59], 0, v[138:139]
	s_add_i32 m0, s28, 0xe000
	s_nop 0
	global_load_lds_dwordx4 v[144:145], off
	s_waitcnt vmcnt(8)
	s_waitcnt lgkmcnt(0)
	s_barrier
	s_setprio 1
	s_waitcnt lgkmcnt(0)
	v_mfma_f32_16x16x32_bf16 v[124:127], v[140:143], v[182:185], v[124:127]
	v_mfma_f32_16x16x32_bf16 v[120:123], v[158:161], v[182:185], v[120:123]
	v_mfma_f32_16x16x32_bf16 v[108:111], v[140:143], v[190:193], v[108:111]
	v_mfma_f32_16x16x32_bf16 v[104:107], v[158:161], v[190:193], v[104:107]
	v_mfma_f32_16x16x32_bf16 v[96:99], v[140:143], v[202:205], v[96:99]
	v_mfma_f32_16x16x32_bf16 v[88:91], v[158:161], v[202:205], v[88:91]
	v_mfma_f32_16x16x32_bf16 v[80:83], v[140:143], v[210:213], v[80:83]
	v_mfma_f32_16x16x32_bf16 v[72:75], v[158:161], v[210:213], v[72:75]
	v_mfma_f32_16x16x32_bf16 v[124:127], v[154:157], v[186:189], v[124:127]
	v_mfma_f32_16x16x32_bf16 v[120:123], v[162:165], v[186:189], v[120:123]
	v_mfma_f32_16x16x32_bf16 v[108:111], v[154:157], v[194:197], v[108:111]
	v_mfma_f32_16x16x32_bf16 v[104:107], v[162:165], v[194:197], v[104:107]
	v_mfma_f32_16x16x32_bf16 v[96:99], v[154:157], v[206:209], v[96:99]
	v_mfma_f32_16x16x32_bf16 v[88:91], v[162:165], v[206:209], v[88:91]
	v_mfma_f32_16x16x32_bf16 v[80:83], v[154:157], v[214:217], v[80:83]
	v_mfma_f32_16x16x32_bf16 v[72:75], v[162:165], v[214:217], v[72:75]
	s_setprio 0
	s_setprio 1
	v_mfma_f32_16x16x32_bf16 v[116:119], v[166:169], v[182:185], v[116:119]
	v_mfma_f32_16x16x32_bf16 v[112:115], v[174:177], v[182:185], v[112:115]
	v_mfma_f32_16x16x32_bf16 v[100:103], v[166:169], v[190:193], v[100:103]
	v_mfma_f32_16x16x32_bf16 v[92:95], v[174:177], v[190:193], v[92:95]
	v_mfma_f32_16x16x32_bf16 v[84:87], v[166:169], v[202:205], v[84:87]
	v_mfma_f32_16x16x32_bf16 v[76:79], v[174:177], v[202:205], v[76:79]
	v_mfma_f32_16x16x32_bf16 v[68:71], v[166:169], v[210:213], v[68:71]
	v_mfma_f32_16x16x32_bf16 v[64:67], v[174:177], v[210:213], v[64:67]
	v_mfma_f32_16x16x32_bf16 v[116:119], v[170:173], v[186:189], v[116:119]
	v_mfma_f32_16x16x32_bf16 v[112:115], v[178:181], v[186:189], v[112:115]
	v_mfma_f32_16x16x32_bf16 v[100:103], v[170:173], v[194:197], v[100:103]
	v_mfma_f32_16x16x32_bf16 v[92:95], v[178:181], v[194:197], v[92:95]
	v_mfma_f32_16x16x32_bf16 v[84:87], v[170:173], v[206:209], v[84:87]
	v_mfma_f32_16x16x32_bf16 v[76:79], v[178:181], v[206:209], v[76:79]
	v_mfma_f32_16x16x32_bf16 v[68:71], v[170:173], v[214:217], v[68:71]
	v_mfma_f32_16x16x32_bf16 v[64:67], v[178:181], v[214:217], v[64:67]
	s_setprio 0
	s_barrier
	s_add_i32 s76, s66, s21
	v_lshl_add_u64 v[144:145], s[60:61], 0, v[130:131]
	s_mov_b32 m0, s76
	ds_read_b128 v[182:185], v151 offset:16384
	ds_read_b128 v[186:189], v151 offset:17408
	ds_read_b128 v[190:193], v151 offset:18432
	ds_read_b128 v[194:197], v151 offset:19456
	ds_read_b128 v[202:205], v151 offset:20480
	ds_read_b128 v[206:209], v151 offset:21504
	ds_read_b128 v[210:213], v151 offset:22528
	ds_read_b128 v[214:217], v151 offset:23552
	global_load_lds_dwordx4 v[144:145], off
	s_add_i32 m0, s76, 0x2000
	s_add_u32 s76, s60, 0x40000
	v_lshl_add_u64 v[198:199], s[60:61], 0, v[134:135]
	s_addc_u32 s77, s61, 0
	s_add_i32 s78, s67, s21
	global_load_lds_dwordx4 v[198:199], off
	v_lshl_add_u64 v[218:219], s[76:77], 0, v[130:131]
	s_mov_b32 m0, s78
	v_lshl_add_u64 v[220:221], s[62:63], 0, v[132:133]
	global_load_lds_dwordx4 v[218:219], off
	v_lshl_add_u64 v[218:219], s[76:77], 0, v[134:135]
	s_add_i32 m0, s78, 0x2000
	s_nop 0
	global_load_lds_dwordx4 v[218:219], off
	v_lshl_add_u64 v[218:219], s[62:63], 0, v[128:129]
	v_mov_b32_e32 v236, v218
	v_mov_b32_e32 v237, v219
	v_mov_b32_e32 v238, v220
	v_mov_b32_e32 v239, v221
	s_waitcnt vmcnt(6)
	s_waitcnt lgkmcnt(0)
	s_barrier
; #define PG8_STAGE(bufoff, gbase, voff) do { _Pragma("unroll") for (int _i = 0; _i < 2; ++_i) \
;         __builtin_amdgcn_global_load_lds((const unsigned*)((const char*)(gbase) + (voff)[_i]), (PG8_LAS unsigned*)(lds + (bufoff) + ldsw + _i * 8192), 16, 0, 0); } while (0)
; #define PG8_LDA(dst, b, h) do { _Pragma("unroll") for (int m = 0; m < 4; ++m) _Pragma("unroll") for (int k = 0; k < 2; ++k) dst[m][k] = *(const PG8_LAS bf16x8*)(lds + PG8_SA(b, h) + aoff + m * 2048 + k * 1024); } while (0)
; #define PG8_LDB(dst, b, h) do { _Pragma("unroll") for (int n = 0; n < 2; ++n) _Pragma("unroll") for (int k = 0; k < 2; ++k) dst[n][k] = *(const PG8_LAS bf16x8*)(lds + PG8_SB(b, h) + boff + n * 2048 + k * 1024); } while (0)
; #define PG8_MMA(ai, bj, At, Bt) do { __builtin_amdgcn_s_setprio(1); _Pragma("unroll") for (int m = 0; m < 4; ++m) _Pragma("unroll") for (int n = 0; n < 2; ++n) _Pragma("unroll") for (int k = 0; k < 2; ++k) \
;         acc[ai][bj][m][n] = __builtin_amdgcn_mfma_f32_16x16x32_bf16(Bt[n][k], At[m][k], acc[ai][bj][m][n], 0, 0, 0); __builtin_amdgcn_s_setprio(0); } while (0)
; #define PG8_WAIT_V(n) asm volatile("s_waitcnt vmcnt(" #n ")" ::: "memory")
; #define PG8_WAIT_L(n) asm volatile("s_waitcnt lgkmcnt(" #n ")" ::: "memory")
; #define PG8_BAR __builtin_amdgcn_s_barrier()
; #define PG8_SCHED __builtin_amdgcn_sched_barrier(0)
; template <class Epi, class Sched, bool ALIGN_EPI = false, bool SP2 = false>
; __device__ __forceinline__ void gemm_phase(PG8_LAS unsigned char* lds, const Gemm g, const Sched& S, const Epi& E) {
;     ...
;             PG8_WAIT_V(8); PG8_WAIT_L(0); PG8_BAR; PG8_MMA(1, 0, At, B0); PG8_MMA(1, 1, At, B1); PG8_BAR; PG8_SCHED;
;             PG8_LDB(B0, 1, 0); PG8_LDB(B1, 1, 1); PG8_SCHED; PG8_LDA(At, 1, 0); PG8_STAGE(PG8_SA(0, 1), a2 + hstep, voffA);
;             PG8_WAIT_V(8); PG8_WAIT_L(0); PG8_BAR; PG8_MMA(0, 0, At, B0); PG8_MMA(0, 1, At, B1); PG8_BAR; PG8_SCHED;
	s_setprio 1
	s_waitcnt lgkmcnt(0)
	v_mfma_f32_16x16x32_bf16 v[60:63], v[140:143], v[182:185], v[60:63]
	v_mfma_f32_16x16x32_bf16 v[56:59], v[158:161], v[182:185], v[56:59]
	v_mfma_f32_16x16x32_bf16 v[48:51], v[140:143], v[190:193], v[48:51]
	v_mfma_f32_16x16x32_bf16 v[40:43], v[158:161], v[190:193], v[40:43]
	v_mfma_f32_16x16x32_bf16 v[32:35], v[140:143], v[202:205], v[32:35]
	v_mfma_f32_16x16x32_bf16 v[24:27], v[158:161], v[202:205], v[24:27]
	v_mfma_f32_16x16x32_bf16 v[16:19], v[140:143], v[210:213], v[16:19]
	v_mfma_f32_16x16x32_bf16 v[8:11], v[158:161], v[210:213], v[8:11]
	v_mfma_f32_16x16x32_bf16 v[60:63], v[154:157], v[186:189], v[60:63]
	v_mfma_f32_16x16x32_bf16 v[56:59], v[162:165], v[186:189], v[56:59]
	v_mfma_f32_16x16x32_bf16 v[48:51], v[154:157], v[194:197], v[48:51]
	v_mfma_f32_16x16x32_bf16 v[40:43], v[162:165], v[194:197], v[40:43]
	v_mfma_f32_16x16x32_bf16 v[32:35], v[154:157], v[206:209], v[32:35]
	v_mfma_f32_16x16x32_bf16 v[24:27], v[162:165], v[206:209], v[24:27]
	v_mfma_f32_16x16x32_bf16 v[16:19], v[154:157], v[214:217], v[16:19]
	v_mfma_f32_16x16x32_bf16 v[8:11], v[162:165], v[214:217], v[8:11]
	s_setprio 0
	s_setprio 1
	v_mfma_f32_16x16x32_bf16 v[52:55], v[166:169], v[182:185], v[52:55]
	v_mfma_f32_16x16x32_bf16 v[44:47], v[174:177], v[182:185], v[44:47]
	v_mfma_f32_16x16x32_bf16 v[36:39], v[166:169], v[190:193], v[36:39]
	v_mfma_f32_16x16x32_bf16 v[28:31], v[174:177], v[190:193], v[28:31]
	v_mfma_f32_16x16x32_bf16 v[20:23], v[166:169], v[202:205], v[20:23]
	v_mfma_f32_16x16x32_bf16 v[12:15], v[174:177], v[202:205], v[12:15]
	v_mfma_f32_16x16x32_bf16 v[4:7], v[166:169], v[210:213], v[4:7]
	v_mfma_f32_16x16x32_bf16 v[0:3], v[174:177], v[210:213], v[0:3]
	v_mfma_f32_16x16x32_bf16 v[52:55], v[170:173], v[186:189], v[52:55]
	v_mfma_f32_16x16x32_bf16 v[44:47], v[178:181], v[186:189], v[44:47]
	v_mfma_f32_16x16x32_bf16 v[36:39], v[170:173], v[194:197], v[36:39]
	v_mfma_f32_16x16x32_bf16 v[28:31], v[178:181], v[194:197], v[28:31]
	v_mfma_f32_16x16x32_bf16 v[20:23], v[170:173], v[206:209], v[20:23]
	v_mfma_f32_16x16x32_bf16 v[12:15], v[178:181], v[206:209], v[12:15]
	v_mfma_f32_16x16x32_bf16 v[4:7], v[170:173], v[214:217], v[4:7]
	v_mfma_f32_16x16x32_bf16 v[0:3], v[178:181], v[214:217], v[0:3]
	s_setprio 0
	s_barrier
	s_add_i32 s76, 0, 0x18000
	v_add_u32_e32 v153, s76, v147
	s_add_i32 s77, 0, 0x1c000
	ds_read_b128 v[140:143], v153
	ds_read_b128 v[154:157], v153 offset:1024
	ds_read_b128 v[158:161], v153 offset:2048
	ds_read_b128 v[162:165], v153 offset:3072
	v_add_u32_e32 v153, s77, v147
	ds_read_b128 v[166:169], v153
	ds_read_b128 v[170:173], v153 offset:1024
	ds_read_b128 v[174:177], v153 offset:2048
	ds_read_b128 v[178:181], v153 offset:3072
	s_add_u32 s62, s62, 0x40000
	s_addc_u32 s63, s63, 0
	s_mov_b32 m0, s28
	s_nop 0
	global_load_lds_dwordx4 v[236:237], off
	s_mov_b32 m0, s29
	s_nop 0
	global_load_lds_dwordx4 v[238:239], off
	s_mov_b32 m0, s30
	v_lshl_add_u64 v[222:223], s[62:63], 0, v[128:129]
	ds_read_b128 v[182:185], v151 offset:32768
	ds_read_b128 v[186:189], v151 offset:33792
	ds_read_b128 v[190:193], v151 offset:34816
	ds_read_b128 v[194:197], v151 offset:35840
	ds_read_b128 v[202:205], v151 offset:36864
	ds_read_b128 v[206:209], v151 offset:37888
	ds_read_b128 v[210:213], v151 offset:38912
	ds_read_b128 v[214:217], v151 offset:39936
	global_load_lds_dwordx4 v[222:223], off
	v_lshl_add_u64 v[222:223], s[62:63], 0, v[132:133]
	s_mov_b32 m0, s31
	s_nop 0
	global_load_lds_dwordx4 v[222:223], off
	s_waitcnt vmcnt(8)
	s_waitcnt lgkmcnt(0)
	s_barrier
	s_setprio 1
	s_waitcnt lgkmcnt(0)
	v_mfma_f32_16x16x32_bf16 v[124:127], v[140:143], v[182:185], v[124:127]
	v_mfma_f32_16x16x32_bf16 v[120:123], v[158:161], v[182:185], v[120:123]
	v_mfma_f32_16x16x32_bf16 v[108:111], v[140:143], v[190:193], v[108:111]
	v_mfma_f32_16x16x32_bf16 v[104:107], v[158:161], v[190:193], v[104:107]
	v_mfma_f32_16x16x32_bf16 v[96:99], v[140:143], v[202:205], v[96:99]
	v_mfma_f32_16x16x32_bf16 v[88:91], v[158:161], v[202:205], v[88:91]
	v_mfma_f32_16x16x32_bf16 v[80:83], v[140:143], v[210:213], v[80:83]
	v_mfma_f32_16x16x32_bf16 v[72:75], v[158:161], v[210:213], v[72:75]
	v_mfma_f32_16x16x32_bf16 v[124:127], v[154:157], v[186:189], v[124:127]
	v_mfma_f32_16x16x32_bf16 v[120:123], v[162:165], v[186:189], v[120:123]
	v_mfma_f32_16x16x32_bf16 v[108:111], v[154:157], v[194:197], v[108:111]
	v_mfma_f32_16x16x32_bf16 v[104:107], v[162:165], v[194:197], v[104:107]
	v_mfma_f32_16x16x32_bf16 v[96:99], v[154:157], v[206:209], v[96:99]
	v_mfma_f32_16x16x32_bf16 v[88:91], v[162:165], v[206:209], v[88:91]
	v_mfma_f32_16x16x32_bf16 v[80:83], v[154:157], v[214:217], v[80:83]
	v_mfma_f32_16x16x32_bf16 v[72:75], v[162:165], v[214:217], v[72:75]
	s_setprio 0
	s_setprio 1
	v_mfma_f32_16x16x32_bf16 v[116:119], v[166:169], v[182:185], v[116:119]
	v_mfma_f32_16x16x32_bf16 v[112:115], v[174:177], v[182:185], v[112:115]
	v_mfma_f32_16x16x32_bf16 v[100:103], v[166:169], v[190:193], v[100:103]
	v_mfma_f32_16x16x32_bf16 v[92:95], v[174:177], v[190:193], v[92:95]
	v_mfma_f32_16x16x32_bf16 v[84:87], v[166:169], v[202:205], v[84:87]
	v_mfma_f32_16x16x32_bf16 v[76:79], v[174:177], v[202:205], v[76:79]
	v_mfma_f32_16x16x32_bf16 v[68:71], v[166:169], v[210:213], v[68:71]
	v_mfma_f32_16x16x32_bf16 v[64:67], v[174:177], v[210:213], v[64:67]
	v_mfma_f32_16x16x32_bf16 v[116:119], v[170:173], v[186:189], v[116:119]
	v_mfma_f32_16x16x32_bf16 v[112:115], v[178:181], v[186:189], v[112:115]
	v_mfma_f32_16x16x32_bf16 v[100:103], v[170:173], v[194:197], v[100:103]
	v_mfma_f32_16x16x32_bf16 v[92:95], v[178:181], v[194:197], v[92:95]
	v_mfma_f32_16x16x32_bf16 v[84:87], v[170:173], v[206:209], v[84:87]
	v_mfma_f32_16x16x32_bf16 v[76:79], v[178:181], v[206:209], v[76:79]
	v_mfma_f32_16x16x32_bf16 v[68:71], v[170:173], v[214:217], v[68:71]
	v_mfma_f32_16x16x32_bf16 v[64:67], v[178:181], v[214:217], v[64:67]
	s_setprio 0
	s_barrier
; #define PG8_STAGE(bufoff, gbase, voff) do { _Pragma("unroll") for (int _i = 0; _i < 2; ++_i) \
;         __builtin_amdgcn_global_load_lds((const unsigned*)((const char*)(gbase) + (voff)[_i]), (PG8_LAS unsigned*)(lds + (bufoff) + ldsw + _i * 8192), 16, 0, 0); } while (0)
; #define PG8_LDA(dst, b, h) do { _Pragma("unroll") for (int m = 0; m < 4; ++m) _Pragma("unroll") for (int k = 0; k < 2; ++k) dst[m][k] = *(const PG8_LAS bf16x8*)(lds + PG8_SA(b, h) + aoff + m * 2048 + k * 1024); } while (0)
; #define PG8_MMA(ai, bj, At, Bt) do { __builtin_amdgcn_s_setprio(1); _Pragma("unroll") for (int m = 0; m < 4; ++m) _Pragma("unroll") for (int n = 0; n < 2; ++n) _Pragma("unroll") for (int k = 0; k < 2; ++k) \
;         acc[ai][bj][m][n] = __builtin_amdgcn_mfma_f32_16x16x32_bf16(Bt[n][k], At[m][k], acc[ai][bj][m][n], 0, 0, 0); __builtin_amdgcn_s_setprio(0); } while (0)
; #define PG8_WAIT_V(n) asm volatile("s_waitcnt vmcnt(" #n ")" ::: "memory")
; #define PG8_WAIT_L(n) asm volatile("s_waitcnt lgkmcnt(" #n ")" ::: "memory")
; #define PG8_BAR __builtin_amdgcn_s_barrier()
; #define PG8_SCHED __builtin_amdgcn_sched_barrier(0)
; template <class Epi, class Sched, bool ALIGN_EPI = false, bool SP2 = false>
; __device__ __forceinline__ void gemm_phase(PG8_LAS unsigned char* lds, const Gemm g, const Sched& S, const Epi& E) {
;     ...
;             PG8_LDA(At, 1, 1); PG8_STAGE(PG8_SB(1, 0), b3, voffB); PG8_STAGE(PG8_SB(1, 1), b3 + hstep, voffB); PG8_STAGE(PG8_SA(1, 0), a3, voffA);
;             PG8_WAIT_V(8); PG8_WAIT_L(0); PG8_BAR; PG8_MMA(1, 0, At, B0); PG8_MMA(1, 1, At, B1); PG8_BAR; PG8_SCHED;
	s_add_i32 s62, s76, s21
	v_lshl_add_u64 v[144:145], v[144:145], 0, s[12:13]
	s_mov_b32 m0, s62
	ds_read_b128 v[182:185], v151 offset:49152
	ds_read_b128 v[186:189], v151 offset:50176
	ds_read_b128 v[190:193], v151 offset:51200
	ds_read_b128 v[194:197], v151 offset:52224
	ds_read_b128 v[202:205], v151 offset:53248
	ds_read_b128 v[206:209], v151 offset:54272
	ds_read_b128 v[210:213], v151 offset:55296
	ds_read_b128 v[214:217], v151 offset:56320
	global_load_lds_dwordx4 v[144:145], off
	s_add_i32 m0, s62, 0x2000
	s_add_u32 s60, s60, 0x40080
	v_lshl_add_u64 v[144:145], v[198:199], 0, s[12:13]
	s_addc_u32 s61, s61, 0
	s_add_i32 s62, s77, s21
	global_load_lds_dwordx4 v[144:145], off
	v_lshl_add_u64 v[144:145], s[60:61], 0, v[130:131]
	s_mov_b32 m0, s62
	s_nop 0
	global_load_lds_dwordx4 v[144:145], off
	v_lshl_add_u64 v[144:145], s[60:61], 0, v[134:135]
	s_add_i32 m0, s62, 0x2000
	s_nop 0
	global_load_lds_dwordx4 v[144:145], off
	v_lshl_add_u64 v[144:145], v[218:219], 0, s[12:13]
	v_mov_b32_e32 v232, v144
	v_mov_b32_e32 v233, v145
	v_lshl_add_u64 v[144:145], v[220:221], 0, s[12:13]
	v_mov_b32_e32 v234, v144
	v_mov_b32_e32 v235, v145
	s_waitcnt vmcnt(6)
	s_waitcnt lgkmcnt(0)
	s_barrier
	s_setprio 1
	s_waitcnt lgkmcnt(0)
	v_mfma_f32_16x16x32_bf16 v[60:63], v[140:143], v[182:185], v[60:63]
	v_mfma_f32_16x16x32_bf16 v[56:59], v[158:161], v[182:185], v[56:59]
	v_mfma_f32_16x16x32_bf16 v[48:51], v[140:143], v[190:193], v[48:51]
	v_mfma_f32_16x16x32_bf16 v[40:43], v[158:161], v[190:193], v[40:43]
	v_mfma_f32_16x16x32_bf16 v[32:35], v[140:143], v[202:205], v[32:35]
	v_mfma_f32_16x16x32_bf16 v[24:27], v[158:161], v[202:205], v[24:27]
	v_mfma_f32_16x16x32_bf16 v[16:19], v[140:143], v[210:213], v[16:19]
	v_mfma_f32_16x16x32_bf16 v[8:11], v[158:161], v[210:213], v[8:11]
	v_mfma_f32_16x16x32_bf16 v[60:63], v[154:157], v[186:189], v[60:63]
	v_mfma_f32_16x16x32_bf16 v[56:59], v[162:165], v[186:189], v[56:59]
	v_mfma_f32_16x16x32_bf16 v[48:51], v[154:157], v[194:197], v[48:51]
	v_mfma_f32_16x16x32_bf16 v[40:43], v[162:165], v[194:197], v[40:43]
	v_mfma_f32_16x16x32_bf16 v[32:35], v[154:157], v[206:209], v[32:35]
	v_mfma_f32_16x16x32_bf16 v[24:27], v[162:165], v[206:209], v[24:27]
	v_mfma_f32_16x16x32_bf16 v[16:19], v[154:157], v[214:217], v[16:19]
	v_mfma_f32_16x16x32_bf16 v[8:11], v[162:165], v[214:217], v[8:11]
	s_setprio 0
	s_setprio 1
	v_mfma_f32_16x16x32_bf16 v[52:55], v[166:169], v[182:185], v[52:55]
	v_mfma_f32_16x16x32_bf16 v[44:47], v[174:177], v[182:185], v[44:47]
	v_mfma_f32_16x16x32_bf16 v[36:39], v[166:169], v[190:193], v[36:39]
	v_mfma_f32_16x16x32_bf16 v[28:31], v[174:177], v[190:193], v[28:31]
	v_mfma_f32_16x16x32_bf16 v[20:23], v[166:169], v[202:205], v[20:23]
	v_mfma_f32_16x16x32_bf16 v[12:15], v[174:177], v[202:205], v[12:15]
	v_mfma_f32_16x16x32_bf16 v[4:7], v[166:169], v[210:213], v[4:7]
	v_mfma_f32_16x16x32_bf16 v[0:3], v[174:177], v[210:213], v[0:3]
	v_mfma_f32_16x16x32_bf16 v[52:55], v[170:173], v[186:189], v[52:55]
	v_mfma_f32_16x16x32_bf16 v[44:47], v[178:181], v[186:189], v[44:47]
	v_mfma_f32_16x16x32_bf16 v[36:39], v[170:173], v[194:197], v[36:39]
	v_mfma_f32_16x16x32_bf16 v[28:31], v[178:181], v[194:197], v[28:31]
	v_mfma_f32_16x16x32_bf16 v[20:23], v[170:173], v[206:209], v[20:23]
	v_mfma_f32_16x16x32_bf16 v[12:15], v[178:181], v[206:209], v[12:15]
	v_mfma_f32_16x16x32_bf16 v[4:7], v[170:173], v[214:217], v[4:7]
	v_mfma_f32_16x16x32_bf16 v[0:3], v[178:181], v[214:217], v[0:3]
	s_setprio 0
	s_barrier
	s_add_i32 s75, s75, 2
	s_add_u32 s58, s58, 0x100
	s_addc_u32 s59, s59, 0
	s_add_u32 s73, s73, 0x100
	s_addc_u32 s74, s74, 0
	s_cmp_gt_u32 s75, 13
	s_cbranch_scc0 .LBB0_1215
	s_and_b64 vcc, exec, s[14:15]
	s_cbranch_vccz .LBB0_1218
	s_barrier

; #define PG8_STAGE(bufoff, gbase, voff) do { _Pragma("unroll") for (int _i = 0; _i < 2; ++_i) \
;         __builtin_amdgcn_global_load_lds((const unsigned*)((const char*)(gbase) + (voff)[_i]), (PG8_LAS unsigned*)(lds + (bufoff) + ldsw + _i * 8192), 16, 0, 0); } while (0)
; #define PG8_WAIT_V(n) asm volatile("s_waitcnt vmcnt(" #n ")" ::: "memory")
; #define PG8_BAR __builtin_amdgcn_s_barrier()
; template <class Epi, class Sched, bool ALIGN_EPI = false, bool SP2 = false>
; __device__ __forceinline__ void gemm_phase(PG8_LAS unsigned char* lds, const Gemm g, const Sched& S, const Epi& E) {
;     ...
;     const unsigned ldsw = (unsigned)wid * 1024u;
;     const int aoff = lds_byte(wr * 64 + fr, fq * 8), boff = lds_byte(wc * 32 + fr, fq * 8);
;     ...
;     const char* cA = (const char*)g.A + (size_t)cur.pm * tstep; const char* cB = (const char*)g.Bt + (size_t)cur.pn * tstep;
;     S.a_ready(cur);
;     if constexpr (SP2) {
;         PG8_STAGE(PG8_SB(0, 0), cB, voffB); PG8_STAGE(PG8_SB(0, 1), cB + hstep, voffB); PG8_STAGE(PG8_SA(0, 0), cA, voffA); PG8_STAGE(PG8_SA(0, 1), cA + hstep, voffA);
;         if (wr == 1) PG8_BAR;
;         PG8_WAIT_V(2); PG8_BAR;
;         PG8_STAGE(PG8_SB(1, 0), cB + kstep, voffB); PG8_STAGE(PG8_SA(1, 0), cA + kstep, voffA); PG8_STAGE(PG8_SB(1, 1), cB + hstep + kstep, voffB);
;         PG8_WAIT_V(6); PG8_BAR;
.LBB0_1287:
	s_add_u32 s6, s26, 0x140000
	s_addc_u32 s7, s27, 0
	s_lshl_b32 s12, s12, 5
	s_and_b32 s17, s12, 0x60
	s_mov_b64 s[12:13], 0x80
	s_add_i32 m0, s28, 0x18000
	v_lshl_add_u64 v[6:7], v[6:7], 0, s[12:13]
	s_lshl_b32 s3, s16, 13
	s_lshl_b32 s42, s17, 7
	s_waitcnt vmcnt(2)
	s_barrier
	global_load_lds_dwordx4 v[6:7], off
	v_lshl_add_u64 v[4:5], v[4:5], 0, s[12:13]
	s_add_i32 m0, s28, 0x1a000
	s_add_i32 s39, s28, 0x8000
	s_add_i32 s58, s28, 0xa000
	global_load_lds_dwordx4 v[4:5], off
	v_lshl_add_u64 v[0:1], v[0:1], 0, s[12:13]
	s_mov_b32 m0, s39
	s_add_u32 s18, s50, 0x40080
	global_load_lds_dwordx4 v[0:1], off
	v_mov_b32_e32 v232, v0
	v_mov_b32_e32 v233, v1
	v_lshl_add_u64 v[0:1], v[2:3], 0, s[12:13]
	s_mov_b32 m0, s58
	s_addc_u32 s19, s51, 0
	global_load_lds_dwordx4 v[0:1], off
	v_mov_b32_e32 v234, v0
	v_mov_b32_e32 v235, v1
	s_add_i32 m0, s28, 0x1c000
	v_lshl_add_u64 v[0:1], s[18:19], 0, v[132:133]
	global_load_lds_dwordx4 v[0:1], off
	v_lshl_add_u64 v[0:1], s[18:19], 0, v[128:129]
	s_add_i32 m0, s28, 0x1e000
	v_lshlrev_b32_e32 v2, 2, v201
	global_load_lds_dwordx4 v[0:1], off
	v_and_b32_e32 v0, 15, v201
	v_lshlrev_b32_e32 v1, 1, v11
	v_lshl_or_b32 v186, s16, 6, v0
	v_lshl_or_b32 v0, v0, 6, v1
	v_and_b32_e32 v2, 32, v2
	v_bitop3_b32 v0, v0, s3, v2 bitop3:0xde
	v_lshlrev_b32_e32 v3, 6, v201
	s_movk_i32 s3, 0x3c0
	v_and_or_b32 v1, v3, s3, v1
	v_bitop3_b32 v187, s42, v1, v2 bitop3:0xf6
	v_lshlrev_b32_e32 v1, 8, v201
	v_and_b32_e32 v1, 0x38000, v1
	v_lshlrev_b32_e32 v2, 11, v12
	v_or3_b32 v1, v9, v1, v2
	v_add_u32_e32 v136, v1, v10
	v_lshlrev_b32_e32 v1, 4, v8
	s_waitcnt vmcnt(6)
	s_cmpk_lt_u32 s15, 0x100
	v_and_b32_e32 v1, 0x78000, v1
	s_sext_i32_i8 s62, s14
	s_cselect_b64 s[14:15], -1, 0
	v_or3_b32 v1, v9, v1, v2
	s_add_i32 s59, 0, 0x10000
	s_add_i32 s60, 0, 0x14000
	v_or_b32_e32 v188, s17, v11
	v_mov_b32_e32 v137, v133
	v_add_u32_e32 v138, v1, v10
	v_mov_b32_e32 v139, v133
	v_add_u32_e32 v189, s59, v187
	v_add_u32_e32 v190, s60, v187
	v_add_u32_e32 v191, 0, v0
	v_mov_b32_e32 v192, 0x358637bd
	s_movk_i32 s61, 0x1600
	s_barrier
	s_branch .LBB0_1290

; #define PG8_STAGE(bufoff, gbase, voff) do { _Pragma("unroll") for (int _i = 0; _i < 2; ++_i) \
;         __builtin_amdgcn_global_load_lds((const unsigned*)((const char*)(gbase) + (voff)[_i]), (PG8_LAS unsigned*)(lds + (bufoff) + ldsw + _i * 8192), 16, 0, 0); } while (0)
; #define PG8_LDA(dst, b, h) do { _Pragma("unroll") for (int m = 0; m < 4; ++m) _Pragma("unroll") for (int k = 0; k < 2; ++k) dst[m][k] = *(const PG8_LAS bf16x8*)(lds + PG8_SA(b, h) + aoff + m * 2048 + k * 1024); } while (0)
; #define PG8_LDB(dst, b, h) do { _Pragma("unroll") for (int n = 0; n < 2; ++n) _Pragma("unroll") for (int k = 0; k < 2; ++k) dst[n][k] = *(const PG8_LAS bf16x8*)(lds + PG8_SB(b, h) + boff + n * 2048 + k * 1024); } while (0)
; #define PG8_MMA(ai, bj, At, Bt) do { __builtin_amdgcn_s_setprio(1); _Pragma("unroll") for (int m = 0; m < 4; ++m) _Pragma("unroll") for (int n = 0; n < 2; ++n) _Pragma("unroll") for (int k = 0; k < 2; ++k) \
;         acc[ai][bj][m][n] = __builtin_amdgcn_mfma_f32_16x16x32_bf16(Bt[n][k], At[m][k], acc[ai][bj][m][n], 0, 0, 0); __builtin_amdgcn_s_setprio(0); } while (0)
; #define PG8_WAIT_V(n) asm volatile("s_waitcnt vmcnt(" #n ")" ::: "memory")
; #define PG8_BAR __builtin_amdgcn_s_barrier()
; template <class Epi, class Sched, bool ALIGN_EPI = false, bool SP2 = false>
; __device__ __forceinline__ void gemm_phase(PG8_LAS unsigned char* lds, const Gemm g, const Sched& S, const Epi& E) {
;     ...
;         for (int t = 0; t < nt; t += 2) {
;             const bool last = (t == nt - 2);
;             const char* a1 = cA + (size_t)(t + 1) * kstep;
;             const char* a2 = last ? nA : cA + (size_t)(t + 2) * kstep; const char* b2 = last ? nB : cB + (size_t)(t + 2) * kstep;
;             const char* a3 = a2 + kstep; const char* b3 = b2 + kstep;
;             if (last && has_next) S.a_ready(nxt);
;             if constexpr (SP2) {
;             PG8_LDB(B0, 0, 0); PG8_LDB(B1, 0, 1); PG8_SCHED; PG8_LDA(At, 0, 0); PG8_STAGE(PG8_SA(1, 1), a1 + hstep, voffA);
;             PG8_WAIT_V(8); PG8_WAIT_L(0); PG8_BAR; PG8_MMA(0, 0, At, B0); PG8_MMA(0, 1, At, B1); PG8_BAR; PG8_SCHED;
;             PG8_LDA(At, 0, 1); PG8_STAGE(PG8_SB(0, 0), b2, voffB); PG8_STAGE(PG8_SB(0, 1), b2 + hstep, voffB); PG8_STAGE(PG8_SA(0, 0), a2, voffA);
;             PG8_WAIT_V(8); PG8_WAIT_L(0); PG8_BAR; PG8_MMA(1, 0, At, B0); PG8_MMA(1, 1, At, B1); PG8_BAR; PG8_SCHED;
.LBB0_1293:
	ds_read_b128 v[140:143], v189
	ds_read_b128 v[144:147], v189 offset:1024
	ds_read_b128 v[148:151], v189 offset:2048
	ds_read_b128 v[152:155], v189 offset:3072
	ds_read_b128 v[156:159], v190
	ds_read_b128 v[160:163], v190 offset:1024
	ds_read_b128 v[164:167], v190 offset:2048
	ds_read_b128 v[168:171], v190 offset:3072
	s_add_u32 s50, s48, 0xfffc0080
	s_addc_u32 s51, s49, -1
	s_cmp_eq_u32 s66, 12
	s_cselect_b32 s57, s3, s51
	s_cselect_b32 s56, s17, s50
	s_cselect_b32 s51, s19, s65
	s_cselect_b32 s50, s63, s64
	v_lshl_add_u64 v[184:185], s[48:49], 0, v[136:137]
	s_mov_b32 m0, s39
	s_nop 0
	global_load_lds_dwordx4 v[232:233], off
	s_mov_b32 m0, s58
	s_nop 0
	global_load_lds_dwordx4 v[234:235], off
	s_add_i32 m0, s28, 0xc000
	ds_read_b128 v[172:175], v191
	ds_read_b128 v[176:179], v191 offset:1024
	ds_read_b128 v[180:183], v191 offset:2048
	ds_read_b128 v[194:197], v191 offset:3072
	ds_read_b128 v[202:205], v191 offset:4096
	ds_read_b128 v[206:209], v191 offset:5120
	ds_read_b128 v[210:213], v191 offset:6144
	ds_read_b128 v[214:217], v191 offset:7168
	global_load_lds_dwordx4 v[184:185], off
	v_lshl_add_u64 v[184:185], s[48:49], 0, v[138:139]
	s_add_i32 m0, s28, 0xe000
	s_nop 0
	global_load_lds_dwordx4 v[184:185], off
	s_waitcnt vmcnt(8)
	s_waitcnt lgkmcnt(0)
	s_barrier
	s_setprio 1
	s_waitcnt lgkmcnt(0)
	v_mfma_f32_16x16x32_bf16 v[124:127], v[140:143], v[172:175], v[124:127]
	v_mfma_f32_16x16x32_bf16 v[120:123], v[148:151], v[172:175], v[120:123]
	v_mfma_f32_16x16x32_bf16 v[108:111], v[140:143], v[180:183], v[108:111]
	v_mfma_f32_16x16x32_bf16 v[104:107], v[148:151], v[180:183], v[104:107]
	v_mfma_f32_16x16x32_bf16 v[92:95], v[140:143], v[202:205], v[92:95]
	v_mfma_f32_16x16x32_bf16 v[88:91], v[148:151], v[202:205], v[88:91]
	v_mfma_f32_16x16x32_bf16 v[76:79], v[140:143], v[210:213], v[76:79]
	v_mfma_f32_16x16x32_bf16 v[72:75], v[148:151], v[210:213], v[72:75]
	v_mfma_f32_16x16x32_bf16 v[124:127], v[144:147], v[176:179], v[124:127]
	v_mfma_f32_16x16x32_bf16 v[120:123], v[152:155], v[176:179], v[120:123]
	v_mfma_f32_16x16x32_bf16 v[108:111], v[144:147], v[194:197], v[108:111]
	v_mfma_f32_16x16x32_bf16 v[104:107], v[152:155], v[194:197], v[104:107]
	v_mfma_f32_16x16x32_bf16 v[92:95], v[144:147], v[206:209], v[92:95]
	v_mfma_f32_16x16x32_bf16 v[88:91], v[152:155], v[206:209], v[88:91]
	v_mfma_f32_16x16x32_bf16 v[76:79], v[144:147], v[214:217], v[76:79]
	v_mfma_f32_16x16x32_bf16 v[72:75], v[152:155], v[214:217], v[72:75]
	s_setprio 0
	s_setprio 1
	v_mfma_f32_16x16x32_bf16 v[116:119], v[156:159], v[172:175], v[116:119]
	v_mfma_f32_16x16x32_bf16 v[112:115], v[164:167], v[172:175], v[112:115]
	v_mfma_f32_16x16x32_bf16 v[100:103], v[156:159], v[180:183], v[100:103]
	v_mfma_f32_16x16x32_bf16 v[96:99], v[164:167], v[180:183], v[96:99]
	v_mfma_f32_16x16x32_bf16 v[84:87], v[156:159], v[202:205], v[84:87]
	v_mfma_f32_16x16x32_bf16 v[80:83], v[164:167], v[202:205], v[80:83]
	v_mfma_f32_16x16x32_bf16 v[68:71], v[156:159], v[210:213], v[68:71]
	v_mfma_f32_16x16x32_bf16 v[64:67], v[164:167], v[210:213], v[64:67]
	v_mfma_f32_16x16x32_bf16 v[116:119], v[160:163], v[176:179], v[116:119]
	v_mfma_f32_16x16x32_bf16 v[112:115], v[168:171], v[176:179], v[112:115]
	v_mfma_f32_16x16x32_bf16 v[100:103], v[160:163], v[194:197], v[100:103]
	v_mfma_f32_16x16x32_bf16 v[96:99], v[168:171], v[194:197], v[96:99]
	v_mfma_f32_16x16x32_bf16 v[84:87], v[160:163], v[206:209], v[84:87]
	v_mfma_f32_16x16x32_bf16 v[80:83], v[168:171], v[206:209], v[80:83]
	v_mfma_f32_16x16x32_bf16 v[68:71], v[160:163], v[214:217], v[68:71]
	v_mfma_f32_16x16x32_bf16 v[64:67], v[168:171], v[214:217], v[64:67]
	s_setprio 0
	s_barrier
	s_add_i32 s67, s59, s21
	v_lshl_add_u64 v[184:185], s[50:51], 0, v[132:133]
	s_mov_b32 m0, s67
	ds_read_b128 v[172:175], v191 offset:16384
	ds_read_b128 v[176:179], v191 offset:17408
	ds_read_b128 v[180:183], v191 offset:18432
	ds_read_b128 v[194:197], v191 offset:19456
	ds_read_b128 v[202:205], v191 offset:20480
	ds_read_b128 v[206:209], v191 offset:21504
	ds_read_b128 v[210:213], v191 offset:22528
	ds_read_b128 v[214:217], v191 offset:23552
	global_load_lds_dwordx4 v[184:185], off
	s_add_i32 m0, s67, 0x2000
	s_add_u32 s68, s50, 0x40000
	v_lshl_add_u64 v[198:199], s[50:51], 0, v[128:129]
	s_addc_u32 s69, s51, 0
	s_add_i32 s67, s60, s21
	global_load_lds_dwordx4 v[198:199], off
	v_lshl_add_u64 v[218:219], s[68:69], 0, v[132:133]
	s_mov_b32 m0, s67
	v_lshl_add_u64 v[220:221], s[56:57], 0, v[130:131]
	global_load_lds_dwordx4 v[218:219], off
	v_lshl_add_u64 v[218:219], s[68:69], 0, v[128:129]
	s_add_i32 m0, s67, 0x2000
	s_nop 0
	global_load_lds_dwordx4 v[218:219], off
	v_lshl_add_u64 v[218:219], s[56:57], 0, v[134:135]
	v_mov_b32_e32 v236, v218
	v_mov_b32_e32 v237, v219
	v_mov_b32_e32 v238, v220
	v_mov_b32_e32 v239, v221
	s_waitcnt vmcnt(6)
	s_waitcnt lgkmcnt(0)
	s_barrier
; #define PG8_STAGE(bufoff, gbase, voff) do { _Pragma("unroll") for (int _i = 0; _i < 2; ++_i) \
;         __builtin_amdgcn_global_load_lds((const unsigned*)((const char*)(gbase) + (voff)[_i]), (PG8_LAS unsigned*)(lds + (bufoff) + ldsw + _i * 8192), 16, 0, 0); } while (0)
; #define PG8_LDA(dst, b, h) do { _Pragma("unroll") for (int m = 0; m < 4; ++m) _Pragma("unroll") for (int k = 0; k < 2; ++k) dst[m][k] = *(const PG8_LAS bf16x8*)(lds + PG8_SA(b, h) + aoff + m * 2048 + k * 1024); } while (0)
; #define PG8_LDB(dst, b, h) do { _Pragma("unroll") for (int n = 0; n < 2; ++n) _Pragma("unroll") for (int k = 0; k < 2; ++k) dst[n][k] = *(const PG8_LAS bf16x8*)(lds + PG8_SB(b, h) + boff + n * 2048 + k * 1024); } while (0)
; #define PG8_MMA(ai, bj, At, Bt) do { __builtin_amdgcn_s_setprio(1); _Pragma("unroll") for (int m = 0; m < 4; ++m) _Pragma("unroll") for (int n = 0; n < 2; ++n) _Pragma("unroll") for (int k = 0; k < 2; ++k) \
;         acc[ai][bj][m][n] = __builtin_amdgcn_mfma_f32_16x16x32_bf16(Bt[n][k], At[m][k], acc[ai][bj][m][n], 0, 0, 0); __builtin_amdgcn_s_setprio(0); } while (0)
; #define PG8_WAIT_V(n) asm volatile("s_waitcnt vmcnt(" #n ")" ::: "memory")
; #define PG8_WAIT_L(n) asm volatile("s_waitcnt lgkmcnt(" #n ")" ::: "memory")
; #define PG8_BAR __builtin_amdgcn_s_barrier()
; #define PG8_SCHED __builtin_amdgcn_sched_barrier(0)
; template <class Epi, class Sched, bool ALIGN_EPI = false, bool SP2 = false>
; __device__ __forceinline__ void gemm_phase(PG8_LAS unsigned char* lds, const Gemm g, const Sched& S, const Epi& E) {
;     ...
;             PG8_WAIT_V(8); PG8_WAIT_L(0); PG8_BAR; PG8_MMA(1, 0, At, B0); PG8_MMA(1, 1, At, B1); PG8_BAR; PG8_SCHED;
;             PG8_LDB(B0, 1, 0); PG8_LDB(B1, 1, 1); PG8_SCHED; PG8_LDA(At, 1, 0); PG8_STAGE(PG8_SA(0, 1), a2 + hstep, voffA);
;             PG8_WAIT_V(8); PG8_WAIT_L(0); PG8_BAR; PG8_MMA(0, 0, At, B0); PG8_MMA(0, 1, At, B1); PG8_BAR; PG8_SCHED;
	s_setprio 1
	s_waitcnt lgkmcnt(0)
	v_mfma_f32_16x16x32_bf16 v[60:63], v[140:143], v[172:175], v[60:63]
	v_mfma_f32_16x16x32_bf16 v[56:59], v[148:151], v[172:175], v[56:59]
	v_mfma_f32_16x16x32_bf16 v[44:47], v[140:143], v[180:183], v[44:47]
	v_mfma_f32_16x16x32_bf16 v[40:43], v[148:151], v[180:183], v[40:43]
	v_mfma_f32_16x16x32_bf16 v[28:31], v[140:143], v[202:205], v[28:31]
	v_mfma_f32_16x16x32_bf16 v[24:27], v[148:151], v[202:205], v[24:27]
	v_mfma_f32_16x16x32_bf16 v[12:15], v[140:143], v[210:213], v[12:15]
	v_mfma_f32_16x16x32_bf16 v[8:11], v[148:151], v[210:213], v[8:11]
	v_mfma_f32_16x16x32_bf16 v[60:63], v[144:147], v[176:179], v[60:63]
	v_mfma_f32_16x16x32_bf16 v[56:59], v[152:155], v[176:179], v[56:59]
	v_mfma_f32_16x16x32_bf16 v[44:47], v[144:147], v[194:197], v[44:47]
	v_mfma_f32_16x16x32_bf16 v[40:43], v[152:155], v[194:197], v[40:43]
	v_mfma_f32_16x16x32_bf16 v[28:31], v[144:147], v[206:209], v[28:31]
	v_mfma_f32_16x16x32_bf16 v[24:27], v[152:155], v[206:209], v[24:27]
	v_mfma_f32_16x16x32_bf16 v[12:15], v[144:147], v[214:217], v[12:15]
	v_mfma_f32_16x16x32_bf16 v[8:11], v[152:155], v[214:217], v[8:11]
	s_setprio 0
	s_setprio 1
	v_mfma_f32_16x16x32_bf16 v[52:55], v[156:159], v[172:175], v[52:55]
	v_mfma_f32_16x16x32_bf16 v[48:51], v[164:167], v[172:175], v[48:51]
	v_mfma_f32_16x16x32_bf16 v[36:39], v[156:159], v[180:183], v[36:39]
	v_mfma_f32_16x16x32_bf16 v[32:35], v[164:167], v[180:183], v[32:35]
	v_mfma_f32_16x16x32_bf16 v[20:23], v[156:159], v[202:205], v[20:23]
	v_mfma_f32_16x16x32_bf16 v[16:19], v[164:167], v[202:205], v[16:19]
	v_mfma_f32_16x16x32_bf16 v[4:7], v[156:159], v[210:213], v[4:7]
	v_mfma_f32_16x16x32_bf16 v[0:3], v[164:167], v[210:213], v[0:3]
	v_mfma_f32_16x16x32_bf16 v[52:55], v[160:163], v[176:179], v[52:55]
	v_mfma_f32_16x16x32_bf16 v[48:51], v[168:171], v[176:179], v[48:51]
	v_mfma_f32_16x16x32_bf16 v[36:39], v[160:163], v[194:197], v[36:39]
	v_mfma_f32_16x16x32_bf16 v[32:35], v[168:171], v[194:197], v[32:35]
	v_mfma_f32_16x16x32_bf16 v[20:23], v[160:163], v[206:209], v[20:23]
	v_mfma_f32_16x16x32_bf16 v[16:19], v[168:171], v[206:209], v[16:19]
	v_mfma_f32_16x16x32_bf16 v[4:7], v[160:163], v[214:217], v[4:7]
	v_mfma_f32_16x16x32_bf16 v[0:3], v[168:171], v[214:217], v[0:3]
	s_setprio 0
	s_barrier
	s_add_i32 s67, 0, 0x18000
	s_add_i32 s68, 0, 0x1c000
	v_add_u32_e32 v152, s67, v187
	v_add_u32_e32 v168, s68, v187
	ds_read_b128 v[140:143], v152
	ds_read_b128 v[144:147], v152 offset:1024
	ds_read_b128 v[148:151], v152 offset:2048
	ds_read_b128 v[152:155], v152 offset:3072
	ds_read_b128 v[156:159], v168
	ds_read_b128 v[160:163], v168 offset:1024
	ds_read_b128 v[164:167], v168 offset:2048
	ds_read_b128 v[168:171], v168 offset:3072
	s_add_u32 s56, s56, 0x40000
	s_addc_u32 s57, s57, 0
	s_mov_b32 m0, s28
	s_nop 0
	global_load_lds_dwordx4 v[236:237], off
	s_mov_b32 m0, s29
	s_nop 0
	global_load_lds_dwordx4 v[238:239], off
	s_mov_b32 m0, s30
	v_lshl_add_u64 v[222:223], s[56:57], 0, v[134:135]
	ds_read_b128 v[172:175], v191 offset:32768
	ds_read_b128 v[176:179], v191 offset:33792
	ds_read_b128 v[180:183], v191 offset:34816
	ds_read_b128 v[194:197], v191 offset:35840
	ds_read_b128 v[202:205], v191 offset:36864
	ds_read_b128 v[206:209], v191 offset:37888
	ds_read_b128 v[210:213], v191 offset:38912
	ds_read_b128 v[214:217], v191 offset:39936
	global_load_lds_dwordx4 v[222:223], off
	v_lshl_add_u64 v[222:223], s[56:57], 0, v[130:131]
	s_mov_b32 m0, s31
	s_nop 0
	global_load_lds_dwordx4 v[222:223], off
	s_waitcnt vmcnt(8)
	s_waitcnt lgkmcnt(0)
	s_barrier
	s_setprio 1
	s_waitcnt lgkmcnt(0)
	v_mfma_f32_16x16x32_bf16 v[124:127], v[140:143], v[172:175], v[124:127]
	v_mfma_f32_16x16x32_bf16 v[120:123], v[148:151], v[172:175], v[120:123]
	v_mfma_f32_16x16x32_bf16 v[108:111], v[140:143], v[180:183], v[108:111]
	v_mfma_f32_16x16x32_bf16 v[104:107], v[148:151], v[180:183], v[104:107]
	v_mfma_f32_16x16x32_bf16 v[92:95], v[140:143], v[202:205], v[92:95]
	v_mfma_f32_16x16x32_bf16 v[88:91], v[148:151], v[202:205], v[88:91]
	v_mfma_f32_16x16x32_bf16 v[76:79], v[140:143], v[210:213], v[76:79]
	v_mfma_f32_16x16x32_bf16 v[72:75], v[148:151], v[210:213], v[72:75]
	v_mfma_f32_16x16x32_bf16 v[124:127], v[144:147], v[176:179], v[124:127]
	v_mfma_f32_16x16x32_bf16 v[120:123], v[152:155], v[176:179], v[120:123]
	v_mfma_f32_16x16x32_bf16 v[108:111], v[144:147], v[194:197], v[108:111]
	v_mfma_f32_16x16x32_bf16 v[104:107], v[152:155], v[194:197], v[104:107]
	v_mfma_f32_16x16x32_bf16 v[92:95], v[144:147], v[206:209], v[92:95]
	v_mfma_f32_16x16x32_bf16 v[88:91], v[152:155], v[206:209], v[88:91]
	v_mfma_f32_16x16x32_bf16 v[76:79], v[144:147], v[214:217], v[76:79]
	v_mfma_f32_16x16x32_bf16 v[72:75], v[152:155], v[214:217], v[72:75]
	s_setprio 0
	s_setprio 1
	v_mfma_f32_16x16x32_bf16 v[116:119], v[156:159], v[172:175], v[116:119]
	v_mfma_f32_16x16x32_bf16 v[112:115], v[164:167], v[172:175], v[112:115]
	v_mfma_f32_16x16x32_bf16 v[100:103], v[156:159], v[180:183], v[100:103]
	v_mfma_f32_16x16x32_bf16 v[96:99], v[164:167], v[180:183], v[96:99]
	v_mfma_f32_16x16x32_bf16 v[84:87], v[156:159], v[202:205], v[84:87]
	v_mfma_f32_16x16x32_bf16 v[80:83], v[164:167], v[202:205], v[80:83]
	v_mfma_f32_16x16x32_bf16 v[68:71], v[156:159], v[210:213], v[68:71]
	v_mfma_f32_16x16x32_bf16 v[64:67], v[164:167], v[210:213], v[64:67]
	v_mfma_f32_16x16x32_bf16 v[116:119], v[160:163], v[176:179], v[116:119]
	v_mfma_f32_16x16x32_bf16 v[112:115], v[168:171], v[176:179], v[112:115]
	v_mfma_f32_16x16x32_bf16 v[100:103], v[160:163], v[194:197], v[100:103]
	v_mfma_f32_16x16x32_bf16 v[96:99], v[168:171], v[194:197], v[96:99]
	v_mfma_f32_16x16x32_bf16 v[84:87], v[160:163], v[206:209], v[84:87]
	v_mfma_f32_16x16x32_bf16 v[80:83], v[168:171], v[206:209], v[80:83]
	v_mfma_f32_16x16x32_bf16 v[68:71], v[160:163], v[214:217], v[68:71]
	v_mfma_f32_16x16x32_bf16 v[64:67], v[168:171], v[214:217], v[64:67]
	s_setprio 0
	s_barrier
; #define PG8_STAGE(bufoff, gbase, voff) do { _Pragma("unroll") for (int _i = 0; _i < 2; ++_i) \
;         __builtin_amdgcn_global_load_lds((const unsigned*)((const char*)(gbase) + (voff)[_i]), (PG8_LAS unsigned*)(lds + (bufoff) + ldsw + _i * 8192), 16, 0, 0); } while (0)
; #define PG8_LDA(dst, b, h) do { _Pragma("unroll") for (int m = 0; m < 4; ++m) _Pragma("unroll") for (int k = 0; k < 2; ++k) dst[m][k] = *(const PG8_LAS bf16x8*)(lds + PG8_SA(b, h) + aoff + m * 2048 + k * 1024); } while (0)
; #define PG8_MMA(ai, bj, At, Bt) do { __builtin_amdgcn_s_setprio(1); _Pragma("unroll") for (int m = 0; m < 4; ++m) _Pragma("unroll") for (int n = 0; n < 2; ++n) _Pragma("unroll") for (int k = 0; k < 2; ++k) \
;         acc[ai][bj][m][n] = __builtin_amdgcn_mfma_f32_16x16x32_bf16(Bt[n][k], At[m][k], acc[ai][bj][m][n], 0, 0, 0); __builtin_amdgcn_s_setprio(0); } while (0)
; #define PG8_WAIT_V(n) asm volatile("s_waitcnt vmcnt(" #n ")" ::: "memory")
; #define PG8_WAIT_L(n) asm volatile("s_waitcnt lgkmcnt(" #n ")" ::: "memory")
; #define PG8_BAR __builtin_amdgcn_s_barrier()
; #define PG8_SCHED __builtin_amdgcn_sched_barrier(0)
; template <class Epi, class Sched, bool ALIGN_EPI = false, bool SP2 = false>
; __device__ __forceinline__ void gemm_phase(PG8_LAS unsigned char* lds, const Gemm g, const Sched& S, const Epi& E) {
;     ...
;             PG8_LDA(At, 1, 1); PG8_STAGE(PG8_SB(1, 0), b3, voffB); PG8_STAGE(PG8_SB(1, 1), b3 + hstep, voffB); PG8_STAGE(PG8_SA(1, 0), a3, voffA);
;             PG8_WAIT_V(8); PG8_WAIT_L(0); PG8_BAR; PG8_MMA(1, 0, At, B0); PG8_MMA(1, 1, At, B1); PG8_BAR; PG8_SCHED;
	s_add_i32 s56, s67, s21
	v_lshl_add_u64 v[184:185], v[184:185], 0, s[12:13]
	s_mov_b32 m0, s56
	ds_read_b128 v[172:175], v191 offset:49152
	ds_read_b128 v[176:179], v191 offset:50176
	ds_read_b128 v[180:183], v191 offset:51200
	ds_read_b128 v[194:197], v191 offset:52224
	ds_read_b128 v[202:205], v191 offset:53248
	ds_read_b128 v[206:209], v191 offset:54272
	ds_read_b128 v[210:213], v191 offset:55296
	ds_read_b128 v[214:217], v191 offset:56320
	global_load_lds_dwordx4 v[184:185], off
	s_add_i32 m0, s56, 0x2000
	s_add_u32 s50, s50, 0x40080
	v_lshl_add_u64 v[184:185], v[198:199], 0, s[12:13]
	s_addc_u32 s51, s51, 0
	s_add_i32 s56, s68, s21
	global_load_lds_dwordx4 v[184:185], off
	v_lshl_add_u64 v[184:185], s[50:51], 0, v[132:133]
	s_mov_b32 m0, s56
	s_nop 0
	global_load_lds_dwordx4 v[184:185], off
	v_lshl_add_u64 v[184:185], s[50:51], 0, v[128:129]
	s_add_i32 m0, s56, 0x2000
	s_nop 0
	global_load_lds_dwordx4 v[184:185], off
	v_lshl_add_u64 v[184:185], v[218:219], 0, s[12:13]
	v_mov_b32_e32 v232, v184
	v_mov_b32_e32 v233, v185
	v_lshl_add_u64 v[184:185], v[220:221], 0, s[12:13]
	v_mov_b32_e32 v234, v184
	v_mov_b32_e32 v235, v185
	s_waitcnt vmcnt(6)
	s_waitcnt lgkmcnt(0)
	s_barrier
	s_setprio 1
	s_waitcnt lgkmcnt(0)
	v_mfma_f32_16x16x32_bf16 v[60:63], v[140:143], v[172:175], v[60:63]
	v_mfma_f32_16x16x32_bf16 v[56:59], v[148:151], v[172:175], v[56:59]
	v_mfma_f32_16x16x32_bf16 v[44:47], v[140:143], v[180:183], v[44:47]
	v_mfma_f32_16x16x32_bf16 v[40:43], v[148:151], v[180:183], v[40:43]
	v_mfma_f32_16x16x32_bf16 v[28:31], v[140:143], v[202:205], v[28:31]
	v_mfma_f32_16x16x32_bf16 v[24:27], v[148:151], v[202:205], v[24:27]
	v_mfma_f32_16x16x32_bf16 v[12:15], v[140:143], v[210:213], v[12:15]
	v_mfma_f32_16x16x32_bf16 v[8:11], v[148:151], v[210:213], v[8:11]
	v_mfma_f32_16x16x32_bf16 v[60:63], v[144:147], v[176:179], v[60:63]
	v_mfma_f32_16x16x32_bf16 v[56:59], v[152:155], v[176:179], v[56:59]
	v_mfma_f32_16x16x32_bf16 v[44:47], v[144:147], v[194:197], v[44:47]
	v_mfma_f32_16x16x32_bf16 v[40:43], v[152:155], v[194:197], v[40:43]
	v_mfma_f32_16x16x32_bf16 v[28:31], v[144:147], v[206:209], v[28:31]
	v_mfma_f32_16x16x32_bf16 v[24:27], v[152:155], v[206:209], v[24:27]
	v_mfma_f32_16x16x32_bf16 v[12:15], v[144:147], v[214:217], v[12:15]
	v_mfma_f32_16x16x32_bf16 v[8:11], v[152:155], v[214:217], v[8:11]
	s_setprio 0
	s_setprio 1
	v_mfma_f32_16x16x32_bf16 v[52:55], v[156:159], v[172:175], v[52:55]
	v_mfma_f32_16x16x32_bf16 v[48:51], v[164:167], v[172:175], v[48:51]
	v_mfma_f32_16x16x32_bf16 v[36:39], v[156:159], v[180:183], v[36:39]
	v_mfma_f32_16x16x32_bf16 v[32:35], v[164:167], v[180:183], v[32:35]
	v_mfma_f32_16x16x32_bf16 v[20:23], v[156:159], v[202:205], v[20:23]
	v_mfma_f32_16x16x32_bf16 v[16:19], v[164:167], v[202:205], v[16:19]
	v_mfma_f32_16x16x32_bf16 v[4:7], v[156:159], v[210:213], v[4:7]
	v_mfma_f32_16x16x32_bf16 v[0:3], v[164:167], v[210:213], v[0:3]
	v_mfma_f32_16x16x32_bf16 v[52:55], v[160:163], v[176:179], v[52:55]
	v_mfma_f32_16x16x32_bf16 v[48:51], v[168:171], v[176:179], v[48:51]
	v_mfma_f32_16x16x32_bf16 v[36:39], v[160:163], v[194:197], v[36:39]
	v_mfma_f32_16x16x32_bf16 v[32:35], v[168:171], v[194:197], v[32:35]
	v_mfma_f32_16x16x32_bf16 v[20:23], v[160:163], v[206:209], v[20:23]
	v_mfma_f32_16x16x32_bf16 v[16:19], v[168:171], v[206:209], v[16:19]
	v_mfma_f32_16x16x32_bf16 v[4:7], v[160:163], v[214:217], v[4:7]
	v_mfma_f32_16x16x32_bf16 v[0:3], v[168:171], v[214:217], v[0:3]
	s_setprio 0
	s_barrier
	s_add_i32 s66, s66, 2
	s_add_u32 s48, s48, 0x100
	s_addc_u32 s49, s49, 0
	s_add_u32 s64, s64, 0x100
	s_addc_u32 s65, s65, 0
	s_cmp_gt_u32 s66, 13
	s_cbranch_scc0 .LBB0_1293
	s_and_b64 vcc, exec, s[14:15]
	s_cbranch_vccz .LBB0_1296
	s_barrier

; #define PG8_STAGE(bufoff, gbase, voff) do { _Pragma("unroll") for (int _i = 0; _i < 2; ++_i) \
;         __builtin_amdgcn_global_load_lds((const unsigned*)((const char*)(gbase) + (voff)[_i]), (PG8_LAS unsigned*)(lds + (bufoff) + ldsw + _i * 8192), 16, 0, 0); } while (0)
; #define PG8_WAIT_V(n) asm volatile("s_waitcnt vmcnt(" #n ")" ::: "memory")
; #define PG8_BAR __builtin_amdgcn_s_barrier()
; template <class Epi, class Sched, bool ALIGN_EPI = false, bool SP2 = false>
; __device__ __forceinline__ void gemm_phase(PG8_LAS unsigned char* lds, const Gemm g, const Sched& S, const Epi& E) {
;     ...
;     const unsigned ldsw = (unsigned)wid * 1024u;
;     const int aoff = lds_byte(wr * 64 + fr, fq * 8), boff = lds_byte(wc * 32 + fr, fq * 8);
;     ...
;     const char* cA = (const char*)g.A + (size_t)cur.pm * tstep; const char* cB = (const char*)g.Bt + (size_t)cur.pn * tstep;
;     S.a_ready(cur);
;     if constexpr (SP2) {
;         PG8_STAGE(PG8_SB(0, 0), cB, voffB); PG8_STAGE(PG8_SB(0, 1), cB + hstep, voffB); PG8_STAGE(PG8_SA(0, 0), cA, voffA); PG8_STAGE(PG8_SA(0, 1), cA + hstep, voffA);
;         if (wr == 1) PG8_BAR;
;         PG8_WAIT_V(2); PG8_BAR;
;         PG8_STAGE(PG8_SB(1, 0), cB + kstep, voffB); PG8_STAGE(PG8_SA(1, 0), cA + kstep, voffA); PG8_STAGE(PG8_SB(1, 1), cB + hstep + kstep, voffB);
;         PG8_WAIT_V(6); PG8_BAR;
.LBB0_1353:
	s_add_u32 s10, s26, 0x180000
	s_addc_u32 s11, s27, 0
	s_lshl_b32 s3, s3, 5
	s_mov_b64 s[12:13], 0x80
	s_and_b32 s16, s3, 0x60
	s_add_i32 m0, s29, 0x18000
	v_lshl_add_u64 v[6:7], v[6:7], 0, s[12:13]
	s_lshl_b32 s5, s2, 13
	s_lshl_b32 s3, s16, 7
	s_waitcnt vmcnt(2)
	s_barrier
	global_load_lds_dwordx4 v[6:7], off
	v_lshl_add_u64 v[4:5], v[4:5], 0, s[12:13]
	s_add_i32 m0, s29, 0x1a000
	s_add_i32 s47, s29, 0x8000
	s_add_i32 s48, s29, 0xa000
	global_load_lds_dwordx4 v[4:5], off
	v_lshl_add_u64 v[0:1], v[0:1], 0, s[12:13]
	s_mov_b32 m0, s47
	s_add_u32 s14, s42, 0xb0080
	global_load_lds_dwordx4 v[0:1], off
	v_mov_b32_e32 v232, v0
	v_mov_b32_e32 v233, v1
	v_lshl_add_u64 v[0:1], v[2:3], 0, s[12:13]
	s_mov_b32 m0, s48
	s_addc_u32 s15, s43, 0
	global_load_lds_dwordx4 v[0:1], off
	v_mov_b32_e32 v234, v0
	v_mov_b32_e32 v235, v1
	s_add_i32 m0, s29, 0x1c000
	v_lshl_add_u64 v[0:1], s[14:15], 0, v[138:139]
	global_load_lds_dwordx4 v[0:1], off
	v_lshl_add_u64 v[0:1], s[14:15], 0, v[142:143]
	s_add_i32 m0, s29, 0x1e000
	v_lshlrev_b32_e32 v3, 2, v201
	global_load_lds_dwordx4 v[0:1], off
	v_bfe_u32 v0, v201, 4, 2
	v_and_b32_e32 v1, 15, v201
	v_lshl_or_b32 v154, s2, 6, v1
	v_lshlrev_b32_e32 v2, 4, v0
	v_lshlrev_b32_e32 v4, 6, v201
	s_movk_i32 s2, 0x3c0
	v_lshl_or_b32 v1, v1, 6, v2
	v_and_b32_e32 v3, 32, v3
	v_and_or_b32 v2, v4, s2, v2
	v_bitop3_b32 v2, s3, v2, v3 bitop3:0xf6
	s_cmpk_lt_u32 s4, 0x100
	v_cmp_eq_u32_e64 s[2:3], 0, v0
	v_lshl_or_b32 v155, v0, 3, s16
	v_add_u16_e32 v0, v8, v9
	s_waitcnt vmcnt(6)
	s_cselect_b64 s[14:15], -1, 0
	v_lshrrev_b16_e32 v0, 1, v0
	s_add_i32 s60, 0, 0x10000
	s_add_i32 s62, 0, 0x14000
	v_bitop3_b32 v1, v1, s5, v3 bitop3:0xde
	v_add_lshl_u32 v144, v10, v0, 1
	v_add_lshl_u32 v146, v11, v0, 1
	v_add_u32_e32 v156, s60, v2
	v_add_u32_e32 v157, s62, v2
	v_mbcnt_lo_u32_b32 v0, -1, 0
	s_add_i32 s60, s60, s28
	s_add_i32 s62, s62, s28
	s_add_i32 s64, 0, 0x18000
	s_add_i32 s65, 0, 0x1c000
	s_mov_b32 s49, 0x18000
	v_mov_b32_e32 v145, v139
	v_mov_b32_e32 v147, v139
	v_add_u32_e32 v158, 0, v1
	s_mov_b32 s50, 0x40000
	s_mov_b32 s51, 0x48000
	s_mov_b32 s56, 0x50000
	s_mov_b32 s57, 0x58000
	v_mbcnt_hi_u32_b32 v159, -1, v0
	s_add_i32 s58, s29, 0xc000
	s_add_i32 s59, s29, 0xe000
	s_add_i32 s61, s60, 0x2000
	s_add_i32 s63, s62, 0x2000
	v_add_u32_e32 v160, s64, v2
	v_add_u32_e32 v161, s65, v2
	s_barrier
	s_branch .LBB0_1356

; #define PG8_STAGE(bufoff, gbase, voff) do { _Pragma("unroll") for (int _i = 0; _i < 2; ++_i) \
;         __builtin_amdgcn_global_load_lds((const unsigned*)((const char*)(gbase) + (voff)[_i]), (PG8_LAS unsigned*)(lds + (bufoff) + ldsw + _i * 8192), 16, 0, 0); } while (0)
; #define PG8_LDA(dst, b, h) do { _Pragma("unroll") for (int m = 0; m < 4; ++m) _Pragma("unroll") for (int k = 0; k < 2; ++k) dst[m][k] = *(const PG8_LAS bf16x8*)(lds + PG8_SA(b, h) + aoff + m * 2048 + k * 1024); } while (0)
; #define PG8_LDB(dst, b, h) do { _Pragma("unroll") for (int n = 0; n < 2; ++n) _Pragma("unroll") for (int k = 0; k < 2; ++k) dst[n][k] = *(const PG8_LAS bf16x8*)(lds + PG8_SB(b, h) + boff + n * 2048 + k * 1024); } while (0)
; #define PG8_MMA(ai, bj, At, Bt) do { __builtin_amdgcn_s_setprio(1); _Pragma("unroll") for (int m = 0; m < 4; ++m) _Pragma("unroll") for (int n = 0; n < 2; ++n) _Pragma("unroll") for (int k = 0; k < 2; ++k) \
;         acc[ai][bj][m][n] = __builtin_amdgcn_mfma_f32_16x16x32_bf16(Bt[n][k], At[m][k], acc[ai][bj][m][n], 0, 0, 0); __builtin_amdgcn_s_setprio(0); } while (0)
; #define PG8_WAIT_V(n) asm volatile("s_waitcnt vmcnt(" #n ")" ::: "memory")
; #define PG8_BAR __builtin_amdgcn_s_barrier()
; template <class Epi, class Sched, bool ALIGN_EPI = false, bool SP2 = false>
; __device__ __forceinline__ void gemm_phase(PG8_LAS unsigned char* lds, const Gemm g, const Sched& S, const Epi& E) {
;     ...
;         for (int t = 0; t < nt; t += 2) {
;             const bool last = (t == nt - 2);
;             const char* a1 = cA + (size_t)(t + 1) * kstep;
;             const char* a2 = last ? nA : cA + (size_t)(t + 2) * kstep; const char* b2 = last ? nB : cB + (size_t)(t + 2) * kstep;
;             const char* a3 = a2 + kstep; const char* b3 = b2 + kstep;
;             if (last && has_next) S.a_ready(nxt);
;             if constexpr (SP2) {
;             PG8_LDB(B0, 0, 0); PG8_LDB(B1, 0, 1); PG8_SCHED; PG8_LDA(At, 0, 0); PG8_STAGE(PG8_SA(1, 1), a1 + hstep, voffA);
;             PG8_WAIT_V(8); PG8_WAIT_L(0); PG8_BAR; PG8_MMA(0, 0, At, B0); PG8_MMA(0, 1, At, B1); PG8_BAR; PG8_SCHED;
;             PG8_LDA(At, 0, 1); PG8_STAGE(PG8_SB(0, 0), b2, voffB); PG8_STAGE(PG8_SB(0, 1), b2 + hstep, voffB); PG8_STAGE(PG8_SA(0, 0), a2, voffA);
;             PG8_WAIT_V(8); PG8_WAIT_L(0); PG8_BAR; PG8_MMA(1, 0, At, B0); PG8_MMA(1, 1, At, B1); PG8_BAR; PG8_SCHED;
.LBB0_1363:
	ds_read_b128 v[128:131], v156
	ds_read_b128 v[132:135], v156 offset:1024
	ds_read_b128 v[148:151], v156 offset:2048
	ds_read_b128 v[162:165], v156 offset:3072
	ds_read_b128 v[166:169], v157
	ds_read_b128 v[170:173], v157 offset:1024
	ds_read_b128 v[174:177], v157 offset:2048
	ds_read_b128 v[178:181], v157 offset:3072
	s_add_u32 s42, s26, 0xfff50080
	s_addc_u32 s43, s27, -1
	s_cmp_eq_u32 s72, 40
	s_cselect_b32 s45, s17, s43
	s_cselect_b32 s44, s16, s42
	s_cselect_b32 s43, s19, s71
	s_cselect_b32 s42, s18, s70
	s_mov_b32 m0, s47
	s_nop 0
	global_load_lds_dwordx4 v[232:233], off
	s_mov_b32 m0, s48
	s_nop 0
	global_load_lds_dwordx4 v[234:235], off
	s_mov_b32 m0, s58
	v_lshl_add_u64 v[152:153], s[26:27], 0, v[144:145]
	ds_read_b128 v[182:185], v158
	ds_read_b128 v[186:189], v158 offset:1024
	ds_read_b128 v[190:193], v158 offset:2048
	ds_read_b128 v[194:197], v158 offset:3072
	ds_read_b128 v[202:205], v158 offset:4096
	ds_read_b128 v[206:209], v158 offset:5120
	ds_read_b128 v[210:213], v158 offset:6144
	ds_read_b128 v[214:217], v158 offset:7168
	global_load_lds_dwordx4 v[152:153], off
	v_lshl_add_u64 v[152:153], s[26:27], 0, v[146:147]
	s_mov_b32 m0, s59
	s_nop 0
	global_load_lds_dwordx4 v[152:153], off
	s_waitcnt vmcnt(8)
	s_waitcnt lgkmcnt(0)
	s_barrier
	s_setprio 1
	s_waitcnt lgkmcnt(0)
	v_mfma_f32_16x16x32_bf16 v[124:127], v[128:131], v[182:185], v[124:127]
	v_mfma_f32_16x16x32_bf16 v[120:123], v[148:151], v[182:185], v[120:123]
	v_mfma_f32_16x16x32_bf16 v[108:111], v[128:131], v[190:193], v[108:111]
	v_mfma_f32_16x16x32_bf16 v[104:107], v[148:151], v[190:193], v[104:107]
	v_mfma_f32_16x16x32_bf16 v[92:95], v[128:131], v[202:205], v[92:95]
	v_mfma_f32_16x16x32_bf16 v[88:91], v[148:151], v[202:205], v[88:91]
	v_mfma_f32_16x16x32_bf16 v[76:79], v[128:131], v[210:213], v[76:79]
	v_mfma_f32_16x16x32_bf16 v[72:75], v[148:151], v[210:213], v[72:75]
	v_mfma_f32_16x16x32_bf16 v[124:127], v[132:135], v[186:189], v[124:127]
	v_mfma_f32_16x16x32_bf16 v[120:123], v[162:165], v[186:189], v[120:123]
	v_mfma_f32_16x16x32_bf16 v[108:111], v[132:135], v[194:197], v[108:111]
	v_mfma_f32_16x16x32_bf16 v[104:107], v[162:165], v[194:197], v[104:107]
	v_mfma_f32_16x16x32_bf16 v[92:95], v[132:135], v[206:209], v[92:95]
	v_mfma_f32_16x16x32_bf16 v[88:91], v[162:165], v[206:209], v[88:91]
	v_mfma_f32_16x16x32_bf16 v[76:79], v[132:135], v[214:217], v[76:79]
	v_mfma_f32_16x16x32_bf16 v[72:75], v[162:165], v[214:217], v[72:75]
	s_setprio 0
	s_setprio 1
	v_mfma_f32_16x16x32_bf16 v[116:119], v[166:169], v[182:185], v[116:119]
	v_mfma_f32_16x16x32_bf16 v[112:115], v[174:177], v[182:185], v[112:115]
	v_mfma_f32_16x16x32_bf16 v[100:103], v[166:169], v[190:193], v[100:103]
	v_mfma_f32_16x16x32_bf16 v[96:99], v[174:177], v[190:193], v[96:99]
	v_mfma_f32_16x16x32_bf16 v[84:87], v[166:169], v[202:205], v[84:87]
	v_mfma_f32_16x16x32_bf16 v[80:83], v[174:177], v[202:205], v[80:83]
	v_mfma_f32_16x16x32_bf16 v[68:71], v[166:169], v[210:213], v[68:71]
	v_mfma_f32_16x16x32_bf16 v[64:67], v[174:177], v[210:213], v[64:67]
	v_mfma_f32_16x16x32_bf16 v[116:119], v[170:173], v[186:189], v[116:119]
	v_mfma_f32_16x16x32_bf16 v[112:115], v[178:181], v[186:189], v[112:115]
	v_mfma_f32_16x16x32_bf16 v[100:103], v[170:173], v[194:197], v[100:103]
	v_mfma_f32_16x16x32_bf16 v[96:99], v[178:181], v[194:197], v[96:99]
	v_mfma_f32_16x16x32_bf16 v[84:87], v[170:173], v[206:209], v[84:87]
	v_mfma_f32_16x16x32_bf16 v[80:83], v[178:181], v[206:209], v[80:83]
	v_mfma_f32_16x16x32_bf16 v[68:71], v[170:173], v[214:217], v[68:71]
	v_mfma_f32_16x16x32_bf16 v[64:67], v[178:181], v[214:217], v[64:67]
	s_setprio 0
	s_barrier
	s_mov_b32 m0, s60
	v_lshl_add_u64 v[152:153], s[42:43], 0, v[138:139]
	s_add_u32 s74, s42, 0xb0000
	ds_read_b128 v[182:185], v158 offset:16384
	ds_read_b128 v[186:189], v158 offset:17408
	ds_read_b128 v[190:193], v158 offset:18432
	ds_read_b128 v[194:197], v158 offset:19456
	ds_read_b128 v[202:205], v158 offset:20480
	ds_read_b128 v[206:209], v158 offset:21504
	ds_read_b128 v[210:213], v158 offset:22528
	ds_read_b128 v[214:217], v158 offset:23552
	global_load_lds_dwordx4 v[152:153], off
	v_lshl_add_u64 v[198:199], s[42:43], 0, v[142:143]
	s_mov_b32 m0, s61
	s_addc_u32 s75, s43, 0
	global_load_lds_dwordx4 v[198:199], off
	v_lshl_add_u64 v[218:219], s[74:75], 0, v[138:139]
	s_mov_b32 m0, s62
	v_lshl_add_u64 v[220:221], s[44:45], 0, v[140:141]
	global_load_lds_dwordx4 v[218:219], off
	v_lshl_add_u64 v[218:219], s[74:75], 0, v[142:143]
	s_mov_b32 m0, s63
	s_nop 0
	global_load_lds_dwordx4 v[218:219], off
	v_lshl_add_u64 v[218:219], s[44:45], 0, v[136:137]
	v_mov_b32_e32 v236, v218
	v_mov_b32_e32 v237, v219
	v_mov_b32_e32 v238, v220
	v_mov_b32_e32 v239, v221
	s_waitcnt vmcnt(6)
	s_waitcnt lgkmcnt(0)
	s_barrier
; #define PG8_STAGE(bufoff, gbase, voff) do { _Pragma("unroll") for (int _i = 0; _i < 2; ++_i) \
;         __builtin_amdgcn_global_load_lds((const unsigned*)((const char*)(gbase) + (voff)[_i]), (PG8_LAS unsigned*)(lds + (bufoff) + ldsw + _i * 8192), 16, 0, 0); } while (0)
; #define PG8_LDA(dst, b, h) do { _Pragma("unroll") for (int m = 0; m < 4; ++m) _Pragma("unroll") for (int k = 0; k < 2; ++k) dst[m][k] = *(const PG8_LAS bf16x8*)(lds + PG8_SA(b, h) + aoff + m * 2048 + k * 1024); } while (0)
; #define PG8_LDB(dst, b, h) do { _Pragma("unroll") for (int n = 0; n < 2; ++n) _Pragma("unroll") for (int k = 0; k < 2; ++k) dst[n][k] = *(const PG8_LAS bf16x8*)(lds + PG8_SB(b, h) + boff + n * 2048 + k * 1024); } while (0)
; #define PG8_MMA(ai, bj, At, Bt) do { __builtin_amdgcn_s_setprio(1); _Pragma("unroll") for (int m = 0; m < 4; ++m) _Pragma("unroll") for (int n = 0; n < 2; ++n) _Pragma("unroll") for (int k = 0; k < 2; ++k) \
;         acc[ai][bj][m][n] = __builtin_amdgcn_mfma_f32_16x16x32_bf16(Bt[n][k], At[m][k], acc[ai][bj][m][n], 0, 0, 0); __builtin_amdgcn_s_setprio(0); } while (0)
; #define PG8_WAIT_V(n) asm volatile("s_waitcnt vmcnt(" #n ")" ::: "memory")
; #define PG8_WAIT_L(n) asm volatile("s_waitcnt lgkmcnt(" #n ")" ::: "memory")
; #define PG8_BAR __builtin_amdgcn_s_barrier()
; #define PG8_SCHED __builtin_amdgcn_sched_barrier(0)
; template <class Epi, class Sched, bool ALIGN_EPI = false, bool SP2 = false>
; __device__ __forceinline__ void gemm_phase(PG8_LAS unsigned char* lds, const Gemm g, const Sched& S, const Epi& E) {
;     ...
;             PG8_WAIT_V(8); PG8_WAIT_L(0); PG8_BAR; PG8_MMA(1, 0, At, B0); PG8_MMA(1, 1, At, B1); PG8_BAR; PG8_SCHED;
;             PG8_LDB(B0, 1, 0); PG8_LDB(B1, 1, 1); PG8_SCHED; PG8_LDA(At, 1, 0); PG8_STAGE(PG8_SA(0, 1), a2 + hstep, voffA);
;             PG8_WAIT_V(8); PG8_WAIT_L(0); PG8_BAR; PG8_MMA(0, 0, At, B0); PG8_MMA(0, 1, At, B1); PG8_BAR; PG8_SCHED;
	s_setprio 1
	s_waitcnt lgkmcnt(0)
	v_mfma_f32_16x16x32_bf16 v[60:63], v[128:131], v[182:185], v[60:63]
	v_mfma_f32_16x16x32_bf16 v[56:59], v[148:151], v[182:185], v[56:59]
	v_mfma_f32_16x16x32_bf16 v[44:47], v[128:131], v[190:193], v[44:47]
	v_mfma_f32_16x16x32_bf16 v[40:43], v[148:151], v[190:193], v[40:43]
	v_mfma_f32_16x16x32_bf16 v[32:35], v[128:131], v[202:205], v[32:35]
	v_mfma_f32_16x16x32_bf16 v[24:27], v[148:151], v[202:205], v[24:27]
	v_mfma_f32_16x16x32_bf16 v[16:19], v[128:131], v[210:213], v[16:19]
	v_mfma_f32_16x16x32_bf16 v[8:11], v[148:151], v[210:213], v[8:11]
	v_mfma_f32_16x16x32_bf16 v[60:63], v[132:135], v[186:189], v[60:63]
	v_mfma_f32_16x16x32_bf16 v[56:59], v[162:165], v[186:189], v[56:59]
	v_mfma_f32_16x16x32_bf16 v[44:47], v[132:135], v[194:197], v[44:47]
	v_mfma_f32_16x16x32_bf16 v[40:43], v[162:165], v[194:197], v[40:43]
	v_mfma_f32_16x16x32_bf16 v[32:35], v[132:135], v[206:209], v[32:35]
	v_mfma_f32_16x16x32_bf16 v[24:27], v[162:165], v[206:209], v[24:27]
	v_mfma_f32_16x16x32_bf16 v[16:19], v[132:135], v[214:217], v[16:19]
	v_mfma_f32_16x16x32_bf16 v[8:11], v[162:165], v[214:217], v[8:11]
	s_setprio 0
	s_setprio 1
	v_mfma_f32_16x16x32_bf16 v[52:55], v[166:169], v[182:185], v[52:55]
	v_mfma_f32_16x16x32_bf16 v[48:51], v[174:177], v[182:185], v[48:51]
	v_mfma_f32_16x16x32_bf16 v[36:39], v[166:169], v[190:193], v[36:39]
	v_mfma_f32_16x16x32_bf16 v[28:31], v[174:177], v[190:193], v[28:31]
	v_mfma_f32_16x16x32_bf16 v[20:23], v[166:169], v[202:205], v[20:23]
	v_mfma_f32_16x16x32_bf16 v[12:15], v[174:177], v[202:205], v[12:15]
	v_mfma_f32_16x16x32_bf16 v[4:7], v[166:169], v[210:213], v[4:7]
	v_mfma_f32_16x16x32_bf16 v[0:3], v[174:177], v[210:213], v[0:3]
	v_mfma_f32_16x16x32_bf16 v[52:55], v[170:173], v[186:189], v[52:55]
	v_mfma_f32_16x16x32_bf16 v[48:51], v[178:181], v[186:189], v[48:51]
	v_mfma_f32_16x16x32_bf16 v[36:39], v[170:173], v[194:197], v[36:39]
	v_mfma_f32_16x16x32_bf16 v[28:31], v[178:181], v[194:197], v[28:31]
	v_mfma_f32_16x16x32_bf16 v[20:23], v[170:173], v[206:209], v[20:23]
	v_mfma_f32_16x16x32_bf16 v[12:15], v[178:181], v[206:209], v[12:15]
	v_mfma_f32_16x16x32_bf16 v[4:7], v[170:173], v[214:217], v[4:7]
	v_mfma_f32_16x16x32_bf16 v[0:3], v[178:181], v[214:217], v[0:3]
	s_setprio 0
	s_barrier
	ds_read_b128 v[128:131], v160
	ds_read_b128 v[132:135], v160 offset:1024
	ds_read_b128 v[148:151], v160 offset:2048
	ds_read_b128 v[162:165], v160 offset:3072
	ds_read_b128 v[166:169], v161
	ds_read_b128 v[170:173], v161 offset:1024
	ds_read_b128 v[174:177], v161 offset:2048
	ds_read_b128 v[178:181], v161 offset:3072
	s_add_u32 s44, s44, 0xb0000
	s_addc_u32 s45, s45, 0
	s_mov_b32 m0, s29
	s_nop 0
	global_load_lds_dwordx4 v[236:237], off
	s_mov_b32 m0, s30
	s_nop 0
	global_load_lds_dwordx4 v[238:239], off
	s_mov_b32 m0, s31
	v_lshl_add_u64 v[222:223], s[44:45], 0, v[136:137]
	ds_read_b128 v[182:185], v158 offset:32768
	ds_read_b128 v[186:189], v158 offset:33792
	ds_read_b128 v[190:193], v158 offset:34816
	ds_read_b128 v[194:197], v158 offset:35840
	ds_read_b128 v[202:205], v158 offset:36864
	ds_read_b128 v[206:209], v158 offset:37888
	ds_read_b128 v[210:213], v158 offset:38912
	ds_read_b128 v[214:217], v158 offset:39936
	global_load_lds_dwordx4 v[222:223], off
	v_lshl_add_u64 v[222:223], s[44:45], 0, v[140:141]
	s_mov_b32 m0, s37
	s_nop 0
	global_load_lds_dwordx4 v[222:223], off
	s_waitcnt vmcnt(8)
	s_waitcnt lgkmcnt(0)
	s_barrier
	s_setprio 1
	s_waitcnt lgkmcnt(0)
	v_mfma_f32_16x16x32_bf16 v[124:127], v[128:131], v[182:185], v[124:127]
	v_mfma_f32_16x16x32_bf16 v[120:123], v[148:151], v[182:185], v[120:123]
	v_mfma_f32_16x16x32_bf16 v[108:111], v[128:131], v[190:193], v[108:111]
	v_mfma_f32_16x16x32_bf16 v[104:107], v[148:151], v[190:193], v[104:107]
	v_mfma_f32_16x16x32_bf16 v[92:95], v[128:131], v[202:205], v[92:95]
	v_mfma_f32_16x16x32_bf16 v[88:91], v[148:151], v[202:205], v[88:91]
	v_mfma_f32_16x16x32_bf16 v[76:79], v[128:131], v[210:213], v[76:79]
	v_mfma_f32_16x16x32_bf16 v[72:75], v[148:151], v[210:213], v[72:75]
	v_mfma_f32_16x16x32_bf16 v[124:127], v[132:135], v[186:189], v[124:127]
	v_mfma_f32_16x16x32_bf16 v[120:123], v[162:165], v[186:189], v[120:123]
	v_mfma_f32_16x16x32_bf16 v[108:111], v[132:135], v[194:197], v[108:111]
	v_mfma_f32_16x16x32_bf16 v[104:107], v[162:165], v[194:197], v[104:107]
	v_mfma_f32_16x16x32_bf16 v[92:95], v[132:135], v[206:209], v[92:95]
	v_mfma_f32_16x16x32_bf16 v[88:91], v[162:165], v[206:209], v[88:91]
	v_mfma_f32_16x16x32_bf16 v[76:79], v[132:135], v[214:217], v[76:79]
	v_mfma_f32_16x16x32_bf16 v[72:75], v[162:165], v[214:217], v[72:75]
	s_setprio 0
	s_setprio 1
	v_mfma_f32_16x16x32_bf16 v[116:119], v[166:169], v[182:185], v[116:119]
	v_mfma_f32_16x16x32_bf16 v[112:115], v[174:177], v[182:185], v[112:115]
	v_mfma_f32_16x16x32_bf16 v[100:103], v[166:169], v[190:193], v[100:103]
	v_mfma_f32_16x16x32_bf16 v[96:99], v[174:177], v[190:193], v[96:99]
	v_mfma_f32_16x16x32_bf16 v[84:87], v[166:169], v[202:205], v[84:87]
	v_mfma_f32_16x16x32_bf16 v[80:83], v[174:177], v[202:205], v[80:83]
	v_mfma_f32_16x16x32_bf16 v[68:71], v[166:169], v[210:213], v[68:71]
	v_mfma_f32_16x16x32_bf16 v[64:67], v[174:177], v[210:213], v[64:67]
	v_mfma_f32_16x16x32_bf16 v[116:119], v[170:173], v[186:189], v[116:119]
	v_mfma_f32_16x16x32_bf16 v[112:115], v[178:181], v[186:189], v[112:115]
	v_mfma_f32_16x16x32_bf16 v[100:103], v[170:173], v[194:197], v[100:103]
	v_mfma_f32_16x16x32_bf16 v[96:99], v[178:181], v[194:197], v[96:99]
	v_mfma_f32_16x16x32_bf16 v[84:87], v[170:173], v[206:209], v[84:87]
	v_mfma_f32_16x16x32_bf16 v[80:83], v[178:181], v[206:209], v[80:83]
	v_mfma_f32_16x16x32_bf16 v[68:71], v[170:173], v[214:217], v[68:71]
	v_mfma_f32_16x16x32_bf16 v[64:67], v[178:181], v[214:217], v[64:67]
	s_setprio 0
	s_barrier
; #define PG8_STAGE(bufoff, gbase, voff) do { _Pragma("unroll") for (int _i = 0; _i < 2; ++_i) \
;         __builtin_amdgcn_global_load_lds((const unsigned*)((const char*)(gbase) + (voff)[_i]), (PG8_LAS unsigned*)(lds + (bufoff) + ldsw + _i * 8192), 16, 0, 0); } while (0)
; #define PG8_LDA(dst, b, h) do { _Pragma("unroll") for (int m = 0; m < 4; ++m) _Pragma("unroll") for (int k = 0; k < 2; ++k) dst[m][k] = *(const PG8_LAS bf16x8*)(lds + PG8_SA(b, h) + aoff + m * 2048 + k * 1024); } while (0)
; #define PG8_MMA(ai, bj, At, Bt) do { __builtin_amdgcn_s_setprio(1); _Pragma("unroll") for (int m = 0; m < 4; ++m) _Pragma("unroll") for (int n = 0; n < 2; ++n) _Pragma("unroll") for (int k = 0; k < 2; ++k) \
;         acc[ai][bj][m][n] = __builtin_amdgcn_mfma_f32_16x16x32_bf16(Bt[n][k], At[m][k], acc[ai][bj][m][n], 0, 0, 0); __builtin_amdgcn_s_setprio(0); } while (0)
; #define PG8_WAIT_V(n) asm volatile("s_waitcnt vmcnt(" #n ")" ::: "memory")
; #define PG8_WAIT_L(n) asm volatile("s_waitcnt lgkmcnt(" #n ")" ::: "memory")
; #define PG8_BAR __builtin_amdgcn_s_barrier()
; #define PG8_SCHED __builtin_amdgcn_sched_barrier(0)
; template <class Epi, class Sched, bool ALIGN_EPI = false, bool SP2 = false>
; __device__ __forceinline__ void gemm_phase(PG8_LAS unsigned char* lds, const Gemm g, const Sched& S, const Epi& E) {
;     ...
;             PG8_LDA(At, 1, 1); PG8_STAGE(PG8_SB(1, 0), b3, voffB); PG8_STAGE(PG8_SB(1, 1), b3 + hstep, voffB); PG8_STAGE(PG8_SA(1, 0), a3, voffA);
;             PG8_WAIT_V(8); PG8_WAIT_L(0); PG8_BAR; PG8_MMA(1, 0, At, B0); PG8_MMA(1, 1, At, B1); PG8_BAR; PG8_SCHED;
	s_add_i32 s44, s64, s28
	v_lshl_add_u64 v[152:153], v[152:153], 0, s[12:13]
	s_mov_b32 m0, s44
	ds_read_b128 v[182:185], v158 offset:49152
	ds_read_b128 v[186:189], v158 offset:50176
	ds_read_b128 v[190:193], v158 offset:51200
	ds_read_b128 v[194:197], v158 offset:52224
	ds_read_b128 v[202:205], v158 offset:53248
	ds_read_b128 v[206:209], v158 offset:54272
	ds_read_b128 v[210:213], v158 offset:55296
	ds_read_b128 v[214:217], v158 offset:56320
	global_load_lds_dwordx4 v[152:153], off
	s_add_i32 m0, s44, 0x2000
	s_add_u32 s42, s42, 0xb0080
	v_lshl_add_u64 v[152:153], v[198:199], 0, s[12:13]
	s_addc_u32 s43, s43, 0
	s_add_i32 s44, s65, s28
	global_load_lds_dwordx4 v[152:153], off
	v_lshl_add_u64 v[152:153], s[42:43], 0, v[138:139]
	s_mov_b32 m0, s44
	s_nop 0
	global_load_lds_dwordx4 v[152:153], off
	v_lshl_add_u64 v[152:153], s[42:43], 0, v[142:143]
	s_add_i32 m0, s44, 0x2000
	s_nop 0
	global_load_lds_dwordx4 v[152:153], off
	v_lshl_add_u64 v[152:153], v[218:219], 0, s[12:13]
	v_mov_b32_e32 v232, v152
	v_mov_b32_e32 v233, v153
	v_lshl_add_u64 v[152:153], v[220:221], 0, s[12:13]
	v_mov_b32_e32 v234, v152
	v_mov_b32_e32 v235, v153
	s_waitcnt vmcnt(6)
	s_waitcnt lgkmcnt(0)
	s_barrier
	s_setprio 1
	s_waitcnt lgkmcnt(0)
	v_mfma_f32_16x16x32_bf16 v[60:63], v[128:131], v[182:185], v[60:63]
	v_mfma_f32_16x16x32_bf16 v[56:59], v[148:151], v[182:185], v[56:59]
	v_mfma_f32_16x16x32_bf16 v[44:47], v[128:131], v[190:193], v[44:47]
	v_mfma_f32_16x16x32_bf16 v[40:43], v[148:151], v[190:193], v[40:43]
	v_mfma_f32_16x16x32_bf16 v[32:35], v[128:131], v[202:205], v[32:35]
	v_mfma_f32_16x16x32_bf16 v[24:27], v[148:151], v[202:205], v[24:27]
	v_mfma_f32_16x16x32_bf16 v[16:19], v[128:131], v[210:213], v[16:19]
	v_mfma_f32_16x16x32_bf16 v[8:11], v[148:151], v[210:213], v[8:11]
	v_mfma_f32_16x16x32_bf16 v[60:63], v[132:135], v[186:189], v[60:63]
	v_mfma_f32_16x16x32_bf16 v[56:59], v[162:165], v[186:189], v[56:59]
	v_mfma_f32_16x16x32_bf16 v[44:47], v[132:135], v[194:197], v[44:47]
	v_mfma_f32_16x16x32_bf16 v[40:43], v[162:165], v[194:197], v[40:43]
	v_mfma_f32_16x16x32_bf16 v[32:35], v[132:135], v[206:209], v[32:35]
	v_mfma_f32_16x16x32_bf16 v[24:27], v[162:165], v[206:209], v[24:27]
	v_mfma_f32_16x16x32_bf16 v[16:19], v[132:135], v[214:217], v[16:19]
	v_mfma_f32_16x16x32_bf16 v[8:11], v[162:165], v[214:217], v[8:11]
	s_setprio 0
	s_setprio 1
	v_mfma_f32_16x16x32_bf16 v[52:55], v[166:169], v[182:185], v[52:55]
	v_mfma_f32_16x16x32_bf16 v[48:51], v[174:177], v[182:185], v[48:51]
	v_mfma_f32_16x16x32_bf16 v[36:39], v[166:169], v[190:193], v[36:39]
	v_mfma_f32_16x16x32_bf16 v[28:31], v[174:177], v[190:193], v[28:31]
	v_mfma_f32_16x16x32_bf16 v[20:23], v[166:169], v[202:205], v[20:23]
	v_mfma_f32_16x16x32_bf16 v[12:15], v[174:177], v[202:205], v[12:15]
	v_mfma_f32_16x16x32_bf16 v[4:7], v[166:169], v[210:213], v[4:7]
	v_mfma_f32_16x16x32_bf16 v[0:3], v[174:177], v[210:213], v[0:3]
	v_mfma_f32_16x16x32_bf16 v[52:55], v[170:173], v[186:189], v[52:55]
	v_mfma_f32_16x16x32_bf16 v[48:51], v[178:181], v[186:189], v[48:51]
	v_mfma_f32_16x16x32_bf16 v[36:39], v[170:173], v[194:197], v[36:39]
	v_mfma_f32_16x16x32_bf16 v[28:31], v[178:181], v[194:197], v[28:31]
	v_mfma_f32_16x16x32_bf16 v[20:23], v[170:173], v[206:209], v[20:23]
	v_mfma_f32_16x16x32_bf16 v[12:15], v[178:181], v[206:209], v[12:15]
	v_mfma_f32_16x16x32_bf16 v[4:7], v[170:173], v[214:217], v[4:7]
	v_mfma_f32_16x16x32_bf16 v[0:3], v[178:181], v[214:217], v[0:3]
	s_setprio 0
	s_barrier
	s_add_i32 s72, s72, 2
	s_add_u32 s26, s26, 0x100
	s_addc_u32 s27, s27, 0
	s_add_u32 s70, s70, 0x100
	s_addc_u32 s71, s71, 0
	s_cmp_gt_u32 s72, 41
	s_cbranch_scc0 .LBB0_1363
	s_and_b64 vcc, exec, s[14:15]
	s_cbranch_vccz .LBB0_1366
	s_barrier

; #define LAS __attribute__((address_space(3)))
; __global__ void __launch_bounds__(NTHREADS, 2) fwd(Args a) {
;     extern __shared__ __attribute__((aligned(16))) unsigned char lds_raw[];
;     LAS unsigned char* lds = (LAS unsigned char*)lds_raw;
;     const int tid = threadIdx.x, lane = tid & 63, wave = __builtin_amdgcn_readfirstlane(tid >> 6);
	.amdhsa_kernel _Z3fwd4Args
		.amdhsa_group_segment_fixed_size 0
		.amdhsa_private_segment_fixed_size 0
		.amdhsa_kernarg_size 416
		.amdhsa_user_sgpr_count 2
		.amdhsa_user_sgpr_dispatch_ptr 0
		.amdhsa_user_sgpr_queue_ptr 0
		.amdhsa_user_sgpr_kernarg_segment_ptr 1
		.amdhsa_user_sgpr_dispatch_id 0
		.amdhsa_user_sgpr_kernarg_preload_length 0
		.amdhsa_user_sgpr_kernarg_preload_offset 0
		.amdhsa_user_sgpr_private_segment_size 0
		.amdhsa_uses_dynamic_stack 0
		.amdhsa_enable_private_segment 0
		.amdhsa_system_sgpr_workgroup_id_x 1
		.amdhsa_system_sgpr_workgroup_id_y 0
		.amdhsa_system_sgpr_workgroup_id_z 0
		.amdhsa_system_sgpr_workgroup_info 0
		.amdhsa_system_vgpr_workitem_id 2
		.amdhsa_next_free_vgpr 240
		.amdhsa_next_free_sgpr 100
		.amdhsa_accum_offset 240
		.amdhsa_reserve_vcc 1
		.amdhsa_float_round_mode_32 0
		.amdhsa_float_round_mode_16_64 0
		.amdhsa_float_denorm_mode_32 3
		.amdhsa_float_denorm_mode_16_64 3
		.amdhsa_dx10_clamp 1
		.amdhsa_ieee_mode 1
		.amdhsa_fp16_overflow 0
		.amdhsa_tg_split 0
		.amdhsa_exception_fp_ieee_invalid_op 0
		.amdhsa_exception_fp_denorm_src 0
		.amdhsa_exception_fp_ieee_div_zero 0
		.amdhsa_exception_fp_ieee_overflow 0
		.amdhsa_exception_fp_ieee_underflow 0
		.amdhsa_exception_fp_ieee_inexact 0
		.amdhsa_exception_int_div_zero 0
	.end_amdhsa_kernel

; #define LAS __attribute__((address_space(3)))
; __global__ void __launch_bounds__(NTHREADS, 2) fwd(Args a) {
;     extern __shared__ __attribute__((aligned(16))) unsigned char lds_raw[];
;     LAS unsigned char* lds = (LAS unsigned char*)lds_raw;
;     const int tid = threadIdx.x, lane = tid & 63, wave = __builtin_amdgcn_readfirstlane(tid >> 6);
amdhsa.kernels:
  - .agpr_count:     0
    .args:
      - .offset:         0
        .size:           160
        .value_kind:     by_value
      - .offset:         160
        .size:           4
        .value_kind:     hidden_block_count_x
      - .offset:         164
        .size:           4
        .value_kind:     hidden_block_count_y
      - .offset:         168
        .size:           4
        .value_kind:     hidden_block_count_z
      - .offset:         172
        .size:           2
        .value_kind:     hidden_group_size_x
      - .offset:         174
        .size:           2
        .value_kind:     hidden_group_size_y
      - .offset:         176
        .size:           2
        .value_kind:     hidden_group_size_z
      - .offset:         178
        .size:           2
        .value_kind:     hidden_remainder_x
      - .offset:         180
        .size:           2
        .value_kind:     hidden_remainder_y
      - .offset:         182
        .size:           2
        .value_kind:     hidden_remainder_z
      - .offset:         200
        .size:           8
        .value_kind:     hidden_global_offset_x
      - .offset:         208
        .size:           8
        .value_kind:     hidden_global_offset_y
      - .offset:         216
        .size:           8
        .value_kind:     hidden_global_offset_z
      - .offset:         224
        .size:           2
        .value_kind:     hidden_grid_dims
      - .offset:         248
        .size:           8
        .value_kind:     hidden_multigrid_sync_arg
      - .offset:         280
        .size:           4
        .value_kind:     hidden_dynamic_lds_size
    .group_segment_fixed_size: 0
    .kernarg_segment_align: 8
    .kernarg_segment_size: 416
    .language:       OpenCL C
    .language_version:
      - 2
      - 0
    .max_flat_workgroup_size: 512
    .name:           _Z3fwd4Args
    .private_segment_fixed_size: 0
    .sgpr_count:     106
    .sgpr_spill_count: 16
    .symbol:         _Z3fwd4Args.kd
    .uniform_work_group_size: 1
    .uses_dynamic_stack: false
    .vgpr_count:     240
    .vgpr_spill_count: 0
    .wavefront_size: 64
